# as previous best but with the baseline MFMA issue order inside each MFMA segment (k-major, consecutive MFMAs share one operand)
# baseline (speedup 1.0000x reference)
.Lmid1_446:
	s_add_i32 s22, 0, 0x10000
	s_add_i32 s23, 0, 0x14000
	s_add_u32 s20, s56, 0xfff50080
	s_addc_u32 s21, s57, -1
	s_cmp_eq_u32 s84, 40
	s_cselect_b32 s61, s49, s21
	s_cselect_b32 s60, s48, s20
	s_cselect_b32 s21, s51, s63
	s_cselect_b32 s20, s50, s62
	s_add_i32 m0, s47, 0xc000
	v_lshl_add_u64 v[162:163], s[56:57], 0, v[156:157]
	global_load_lds_dwordx4 v[162:163], off
	v_lshl_add_u64 v[162:163], v[162:163], 0, s[2:3]
	s_add_i32 m0, s47, 0xe000
	s_nop 0
	global_load_lds_dwordx4 v[162:163], off
	s_waitcnt vmcnt(8)
	s_waitcnt lgkmcnt(0)
	s_barrier
	s_setprio 1
	s_waitcnt lgkmcnt(0)
	v_mfma_f32_16x16x32_bf16 v[142:145], v[114:117], v[186:189], 0
	v_mfma_f32_16x16x32_bf16 v[138:141], v[130:133], v[186:189], 0
	v_mfma_f32_16x16x32_bf16 v[110:113], v[114:117], v[198:201], 0
	v_mfma_f32_16x16x32_bf16 v[106:109], v[130:133], v[198:201], 0
	v_mfma_f32_16x16x32_bf16 v[94:97], v[114:117], v[218:221], 0
	v_mfma_f32_16x16x32_bf16 v[90:93], v[130:133], v[218:221], 0
	v_mfma_f32_16x16x32_bf16 v[78:81], v[114:117], v[226:229], 0
	v_mfma_f32_16x16x32_bf16 v[74:77], v[130:133], v[226:229], 0
	v_mfma_f32_16x16x32_bf16 v[142:145], v[126:129], v[194:197], v[142:145]
	v_mfma_f32_16x16x32_bf16 v[138:141], v[134:137], v[194:197], v[138:141]
	v_mfma_f32_16x16x32_bf16 v[110:113], v[126:129], v[214:217], v[110:113]
	v_mfma_f32_16x16x32_bf16 v[106:109], v[134:137], v[214:217], v[106:109]
	v_mfma_f32_16x16x32_bf16 v[94:97], v[126:129], v[222:225], v[94:97]
	v_mfma_f32_16x16x32_bf16 v[90:93], v[134:137], v[222:225], v[90:93]
	v_mfma_f32_16x16x32_bf16 v[78:81], v[126:129], v[230:233], v[78:81]
	v_mfma_f32_16x16x32_bf16 v[74:77], v[134:137], v[230:233], v[74:77]
	s_setprio 0
	s_setprio 1
	v_mfma_f32_16x16x32_bf16 v[122:125], v[146:149], v[186:189], 0
	v_mfma_f32_16x16x32_bf16 v[118:121], v[158:161], v[186:189], 0
	v_mfma_f32_16x16x32_bf16 v[102:105], v[146:149], v[198:201], 0
	v_mfma_f32_16x16x32_bf16 v[98:101], v[158:161], v[198:201], 0
	v_mfma_f32_16x16x32_bf16 v[86:89], v[146:149], v[218:221], 0
	v_mfma_f32_16x16x32_bf16 v[82:85], v[158:161], v[218:221], 0
	v_mfma_f32_16x16x32_bf16 v[70:73], v[146:149], v[226:229], 0
	v_mfma_f32_16x16x32_bf16 v[66:69], v[158:161], v[226:229], 0
	v_mfma_f32_16x16x32_bf16 v[122:125], v[150:153], v[194:197], v[122:125]
	v_mfma_f32_16x16x32_bf16 v[118:121], v[182:185], v[194:197], v[118:121]
	v_mfma_f32_16x16x32_bf16 v[102:105], v[150:153], v[214:217], v[102:105]
	v_mfma_f32_16x16x32_bf16 v[98:101], v[182:185], v[214:217], v[98:101]
	v_mfma_f32_16x16x32_bf16 v[86:89], v[150:153], v[222:225], v[86:89]
	v_mfma_f32_16x16x32_bf16 v[82:85], v[182:185], v[222:225], v[82:85]
	v_mfma_f32_16x16x32_bf16 v[70:73], v[150:153], v[230:233], v[70:73]
	v_mfma_f32_16x16x32_bf16 v[66:69], v[182:185], v[230:233], v[66:69]
	s_setprio 0
	s_barrier
	ds_read_b128 v[186:189], v193 offset:16384
	ds_read_b128 v[194:197], v193 offset:17408
	ds_read_b128 v[198:201], v193 offset:18432
	ds_read_b128 v[214:217], v193 offset:19456
	ds_read_b128 v[218:221], v193 offset:20480
	ds_read_b128 v[222:225], v193 offset:21504
	ds_read_b128 v[226:229], v193 offset:22528
	ds_read_b128 v[230:233], v193 offset:23552
	v_lshl_add_u64 v[162:163], s[20:21], 0, v[0:1]
	s_add_i32 s20, s22, s46
	s_mov_b32 m0, s20
	s_nop 0
	s_nop 0
	global_load_lds_dwordx4 v[162:163], off
	v_lshl_add_u64 v[202:203], v[162:163], 0, s[2:3]
	s_add_i32 m0, s20, 0x2000
	s_add_i32 s20, s23, s46
	global_load_lds_dwordx4 v[202:203], off
	v_lshl_add_u64 v[202:203], v[162:163], 0, s[12:13]
	s_mov_b32 m0, s20
	s_nop 0
	global_load_lds_dwordx4 v[202:203], off
	v_lshl_add_u64 v[202:203], v[162:163], 0, s[86:87]
	s_add_i32 m0, s20, 0x2000
	s_nop 0
	global_load_lds_dwordx4 v[202:203], off
	v_lshl_add_u64 v[202:203], s[60:61], 0, v[154:155]
	s_mov_b32 m0, s47
	v_lshl_add_u64 v[234:235], v[202:203], 0, s[2:3]
	global_load_lds_dwordx4 v[202:203], off
	s_mov_b32 m0, s68
	s_nop 0
	global_load_lds_dwordx4 v[234:235], off
	s_waitcnt vmcnt(8)
	s_waitcnt lgkmcnt(0)
	s_barrier
	s_setprio 1
	s_waitcnt lgkmcnt(0)
	v_mfma_f32_16x16x32_bf16 v[62:65], v[114:117], v[186:189], 0
	v_mfma_f32_16x16x32_bf16 v[58:61], v[130:133], v[186:189], 0
	v_mfma_f32_16x16x32_bf16 v[46:49], v[114:117], v[198:201], 0
	v_mfma_f32_16x16x32_bf16 v[42:45], v[130:133], v[198:201], 0
	v_mfma_f32_16x16x32_bf16 v[30:33], v[114:117], v[218:221], 0
	v_mfma_f32_16x16x32_bf16 v[26:29], v[130:133], v[218:221], 0
	v_mfma_f32_16x16x32_bf16 v[14:17], v[114:117], v[226:229], 0
	v_mfma_f32_16x16x32_bf16 v[10:13], v[130:133], v[226:229], 0
	v_mfma_f32_16x16x32_bf16 v[62:65], v[126:129], v[194:197], v[62:65]
	v_mfma_f32_16x16x32_bf16 v[58:61], v[134:137], v[194:197], v[58:61]
	v_mfma_f32_16x16x32_bf16 v[46:49], v[126:129], v[214:217], v[46:49]
	v_mfma_f32_16x16x32_bf16 v[42:45], v[134:137], v[214:217], v[42:45]
	v_mfma_f32_16x16x32_bf16 v[30:33], v[126:129], v[222:225], v[30:33]
	v_mfma_f32_16x16x32_bf16 v[26:29], v[134:137], v[222:225], v[26:29]
	v_mfma_f32_16x16x32_bf16 v[14:17], v[126:129], v[230:233], v[14:17]
	v_mfma_f32_16x16x32_bf16 v[10:13], v[134:137], v[230:233], v[10:13]
	s_setprio 0
	s_setprio 1
	v_mfma_f32_16x16x32_bf16 v[54:57], v[146:149], v[186:189], 0
	v_mfma_f32_16x16x32_bf16 v[50:53], v[158:161], v[186:189], 0
	v_mfma_f32_16x16x32_bf16 v[38:41], v[146:149], v[198:201], 0
	v_mfma_f32_16x16x32_bf16 v[34:37], v[158:161], v[198:201], 0
	v_mfma_f32_16x16x32_bf16 v[22:25], v[146:149], v[218:221], 0
	v_mfma_f32_16x16x32_bf16 v[18:21], v[158:161], v[218:221], 0
	v_mfma_f32_16x16x32_bf16 v[6:9], v[146:149], v[226:229], 0
	v_mfma_f32_16x16x32_bf16 v[2:5], v[158:161], v[226:229], 0
	v_mfma_f32_16x16x32_bf16 v[54:57], v[150:153], v[194:197], v[54:57]
	v_mfma_f32_16x16x32_bf16 v[50:53], v[182:185], v[194:197], v[50:53]
	v_mfma_f32_16x16x32_bf16 v[38:41], v[150:153], v[214:217], v[38:41]
	v_mfma_f32_16x16x32_bf16 v[34:37], v[182:185], v[214:217], v[34:37]
	v_mfma_f32_16x16x32_bf16 v[22:25], v[150:153], v[222:225], v[22:25]
	v_mfma_f32_16x16x32_bf16 v[18:21], v[182:185], v[222:225], v[18:21]
	v_mfma_f32_16x16x32_bf16 v[6:9], v[150:153], v[230:233], v[6:9]
	v_mfma_f32_16x16x32_bf16 v[2:5], v[182:185], v[230:233], v[2:5]
	s_setprio 0
	s_barrier
	s_add_i32 s20, 0, 0x18000
	s_add_i32 s21, 0, 0x1c000
	v_add_u32_e32 v134, s20, v191
	v_add_u32_e32 v182, s21, v191
	ds_read_b128 v[114:117], v134
	ds_read_b128 v[126:129], v134 offset:1024
	ds_read_b128 v[130:133], v134 offset:2048
	ds_read_b128 v[134:137], v134 offset:3072
	ds_read_b128 v[146:149], v182
	ds_read_b128 v[150:153], v182 offset:1024
	ds_read_b128 v[158:161], v182 offset:2048
	ds_read_b128 v[182:185], v182 offset:3072
	ds_read_b128 v[186:189], v193 offset:32768
	ds_read_b128 v[194:197], v193 offset:33792
	ds_read_b128 v[198:201], v193 offset:34816
	ds_read_b128 v[214:217], v193 offset:35840
	ds_read_b128 v[218:221], v193 offset:36864
	ds_read_b128 v[222:225], v193 offset:37888
	ds_read_b128 v[226:229], v193 offset:38912
	ds_read_b128 v[230:233], v193 offset:39936
	s_mov_b32 m0, s69
	v_lshl_add_u64 v[234:235], v[202:203], 0, s[12:13]
	global_load_lds_dwordx4 v[234:235], off
	v_lshl_add_u64 v[234:235], v[202:203], 0, s[86:87]
	s_mov_b32 m0, s76
	s_nop 0
	global_load_lds_dwordx4 v[234:235], off
	s_waitcnt vmcnt(8)
	s_waitcnt lgkmcnt(0)
	s_barrier
	s_setprio 1
	s_waitcnt lgkmcnt(0)
	v_mfma_f32_16x16x32_bf16 v[142:145], v[114:117], v[186:189], v[142:145]
	v_mfma_f32_16x16x32_bf16 v[138:141], v[130:133], v[186:189], v[138:141]
	v_mfma_f32_16x16x32_bf16 v[110:113], v[114:117], v[198:201], v[110:113]
	v_mfma_f32_16x16x32_bf16 v[106:109], v[130:133], v[198:201], v[106:109]
	v_mfma_f32_16x16x32_bf16 v[94:97], v[114:117], v[218:221], v[94:97]
	v_mfma_f32_16x16x32_bf16 v[90:93], v[130:133], v[218:221], v[90:93]
	v_mfma_f32_16x16x32_bf16 v[78:81], v[114:117], v[226:229], v[78:81]
	v_mfma_f32_16x16x32_bf16 v[74:77], v[130:133], v[226:229], v[74:77]
	v_mfma_f32_16x16x32_bf16 v[142:145], v[126:129], v[194:197], v[142:145]
	v_mfma_f32_16x16x32_bf16 v[138:141], v[134:137], v[194:197], v[138:141]
	v_mfma_f32_16x16x32_bf16 v[110:113], v[126:129], v[214:217], v[110:113]
	v_mfma_f32_16x16x32_bf16 v[106:109], v[134:137], v[214:217], v[106:109]
	v_mfma_f32_16x16x32_bf16 v[94:97], v[126:129], v[222:225], v[94:97]
	v_mfma_f32_16x16x32_bf16 v[90:93], v[134:137], v[222:225], v[90:93]
	v_mfma_f32_16x16x32_bf16 v[78:81], v[126:129], v[230:233], v[78:81]
	v_mfma_f32_16x16x32_bf16 v[74:77], v[134:137], v[230:233], v[74:77]
	s_setprio 0
	s_setprio 1
	v_mfma_f32_16x16x32_bf16 v[122:125], v[146:149], v[186:189], v[122:125]
	v_mfma_f32_16x16x32_bf16 v[118:121], v[158:161], v[186:189], v[118:121]
	v_mfma_f32_16x16x32_bf16 v[102:105], v[146:149], v[198:201], v[102:105]
	v_mfma_f32_16x16x32_bf16 v[98:101], v[158:161], v[198:201], v[98:101]
	v_mfma_f32_16x16x32_bf16 v[86:89], v[146:149], v[218:221], v[86:89]
	v_mfma_f32_16x16x32_bf16 v[82:85], v[158:161], v[218:221], v[82:85]
	v_mfma_f32_16x16x32_bf16 v[70:73], v[146:149], v[226:229], v[70:73]
	v_mfma_f32_16x16x32_bf16 v[66:69], v[158:161], v[226:229], v[66:69]
	v_mfma_f32_16x16x32_bf16 v[122:125], v[150:153], v[194:197], v[122:125]
	v_mfma_f32_16x16x32_bf16 v[118:121], v[182:185], v[194:197], v[118:121]
	v_mfma_f32_16x16x32_bf16 v[102:105], v[150:153], v[214:217], v[102:105]
	v_mfma_f32_16x16x32_bf16 v[98:101], v[182:185], v[214:217], v[98:101]
	v_mfma_f32_16x16x32_bf16 v[86:89], v[150:153], v[222:225], v[86:89]
	v_mfma_f32_16x16x32_bf16 v[82:85], v[182:185], v[222:225], v[82:85]
	v_mfma_f32_16x16x32_bf16 v[70:73], v[150:153], v[230:233], v[70:73]
	v_mfma_f32_16x16x32_bf16 v[66:69], v[182:185], v[230:233], v[66:69]
	s_setprio 0
	s_barrier
	ds_read_b128 v[186:189], v193 offset:49152
	ds_read_b128 v[194:197], v193 offset:50176
	ds_read_b128 v[198:201], v193 offset:51200
	ds_read_b128 v[214:217], v193 offset:52224
	ds_read_b128 v[218:221], v193 offset:53248
	ds_read_b128 v[222:225], v193 offset:54272
	ds_read_b128 v[226:229], v193 offset:55296
	ds_read_b128 v[230:233], v193 offset:56320
	s_add_i32 s20, s20, s46
	s_mov_b32 m0, s20
	v_lshl_add_u64 v[234:235], v[162:163], 0, s[34:35]
	global_load_lds_dwordx4 v[234:235], off
	v_lshl_add_u64 v[234:235], v[162:163], 0, s[96:97]
	s_add_i32 m0, s20, 0x2000
	s_add_i32 s20, s21, s46
	global_load_lds_dwordx4 v[234:235], off
	v_lshl_add_u64 v[234:235], v[162:163], 0, vcc
	s_mov_b32 m0, s20
	v_lshl_add_u64 v[162:163], v[162:163], 0, s[0:1]
	global_load_lds_dwordx4 v[234:235], off
	s_add_i32 m0, s20, 0x2000
	s_nop 0
	global_load_lds_dwordx4 v[162:163], off
	v_lshl_add_u64 v[162:163], v[202:203], 0, s[34:35]
	s_mov_b32 m0, s77
	s_nop 0
	global_load_lds_dwordx4 v[162:163], off
	v_lshl_add_u64 v[162:163], v[202:203], 0, s[96:97]
	s_mov_b32 m0, s78
	s_nop 0
	global_load_lds_dwordx4 v[162:163], off
	s_waitcnt vmcnt(8)
	s_waitcnt lgkmcnt(0)
	s_barrier
	s_setprio 1
	s_waitcnt lgkmcnt(0)
	v_mfma_f32_16x16x32_bf16 v[62:65], v[114:117], v[186:189], v[62:65]
	v_mfma_f32_16x16x32_bf16 v[58:61], v[130:133], v[186:189], v[58:61]
	v_mfma_f32_16x16x32_bf16 v[46:49], v[114:117], v[198:201], v[46:49]
	v_mfma_f32_16x16x32_bf16 v[42:45], v[130:133], v[198:201], v[42:45]
	v_mfma_f32_16x16x32_bf16 v[30:33], v[114:117], v[218:221], v[30:33]
	v_mfma_f32_16x16x32_bf16 v[26:29], v[130:133], v[218:221], v[26:29]
	v_mfma_f32_16x16x32_bf16 v[14:17], v[114:117], v[226:229], v[14:17]
	v_mfma_f32_16x16x32_bf16 v[10:13], v[130:133], v[226:229], v[10:13]
	v_mfma_f32_16x16x32_bf16 v[62:65], v[126:129], v[194:197], v[62:65]
	v_mfma_f32_16x16x32_bf16 v[58:61], v[134:137], v[194:197], v[58:61]
	v_mfma_f32_16x16x32_bf16 v[46:49], v[126:129], v[214:217], v[46:49]
	v_mfma_f32_16x16x32_bf16 v[42:45], v[134:137], v[214:217], v[42:45]
	v_mfma_f32_16x16x32_bf16 v[30:33], v[126:129], v[222:225], v[30:33]
	v_mfma_f32_16x16x32_bf16 v[26:29], v[134:137], v[222:225], v[26:29]
	v_mfma_f32_16x16x32_bf16 v[14:17], v[126:129], v[230:233], v[14:17]
	v_mfma_f32_16x16x32_bf16 v[10:13], v[134:137], v[230:233], v[10:13]
	s_add_i32 s84, s84, 2
	s_add_u32 s56, s56, 0x100
	s_addc_u32 s57, s57, 0
	s_add_u32 s62, s62, 0x100
	s_addc_u32 s63, s63, 0
	s_setprio 0
	s_setprio 1
	v_mfma_f32_16x16x32_bf16 v[54:57], v[146:149], v[186:189], v[54:57]
	v_mfma_f32_16x16x32_bf16 v[50:53], v[158:161], v[186:189], v[50:53]
	v_mfma_f32_16x16x32_bf16 v[38:41], v[146:149], v[198:201], v[38:41]
	v_mfma_f32_16x16x32_bf16 v[34:37], v[158:161], v[198:201], v[34:37]
	v_mfma_f32_16x16x32_bf16 v[22:25], v[146:149], v[218:221], v[22:25]
	v_mfma_f32_16x16x32_bf16 v[18:21], v[158:161], v[218:221], v[18:21]
	v_mfma_f32_16x16x32_bf16 v[6:9], v[146:149], v[226:229], v[6:9]
	v_mfma_f32_16x16x32_bf16 v[2:5], v[158:161], v[226:229], v[2:5]
	v_mfma_f32_16x16x32_bf16 v[54:57], v[150:153], v[194:197], v[54:57]
	v_mfma_f32_16x16x32_bf16 v[50:53], v[182:185], v[194:197], v[50:53]
	v_mfma_f32_16x16x32_bf16 v[38:41], v[150:153], v[214:217], v[38:41]
	v_mfma_f32_16x16x32_bf16 v[34:37], v[182:185], v[214:217], v[34:37]
	v_mfma_f32_16x16x32_bf16 v[22:25], v[150:153], v[222:225], v[22:25]
	v_mfma_f32_16x16x32_bf16 v[18:21], v[182:185], v[222:225], v[18:21]
	v_mfma_f32_16x16x32_bf16 v[6:9], v[150:153], v[230:233], v[6:9]
	v_mfma_f32_16x16x32_bf16 v[2:5], v[182:185], v[230:233], v[2:5]
	s_setprio 0
	s_barrier
	s_branch .LBB0_446
	.p2alignl 6, 3212836864
.LBB0_446:
	s_add_i32 s22, 0, 0x10000
	s_add_i32 s23, 0, 0x14000
	v_add_u32_e32 v134, s22, v191
	v_add_u32_e32 v162, s23, v191
	ds_read_b128 v[114:117], v134
	ds_read_b128 v[126:129], v134 offset:1024
	ds_read_b128 v[130:133], v134 offset:2048
	ds_read_b128 v[134:137], v134 offset:3072
	ds_read_b128 v[146:149], v162
	ds_read_b128 v[150:153], v162 offset:1024
	ds_read_b128 v[158:161], v162 offset:2048
	ds_read_b128 v[182:185], v162 offset:3072
	ds_read_b128 v[186:189], v193
	ds_read_b128 v[194:197], v193 offset:1024
	ds_read_b128 v[198:201], v193 offset:2048
	ds_read_b128 v[214:217], v193 offset:3072
	ds_read_b128 v[218:221], v193 offset:4096
	ds_read_b128 v[222:225], v193 offset:5120
	ds_read_b128 v[226:229], v193 offset:6144
	ds_read_b128 v[230:233], v193 offset:7168
	s_add_u32 s20, s56, 0xfff50080
	s_addc_u32 s21, s57, -1
	s_cmp_eq_u32 s84, 40
	s_cselect_b32 s61, s49, s21
	s_cselect_b32 s60, s48, s20
	s_cselect_b32 s21, s51, s63
	s_cselect_b32 s20, s50, s62
	s_add_i32 m0, s47, 0xc000
	v_lshl_add_u64 v[162:163], s[56:57], 0, v[156:157]
	global_load_lds_dwordx4 v[162:163], off
	v_lshl_add_u64 v[162:163], v[162:163], 0, s[2:3]
	s_add_i32 m0, s47, 0xe000
	s_nop 0
	global_load_lds_dwordx4 v[162:163], off
	s_waitcnt vmcnt(8)
	s_waitcnt lgkmcnt(0)
	s_barrier
	s_setprio 1
	s_waitcnt lgkmcnt(0)
	v_mfma_f32_16x16x32_bf16 v[142:145], v[114:117], v[186:189], v[142:145]
	v_mfma_f32_16x16x32_bf16 v[138:141], v[130:133], v[186:189], v[138:141]
	v_mfma_f32_16x16x32_bf16 v[110:113], v[114:117], v[198:201], v[110:113]
	v_mfma_f32_16x16x32_bf16 v[106:109], v[130:133], v[198:201], v[106:109]
	v_mfma_f32_16x16x32_bf16 v[94:97], v[114:117], v[218:221], v[94:97]
	v_mfma_f32_16x16x32_bf16 v[90:93], v[130:133], v[218:221], v[90:93]
	v_mfma_f32_16x16x32_bf16 v[78:81], v[114:117], v[226:229], v[78:81]
	v_mfma_f32_16x16x32_bf16 v[74:77], v[130:133], v[226:229], v[74:77]
	v_mfma_f32_16x16x32_bf16 v[142:145], v[126:129], v[194:197], v[142:145]
	v_mfma_f32_16x16x32_bf16 v[138:141], v[134:137], v[194:197], v[138:141]
	v_mfma_f32_16x16x32_bf16 v[110:113], v[126:129], v[214:217], v[110:113]
	v_mfma_f32_16x16x32_bf16 v[106:109], v[134:137], v[214:217], v[106:109]
	v_mfma_f32_16x16x32_bf16 v[94:97], v[126:129], v[222:225], v[94:97]
	v_mfma_f32_16x16x32_bf16 v[90:93], v[134:137], v[222:225], v[90:93]
	v_mfma_f32_16x16x32_bf16 v[78:81], v[126:129], v[230:233], v[78:81]
	v_mfma_f32_16x16x32_bf16 v[74:77], v[134:137], v[230:233], v[74:77]
	s_setprio 0
	s_setprio 1
	v_mfma_f32_16x16x32_bf16 v[122:125], v[146:149], v[186:189], v[122:125]
	v_mfma_f32_16x16x32_bf16 v[118:121], v[158:161], v[186:189], v[118:121]
	v_mfma_f32_16x16x32_bf16 v[102:105], v[146:149], v[198:201], v[102:105]
	v_mfma_f32_16x16x32_bf16 v[98:101], v[158:161], v[198:201], v[98:101]
	v_mfma_f32_16x16x32_bf16 v[86:89], v[146:149], v[218:221], v[86:89]
	v_mfma_f32_16x16x32_bf16 v[82:85], v[158:161], v[218:221], v[82:85]
	v_mfma_f32_16x16x32_bf16 v[70:73], v[146:149], v[226:229], v[70:73]
	v_mfma_f32_16x16x32_bf16 v[66:69], v[158:161], v[226:229], v[66:69]
	v_mfma_f32_16x16x32_bf16 v[122:125], v[150:153], v[194:197], v[122:125]
	v_mfma_f32_16x16x32_bf16 v[118:121], v[182:185], v[194:197], v[118:121]
	v_mfma_f32_16x16x32_bf16 v[102:105], v[150:153], v[214:217], v[102:105]
	v_mfma_f32_16x16x32_bf16 v[98:101], v[182:185], v[214:217], v[98:101]
	v_mfma_f32_16x16x32_bf16 v[86:89], v[150:153], v[222:225], v[86:89]
	v_mfma_f32_16x16x32_bf16 v[82:85], v[182:185], v[222:225], v[82:85]
	v_mfma_f32_16x16x32_bf16 v[70:73], v[150:153], v[230:233], v[70:73]
	v_mfma_f32_16x16x32_bf16 v[66:69], v[182:185], v[230:233], v[66:69]
	s_setprio 0
	s_barrier
	ds_read_b128 v[186:189], v193 offset:16384
	ds_read_b128 v[194:197], v193 offset:17408
	ds_read_b128 v[198:201], v193 offset:18432
	ds_read_b128 v[214:217], v193 offset:19456
	ds_read_b128 v[218:221], v193 offset:20480
	ds_read_b128 v[222:225], v193 offset:21504
	ds_read_b128 v[226:229], v193 offset:22528
	ds_read_b128 v[230:233], v193 offset:23552
	v_lshl_add_u64 v[162:163], s[20:21], 0, v[0:1]
	s_add_i32 s20, s22, s46
	s_mov_b32 m0, s20
	s_nop 0
	s_nop 0
	global_load_lds_dwordx4 v[162:163], off
	v_lshl_add_u64 v[202:203], v[162:163], 0, s[2:3]
	s_add_i32 m0, s20, 0x2000
	s_add_i32 s20, s23, s46
	global_load_lds_dwordx4 v[202:203], off
	v_lshl_add_u64 v[202:203], v[162:163], 0, s[12:13]
	s_mov_b32 m0, s20
	s_nop 0
	global_load_lds_dwordx4 v[202:203], off
	v_lshl_add_u64 v[202:203], v[162:163], 0, s[86:87]
	s_add_i32 m0, s20, 0x2000
	s_nop 0
	global_load_lds_dwordx4 v[202:203], off
	v_lshl_add_u64 v[202:203], s[60:61], 0, v[154:155]
	s_mov_b32 m0, s47
	v_lshl_add_u64 v[234:235], v[202:203], 0, s[2:3]
	global_load_lds_dwordx4 v[202:203], off
	s_mov_b32 m0, s68
	s_nop 0
	global_load_lds_dwordx4 v[234:235], off
	s_waitcnt vmcnt(8)
	s_waitcnt lgkmcnt(0)
	s_barrier
	s_setprio 1
	s_waitcnt lgkmcnt(0)
	v_mfma_f32_16x16x32_bf16 v[62:65], v[114:117], v[186:189], v[62:65]
	v_mfma_f32_16x16x32_bf16 v[58:61], v[130:133], v[186:189], v[58:61]
	v_mfma_f32_16x16x32_bf16 v[46:49], v[114:117], v[198:201], v[46:49]
	v_mfma_f32_16x16x32_bf16 v[42:45], v[130:133], v[198:201], v[42:45]
	v_mfma_f32_16x16x32_bf16 v[30:33], v[114:117], v[218:221], v[30:33]
	v_mfma_f32_16x16x32_bf16 v[26:29], v[130:133], v[218:221], v[26:29]
	v_mfma_f32_16x16x32_bf16 v[14:17], v[114:117], v[226:229], v[14:17]
	v_mfma_f32_16x16x32_bf16 v[10:13], v[130:133], v[226:229], v[10:13]
	v_mfma_f32_16x16x32_bf16 v[62:65], v[126:129], v[194:197], v[62:65]
	v_mfma_f32_16x16x32_bf16 v[58:61], v[134:137], v[194:197], v[58:61]
	v_mfma_f32_16x16x32_bf16 v[46:49], v[126:129], v[214:217], v[46:49]
	v_mfma_f32_16x16x32_bf16 v[42:45], v[134:137], v[214:217], v[42:45]
	v_mfma_f32_16x16x32_bf16 v[30:33], v[126:129], v[222:225], v[30:33]
	v_mfma_f32_16x16x32_bf16 v[26:29], v[134:137], v[222:225], v[26:29]
	v_mfma_f32_16x16x32_bf16 v[14:17], v[126:129], v[230:233], v[14:17]
	v_mfma_f32_16x16x32_bf16 v[10:13], v[134:137], v[230:233], v[10:13]
	s_setprio 0
	s_setprio 1
	v_mfma_f32_16x16x32_bf16 v[54:57], v[146:149], v[186:189], v[54:57]
	v_mfma_f32_16x16x32_bf16 v[50:53], v[158:161], v[186:189], v[50:53]
	v_mfma_f32_16x16x32_bf16 v[38:41], v[146:149], v[198:201], v[38:41]
	v_mfma_f32_16x16x32_bf16 v[34:37], v[158:161], v[198:201], v[34:37]
	v_mfma_f32_16x16x32_bf16 v[22:25], v[146:149], v[218:221], v[22:25]
	v_mfma_f32_16x16x32_bf16 v[18:21], v[158:161], v[218:221], v[18:21]
	v_mfma_f32_16x16x32_bf16 v[6:9], v[146:149], v[226:229], v[6:9]
	v_mfma_f32_16x16x32_bf16 v[2:5], v[158:161], v[226:229], v[2:5]
	v_mfma_f32_16x16x32_bf16 v[54:57], v[150:153], v[194:197], v[54:57]
	v_mfma_f32_16x16x32_bf16 v[50:53], v[182:185], v[194:197], v[50:53]
	v_mfma_f32_16x16x32_bf16 v[38:41], v[150:153], v[214:217], v[38:41]
	v_mfma_f32_16x16x32_bf16 v[34:37], v[182:185], v[214:217], v[34:37]
	v_mfma_f32_16x16x32_bf16 v[22:25], v[150:153], v[222:225], v[22:25]
	v_mfma_f32_16x16x32_bf16 v[18:21], v[182:185], v[222:225], v[18:21]
	v_mfma_f32_16x16x32_bf16 v[6:9], v[150:153], v[230:233], v[6:9]
	v_mfma_f32_16x16x32_bf16 v[2:5], v[182:185], v[230:233], v[2:5]
	s_setprio 0
	s_barrier
	s_add_i32 s20, 0, 0x18000
	s_add_i32 s21, 0, 0x1c000
	v_add_u32_e32 v134, s20, v191
	v_add_u32_e32 v182, s21, v191
	ds_read_b128 v[114:117], v134
	ds_read_b128 v[126:129], v134 offset:1024
	ds_read_b128 v[130:133], v134 offset:2048
	ds_read_b128 v[134:137], v134 offset:3072
	ds_read_b128 v[146:149], v182
	ds_read_b128 v[150:153], v182 offset:1024
	ds_read_b128 v[158:161], v182 offset:2048
	ds_read_b128 v[182:185], v182 offset:3072
	ds_read_b128 v[186:189], v193 offset:32768
	ds_read_b128 v[194:197], v193 offset:33792
	ds_read_b128 v[198:201], v193 offset:34816
	ds_read_b128 v[214:217], v193 offset:35840
	ds_read_b128 v[218:221], v193 offset:36864
	ds_read_b128 v[222:225], v193 offset:37888
	ds_read_b128 v[226:229], v193 offset:38912
	ds_read_b128 v[230:233], v193 offset:39936
	s_mov_b32 m0, s69
	v_lshl_add_u64 v[234:235], v[202:203], 0, s[12:13]
	global_load_lds_dwordx4 v[234:235], off
	v_lshl_add_u64 v[234:235], v[202:203], 0, s[86:87]
	s_mov_b32 m0, s76
	s_nop 0
	global_load_lds_dwordx4 v[234:235], off
	s_waitcnt vmcnt(8)
	s_waitcnt lgkmcnt(0)
	s_barrier
	s_setprio 1
	s_waitcnt lgkmcnt(0)
	v_mfma_f32_16x16x32_bf16 v[142:145], v[114:117], v[186:189], v[142:145]
	v_mfma_f32_16x16x32_bf16 v[138:141], v[130:133], v[186:189], v[138:141]
	v_mfma_f32_16x16x32_bf16 v[110:113], v[114:117], v[198:201], v[110:113]
	v_mfma_f32_16x16x32_bf16 v[106:109], v[130:133], v[198:201], v[106:109]
	v_mfma_f32_16x16x32_bf16 v[94:97], v[114:117], v[218:221], v[94:97]
	v_mfma_f32_16x16x32_bf16 v[90:93], v[130:133], v[218:221], v[90:93]
	v_mfma_f32_16x16x32_bf16 v[78:81], v[114:117], v[226:229], v[78:81]
	v_mfma_f32_16x16x32_bf16 v[74:77], v[130:133], v[226:229], v[74:77]
	v_mfma_f32_16x16x32_bf16 v[142:145], v[126:129], v[194:197], v[142:145]
	v_mfma_f32_16x16x32_bf16 v[138:141], v[134:137], v[194:197], v[138:141]
	v_mfma_f32_16x16x32_bf16 v[110:113], v[126:129], v[214:217], v[110:113]
	v_mfma_f32_16x16x32_bf16 v[106:109], v[134:137], v[214:217], v[106:109]
	v_mfma_f32_16x16x32_bf16 v[94:97], v[126:129], v[222:225], v[94:97]
	v_mfma_f32_16x16x32_bf16 v[90:93], v[134:137], v[222:225], v[90:93]
	v_mfma_f32_16x16x32_bf16 v[78:81], v[126:129], v[230:233], v[78:81]
	v_mfma_f32_16x16x32_bf16 v[74:77], v[134:137], v[230:233], v[74:77]
	s_setprio 0
	s_setprio 1
	v_mfma_f32_16x16x32_bf16 v[122:125], v[146:149], v[186:189], v[122:125]
	v_mfma_f32_16x16x32_bf16 v[118:121], v[158:161], v[186:189], v[118:121]
	v_mfma_f32_16x16x32_bf16 v[102:105], v[146:149], v[198:201], v[102:105]
	v_mfma_f32_16x16x32_bf16 v[98:101], v[158:161], v[198:201], v[98:101]
	v_mfma_f32_16x16x32_bf16 v[86:89], v[146:149], v[218:221], v[86:89]
	v_mfma_f32_16x16x32_bf16 v[82:85], v[158:161], v[218:221], v[82:85]
	v_mfma_f32_16x16x32_bf16 v[70:73], v[146:149], v[226:229], v[70:73]
	v_mfma_f32_16x16x32_bf16 v[66:69], v[158:161], v[226:229], v[66:69]
	v_mfma_f32_16x16x32_bf16 v[122:125], v[150:153], v[194:197], v[122:125]
	v_mfma_f32_16x16x32_bf16 v[118:121], v[182:185], v[194:197], v[118:121]
	v_mfma_f32_16x16x32_bf16 v[102:105], v[150:153], v[214:217], v[102:105]
	v_mfma_f32_16x16x32_bf16 v[98:101], v[182:185], v[214:217], v[98:101]
	v_mfma_f32_16x16x32_bf16 v[86:89], v[150:153], v[222:225], v[86:89]
	v_mfma_f32_16x16x32_bf16 v[82:85], v[182:185], v[222:225], v[82:85]
	v_mfma_f32_16x16x32_bf16 v[70:73], v[150:153], v[230:233], v[70:73]
	v_mfma_f32_16x16x32_bf16 v[66:69], v[182:185], v[230:233], v[66:69]
	s_setprio 0
	s_barrier
	ds_read_b128 v[186:189], v193 offset:49152
	ds_read_b128 v[194:197], v193 offset:50176
	ds_read_b128 v[198:201], v193 offset:51200
	ds_read_b128 v[214:217], v193 offset:52224
	ds_read_b128 v[218:221], v193 offset:53248
	ds_read_b128 v[222:225], v193 offset:54272
	ds_read_b128 v[226:229], v193 offset:55296
	ds_read_b128 v[230:233], v193 offset:56320
	s_add_i32 s20, s20, s46
	s_mov_b32 m0, s20
	v_lshl_add_u64 v[234:235], v[162:163], 0, s[34:35]
	global_load_lds_dwordx4 v[234:235], off
	v_lshl_add_u64 v[234:235], v[162:163], 0, s[96:97]
	s_add_i32 m0, s20, 0x2000
	s_add_i32 s20, s21, s46
	global_load_lds_dwordx4 v[234:235], off
	v_lshl_add_u64 v[234:235], v[162:163], 0, vcc
	s_mov_b32 m0, s20
	v_lshl_add_u64 v[162:163], v[162:163], 0, s[0:1]
	global_load_lds_dwordx4 v[234:235], off
	s_add_i32 m0, s20, 0x2000
	s_nop 0
	global_load_lds_dwordx4 v[162:163], off
	v_lshl_add_u64 v[162:163], v[202:203], 0, s[34:35]
	s_mov_b32 m0, s77
	s_nop 0
	global_load_lds_dwordx4 v[162:163], off
	v_lshl_add_u64 v[162:163], v[202:203], 0, s[96:97]
	s_mov_b32 m0, s78
	s_nop 0
	global_load_lds_dwordx4 v[162:163], off
	s_waitcnt vmcnt(8)
	s_waitcnt lgkmcnt(0)
	s_barrier
	s_setprio 1
	s_waitcnt lgkmcnt(0)
	v_mfma_f32_16x16x32_bf16 v[62:65], v[114:117], v[186:189], v[62:65]
	v_mfma_f32_16x16x32_bf16 v[58:61], v[130:133], v[186:189], v[58:61]
	v_mfma_f32_16x16x32_bf16 v[46:49], v[114:117], v[198:201], v[46:49]
	v_mfma_f32_16x16x32_bf16 v[42:45], v[130:133], v[198:201], v[42:45]
	v_mfma_f32_16x16x32_bf16 v[30:33], v[114:117], v[218:221], v[30:33]
	v_mfma_f32_16x16x32_bf16 v[26:29], v[130:133], v[218:221], v[26:29]
	v_mfma_f32_16x16x32_bf16 v[14:17], v[114:117], v[226:229], v[14:17]
	v_mfma_f32_16x16x32_bf16 v[10:13], v[130:133], v[226:229], v[10:13]
	v_mfma_f32_16x16x32_bf16 v[62:65], v[126:129], v[194:197], v[62:65]
	v_mfma_f32_16x16x32_bf16 v[58:61], v[134:137], v[194:197], v[58:61]
	v_mfma_f32_16x16x32_bf16 v[46:49], v[126:129], v[214:217], v[46:49]
	v_mfma_f32_16x16x32_bf16 v[42:45], v[134:137], v[214:217], v[42:45]
	v_mfma_f32_16x16x32_bf16 v[30:33], v[126:129], v[222:225], v[30:33]
	v_mfma_f32_16x16x32_bf16 v[26:29], v[134:137], v[222:225], v[26:29]
	v_mfma_f32_16x16x32_bf16 v[14:17], v[126:129], v[230:233], v[14:17]
	v_mfma_f32_16x16x32_bf16 v[10:13], v[134:137], v[230:233], v[10:13]
	s_add_i32 s84, s84, 2
	s_add_u32 s56, s56, 0x100
	s_addc_u32 s57, s57, 0
	s_add_u32 s62, s62, 0x100
	s_addc_u32 s63, s63, 0
	s_setprio 0
	s_setprio 1
	v_mfma_f32_16x16x32_bf16 v[54:57], v[146:149], v[186:189], v[54:57]
	v_mfma_f32_16x16x32_bf16 v[50:53], v[158:161], v[186:189], v[50:53]
	v_mfma_f32_16x16x32_bf16 v[38:41], v[146:149], v[198:201], v[38:41]
	v_mfma_f32_16x16x32_bf16 v[34:37], v[158:161], v[198:201], v[34:37]
	v_mfma_f32_16x16x32_bf16 v[22:25], v[146:149], v[218:221], v[22:25]
	v_mfma_f32_16x16x32_bf16 v[18:21], v[158:161], v[218:221], v[18:21]
	v_mfma_f32_16x16x32_bf16 v[6:9], v[146:149], v[226:229], v[6:9]
	v_mfma_f32_16x16x32_bf16 v[2:5], v[158:161], v[226:229], v[2:5]
	v_mfma_f32_16x16x32_bf16 v[54:57], v[150:153], v[194:197], v[54:57]
	v_mfma_f32_16x16x32_bf16 v[50:53], v[182:185], v[194:197], v[50:53]
	v_mfma_f32_16x16x32_bf16 v[38:41], v[150:153], v[214:217], v[38:41]
	v_mfma_f32_16x16x32_bf16 v[34:37], v[182:185], v[214:217], v[34:37]
	v_mfma_f32_16x16x32_bf16 v[22:25], v[150:153], v[222:225], v[22:25]
	v_mfma_f32_16x16x32_bf16 v[18:21], v[182:185], v[222:225], v[18:21]
	v_mfma_f32_16x16x32_bf16 v[6:9], v[150:153], v[230:233], v[6:9]
	v_mfma_f32_16x16x32_bf16 v[2:5], v[182:185], v[230:233], v[2:5]
	s_setprio 0
	s_barrier
	s_cmp_gt_u32 s84, 41
	s_cbranch_scc0 .LBB0_446
	s_and_b64 vcc, exec, s[40:41]
	s_cbranch_vccz .LBB0_449
	s_barrier

.Lmid1_488:
	s_add_i32 s22, 0, 0x10000
	s_add_i32 s23, 0, 0x14000
	s_add_u32 s20, s68, 0xfffc0080
	s_addc_u32 s21, s69, -1
	s_cmp_eq_u32 s97, 12
	s_cselect_b32 s77, s57, s21
	s_cselect_b32 s76, s86, s20
	s_cselect_b32 s21, s51, s96
	s_cselect_b32 s20, s87, s91
	s_add_i32 m0, s43, 0xc000
	v_lshl_add_u64 v[202:203], s[68:69], 0, v[132:133]
	global_load_lds_dwordx4 v[202:203], off
	v_lshl_add_u64 v[202:203], v[202:203], 0, s[72:73]
	s_add_i32 m0, s43, 0xe000
	s_nop 0
	global_load_lds_dwordx4 v[202:203], off
	s_waitcnt vmcnt(8)
	s_waitcnt lgkmcnt(0)
	s_barrier
	s_setprio 1
	s_waitcnt lgkmcnt(0)
	v_mfma_f32_16x16x32_bf16 v[126:129], v[134:137], v[190:193], 0
	v_mfma_f32_16x16x32_bf16 v[114:117], v[148:151], v[190:193], 0
	v_mfma_f32_16x16x32_bf16 v[110:113], v[134:137], v[198:201], 0
	v_mfma_f32_16x16x32_bf16 v[98:101], v[148:151], v[198:201], 0
	v_mfma_f32_16x16x32_bf16 v[94:97], v[134:137], v[218:221], 0
	v_mfma_f32_16x16x32_bf16 v[82:85], v[148:151], v[218:221], 0
	v_mfma_f32_16x16x32_bf16 v[78:81], v[134:137], v[226:229], 0
	v_mfma_f32_16x16x32_bf16 v[66:69], v[148:151], v[226:229], 0
	v_mfma_f32_16x16x32_bf16 v[126:129], v[144:147], v[194:197], v[126:129]
	v_mfma_f32_16x16x32_bf16 v[114:117], v[152:155], v[194:197], v[114:117]
	v_mfma_f32_16x16x32_bf16 v[110:113], v[144:147], v[214:217], v[110:113]
	v_mfma_f32_16x16x32_bf16 v[98:101], v[152:155], v[214:217], v[98:101]
	v_mfma_f32_16x16x32_bf16 v[94:97], v[144:147], v[222:225], v[94:97]
	v_mfma_f32_16x16x32_bf16 v[82:85], v[152:155], v[222:225], v[82:85]
	v_mfma_f32_16x16x32_bf16 v[78:81], v[144:147], v[230:233], v[78:81]
	v_mfma_f32_16x16x32_bf16 v[66:69], v[152:155], v[230:233], v[66:69]
	s_setprio 0
	s_setprio 1
	v_mfma_f32_16x16x32_bf16 v[122:125], v[156:159], v[190:193], 0
	v_mfma_f32_16x16x32_bf16 v[118:121], v[182:185], v[190:193], 0
	v_mfma_f32_16x16x32_bf16 v[106:109], v[156:159], v[198:201], 0
	v_mfma_f32_16x16x32_bf16 v[102:105], v[182:185], v[198:201], 0
	v_mfma_f32_16x16x32_bf16 v[90:93], v[156:159], v[218:221], 0
	v_mfma_f32_16x16x32_bf16 v[86:89], v[182:185], v[218:221], 0
	v_mfma_f32_16x16x32_bf16 v[74:77], v[156:159], v[226:229], 0
	v_mfma_f32_16x16x32_bf16 v[70:73], v[182:185], v[226:229], 0
	v_mfma_f32_16x16x32_bf16 v[122:125], v[160:163], v[194:197], v[122:125]
	v_mfma_f32_16x16x32_bf16 v[118:121], v[186:189], v[194:197], v[118:121]
	v_mfma_f32_16x16x32_bf16 v[106:109], v[160:163], v[214:217], v[106:109]
	v_mfma_f32_16x16x32_bf16 v[102:105], v[186:189], v[214:217], v[102:105]
	v_mfma_f32_16x16x32_bf16 v[90:93], v[160:163], v[222:225], v[90:93]
	v_mfma_f32_16x16x32_bf16 v[86:89], v[186:189], v[222:225], v[86:89]
	v_mfma_f32_16x16x32_bf16 v[74:77], v[160:163], v[230:233], v[74:77]
	v_mfma_f32_16x16x32_bf16 v[70:73], v[186:189], v[230:233], v[70:73]
	s_setprio 0
	s_barrier
	ds_read_b128 v[190:193], v142 offset:16384
	ds_read_b128 v[194:197], v142 offset:17408
	ds_read_b128 v[198:201], v142 offset:18432
	ds_read_b128 v[214:217], v142 offset:19456
	ds_read_b128 v[218:221], v142 offset:20480
	ds_read_b128 v[222:225], v142 offset:21504
	ds_read_b128 v[226:229], v142 offset:22528
	ds_read_b128 v[230:233], v142 offset:23552
	v_lshl_add_u64 v[202:203], s[20:21], 0, v[0:1]
	s_add_i32 s20, s22, s14
	s_mov_b32 m0, s20
	s_nop 0
	s_nop 0
	global_load_lds_dwordx4 v[202:203], off
	v_lshl_add_u64 v[234:235], v[202:203], 0, s[72:73]
	s_add_i32 m0, s20, 0x2000
	s_add_i32 s20, s23, s14
	global_load_lds_dwordx4 v[234:235], off
	v_lshl_add_u64 v[234:235], v[202:203], 0, s[28:29]
	s_mov_b32 m0, s20
	s_nop 0
	global_load_lds_dwordx4 v[234:235], off
	v_lshl_add_u64 v[234:235], v[202:203], 0, s[82:83]
	s_add_i32 m0, s20, 0x2000
	s_nop 0
	global_load_lds_dwordx4 v[234:235], off
	v_lshl_add_u64 v[234:235], s[76:77], 0, v[130:131]
	s_mov_b32 m0, s43
	v_lshl_add_u64 v[236:237], v[234:235], 0, s[72:73]
	global_load_lds_dwordx4 v[234:235], off
	s_mov_b32 m0, s46
	s_nop 0
	global_load_lds_dwordx4 v[236:237], off
	s_waitcnt vmcnt(8)
	s_waitcnt lgkmcnt(0)
	s_barrier
	s_setprio 1
	s_waitcnt lgkmcnt(0)
	v_mfma_f32_16x16x32_bf16 v[62:65], v[134:137], v[190:193], 0
	v_mfma_f32_16x16x32_bf16 v[50:53], v[148:151], v[190:193], 0
	v_mfma_f32_16x16x32_bf16 v[46:49], v[134:137], v[198:201], 0
	v_mfma_f32_16x16x32_bf16 v[34:37], v[148:151], v[198:201], 0
	v_mfma_f32_16x16x32_bf16 v[30:33], v[134:137], v[218:221], 0
	v_mfma_f32_16x16x32_bf16 v[18:21], v[148:151], v[218:221], 0
	v_mfma_f32_16x16x32_bf16 v[14:17], v[134:137], v[226:229], 0
	v_mfma_f32_16x16x32_bf16 v[6:9], v[148:151], v[226:229], 0
	v_mfma_f32_16x16x32_bf16 v[62:65], v[144:147], v[194:197], v[62:65]
	v_mfma_f32_16x16x32_bf16 v[50:53], v[152:155], v[194:197], v[50:53]
	v_mfma_f32_16x16x32_bf16 v[46:49], v[144:147], v[214:217], v[46:49]
	v_mfma_f32_16x16x32_bf16 v[34:37], v[152:155], v[214:217], v[34:37]
	v_mfma_f32_16x16x32_bf16 v[30:33], v[144:147], v[222:225], v[30:33]
	v_mfma_f32_16x16x32_bf16 v[18:21], v[152:155], v[222:225], v[18:21]
	v_mfma_f32_16x16x32_bf16 v[14:17], v[144:147], v[230:233], v[14:17]
	v_mfma_f32_16x16x32_bf16 v[6:9], v[152:155], v[230:233], v[6:9]
	s_setprio 0
	s_setprio 1
	v_mfma_f32_16x16x32_bf16 v[58:61], v[156:159], v[190:193], 0
	v_mfma_f32_16x16x32_bf16 v[54:57], v[182:185], v[190:193], 0
	v_mfma_f32_16x16x32_bf16 v[42:45], v[156:159], v[198:201], 0
	v_mfma_f32_16x16x32_bf16 v[38:41], v[182:185], v[198:201], 0
	v_mfma_f32_16x16x32_bf16 v[26:29], v[156:159], v[218:221], 0
	v_mfma_f32_16x16x32_bf16 v[22:25], v[182:185], v[218:221], 0
	v_mfma_f32_16x16x32_bf16 v[10:13], v[156:159], v[226:229], 0
	v_mfma_f32_16x16x32_bf16 v[2:5], v[182:185], v[226:229], 0
	v_mfma_f32_16x16x32_bf16 v[58:61], v[160:163], v[194:197], v[58:61]
	v_mfma_f32_16x16x32_bf16 v[54:57], v[186:189], v[194:197], v[54:57]
	v_mfma_f32_16x16x32_bf16 v[42:45], v[160:163], v[214:217], v[42:45]
	v_mfma_f32_16x16x32_bf16 v[38:41], v[186:189], v[214:217], v[38:41]
	v_mfma_f32_16x16x32_bf16 v[26:29], v[160:163], v[222:225], v[26:29]
	v_mfma_f32_16x16x32_bf16 v[22:25], v[186:189], v[222:225], v[22:25]
	v_mfma_f32_16x16x32_bf16 v[10:13], v[160:163], v[230:233], v[10:13]
	v_mfma_f32_16x16x32_bf16 v[2:5], v[186:189], v[230:233], v[2:5]
	s_setprio 0
	s_barrier
	s_add_i32 s20, 0, 0x18000
	v_add_u32_e32 v143, s20, v139
	s_add_i32 s21, 0, 0x1c000
	ds_read_b128 v[134:137], v143
	ds_read_b128 v[144:147], v143 offset:1024
	ds_read_b128 v[148:151], v143 offset:2048
	ds_read_b128 v[152:155], v143 offset:3072
	v_add_u32_e32 v143, s21, v139
	ds_read_b128 v[156:159], v143
	ds_read_b128 v[160:163], v143 offset:1024
	ds_read_b128 v[182:185], v143 offset:2048
	ds_read_b128 v[186:189], v143 offset:3072
	ds_read_b128 v[190:193], v142 offset:32768
	ds_read_b128 v[194:197], v142 offset:33792
	ds_read_b128 v[198:201], v142 offset:34816
	ds_read_b128 v[214:217], v142 offset:35840
	ds_read_b128 v[218:221], v142 offset:36864
	ds_read_b128 v[222:225], v142 offset:37888
	ds_read_b128 v[226:229], v142 offset:38912
	ds_read_b128 v[230:233], v142 offset:39936
	s_mov_b32 m0, s47
	v_lshl_add_u64 v[236:237], v[234:235], 0, s[28:29]
	global_load_lds_dwordx4 v[236:237], off
	v_lshl_add_u64 v[236:237], v[234:235], 0, s[82:83]
	s_mov_b32 m0, s78
	s_nop 0
	global_load_lds_dwordx4 v[236:237], off
	s_waitcnt vmcnt(8)
	s_waitcnt lgkmcnt(0)
	s_barrier
	s_setprio 1
	s_waitcnt lgkmcnt(0)
	v_mfma_f32_16x16x32_bf16 v[126:129], v[134:137], v[190:193], v[126:129]
	v_mfma_f32_16x16x32_bf16 v[114:117], v[148:151], v[190:193], v[114:117]
	v_mfma_f32_16x16x32_bf16 v[110:113], v[134:137], v[198:201], v[110:113]
	v_mfma_f32_16x16x32_bf16 v[98:101], v[148:151], v[198:201], v[98:101]
	v_mfma_f32_16x16x32_bf16 v[94:97], v[134:137], v[218:221], v[94:97]
	v_mfma_f32_16x16x32_bf16 v[82:85], v[148:151], v[218:221], v[82:85]
	v_mfma_f32_16x16x32_bf16 v[78:81], v[134:137], v[226:229], v[78:81]
	v_mfma_f32_16x16x32_bf16 v[66:69], v[148:151], v[226:229], v[66:69]
	v_mfma_f32_16x16x32_bf16 v[126:129], v[144:147], v[194:197], v[126:129]
	v_mfma_f32_16x16x32_bf16 v[114:117], v[152:155], v[194:197], v[114:117]
	v_mfma_f32_16x16x32_bf16 v[110:113], v[144:147], v[214:217], v[110:113]
	v_mfma_f32_16x16x32_bf16 v[98:101], v[152:155], v[214:217], v[98:101]
	v_mfma_f32_16x16x32_bf16 v[94:97], v[144:147], v[222:225], v[94:97]
	v_mfma_f32_16x16x32_bf16 v[82:85], v[152:155], v[222:225], v[82:85]
	v_mfma_f32_16x16x32_bf16 v[78:81], v[144:147], v[230:233], v[78:81]
	v_mfma_f32_16x16x32_bf16 v[66:69], v[152:155], v[230:233], v[66:69]
	s_setprio 0
	s_setprio 1
	v_mfma_f32_16x16x32_bf16 v[122:125], v[156:159], v[190:193], v[122:125]
	v_mfma_f32_16x16x32_bf16 v[118:121], v[182:185], v[190:193], v[118:121]
	v_mfma_f32_16x16x32_bf16 v[106:109], v[156:159], v[198:201], v[106:109]
	v_mfma_f32_16x16x32_bf16 v[102:105], v[182:185], v[198:201], v[102:105]
	v_mfma_f32_16x16x32_bf16 v[90:93], v[156:159], v[218:221], v[90:93]
	v_mfma_f32_16x16x32_bf16 v[86:89], v[182:185], v[218:221], v[86:89]
	v_mfma_f32_16x16x32_bf16 v[74:77], v[156:159], v[226:229], v[74:77]
	v_mfma_f32_16x16x32_bf16 v[70:73], v[182:185], v[226:229], v[70:73]
	v_mfma_f32_16x16x32_bf16 v[122:125], v[160:163], v[194:197], v[122:125]
	v_mfma_f32_16x16x32_bf16 v[118:121], v[186:189], v[194:197], v[118:121]
	v_mfma_f32_16x16x32_bf16 v[106:109], v[160:163], v[214:217], v[106:109]
	v_mfma_f32_16x16x32_bf16 v[102:105], v[186:189], v[214:217], v[102:105]
	v_mfma_f32_16x16x32_bf16 v[90:93], v[160:163], v[222:225], v[90:93]
	v_mfma_f32_16x16x32_bf16 v[86:89], v[186:189], v[222:225], v[86:89]
	v_mfma_f32_16x16x32_bf16 v[74:77], v[160:163], v[230:233], v[74:77]
	v_mfma_f32_16x16x32_bf16 v[70:73], v[186:189], v[230:233], v[70:73]
	s_setprio 0
	s_barrier
	ds_read_b128 v[190:193], v142 offset:49152
	ds_read_b128 v[194:197], v142 offset:50176
	ds_read_b128 v[198:201], v142 offset:51200
	ds_read_b128 v[214:217], v142 offset:52224
	ds_read_b128 v[218:221], v142 offset:53248
	ds_read_b128 v[222:225], v142 offset:54272
	ds_read_b128 v[226:229], v142 offset:55296
	ds_read_b128 v[230:233], v142 offset:56320
	s_add_i32 s20, s20, s14
	s_mov_b32 m0, s20
	v_lshl_add_u64 v[236:237], v[202:203], 0, s[34:35]
	global_load_lds_dwordx4 v[236:237], off
	v_lshl_add_u64 v[236:237], v[202:203], 0, s[38:39]
	s_add_i32 m0, s20, 0x2000
	s_add_i32 s20, s21, s14
	global_load_lds_dwordx4 v[236:237], off
	v_lshl_add_u64 v[236:237], v[202:203], 0, s[44:45]
	s_mov_b32 m0, s20
	v_lshl_add_u64 v[202:203], v[202:203], 0, s[10:11]
	global_load_lds_dwordx4 v[236:237], off
	s_add_i32 m0, s20, 0x2000
	s_nop 0
	global_load_lds_dwordx4 v[202:203], off
	v_lshl_add_u64 v[202:203], v[234:235], 0, s[34:35]
	s_mov_b32 m0, s79
	s_nop 0
	global_load_lds_dwordx4 v[202:203], off
	v_lshl_add_u64 v[202:203], v[234:235], 0, s[38:39]
	s_mov_b32 m0, s88
	s_nop 0
	global_load_lds_dwordx4 v[202:203], off
	s_waitcnt vmcnt(8)
	s_waitcnt lgkmcnt(0)
	s_barrier
	s_setprio 1
	s_waitcnt lgkmcnt(0)
	v_mfma_f32_16x16x32_bf16 v[62:65], v[134:137], v[190:193], v[62:65]
	v_mfma_f32_16x16x32_bf16 v[50:53], v[148:151], v[190:193], v[50:53]
	v_mfma_f32_16x16x32_bf16 v[46:49], v[134:137], v[198:201], v[46:49]
	v_mfma_f32_16x16x32_bf16 v[34:37], v[148:151], v[198:201], v[34:37]
	v_mfma_f32_16x16x32_bf16 v[30:33], v[134:137], v[218:221], v[30:33]
	v_mfma_f32_16x16x32_bf16 v[18:21], v[148:151], v[218:221], v[18:21]
	v_mfma_f32_16x16x32_bf16 v[14:17], v[134:137], v[226:229], v[14:17]
	v_mfma_f32_16x16x32_bf16 v[6:9], v[148:151], v[226:229], v[6:9]
	v_mfma_f32_16x16x32_bf16 v[62:65], v[144:147], v[194:197], v[62:65]
	v_mfma_f32_16x16x32_bf16 v[50:53], v[152:155], v[194:197], v[50:53]
	v_mfma_f32_16x16x32_bf16 v[46:49], v[144:147], v[214:217], v[46:49]
	v_mfma_f32_16x16x32_bf16 v[34:37], v[152:155], v[214:217], v[34:37]
	v_mfma_f32_16x16x32_bf16 v[30:33], v[144:147], v[222:225], v[30:33]
	v_mfma_f32_16x16x32_bf16 v[18:21], v[152:155], v[222:225], v[18:21]
	v_mfma_f32_16x16x32_bf16 v[14:17], v[144:147], v[230:233], v[14:17]
	v_mfma_f32_16x16x32_bf16 v[6:9], v[152:155], v[230:233], v[6:9]
	s_add_i32 s97, s97, 2
	s_add_u32 s68, s68, 0x100
	s_addc_u32 s69, s69, 0
	s_add_u32 s91, s91, 0x100
	s_addc_u32 s96, s96, 0
	s_setprio 0
	s_setprio 1
	v_mfma_f32_16x16x32_bf16 v[58:61], v[156:159], v[190:193], v[58:61]
	v_mfma_f32_16x16x32_bf16 v[54:57], v[182:185], v[190:193], v[54:57]
	v_mfma_f32_16x16x32_bf16 v[42:45], v[156:159], v[198:201], v[42:45]
	v_mfma_f32_16x16x32_bf16 v[38:41], v[182:185], v[198:201], v[38:41]
	v_mfma_f32_16x16x32_bf16 v[26:29], v[156:159], v[218:221], v[26:29]
	v_mfma_f32_16x16x32_bf16 v[22:25], v[182:185], v[218:221], v[22:25]
	v_mfma_f32_16x16x32_bf16 v[10:13], v[156:159], v[226:229], v[10:13]
	v_mfma_f32_16x16x32_bf16 v[2:5], v[182:185], v[226:229], v[2:5]
	v_mfma_f32_16x16x32_bf16 v[58:61], v[160:163], v[194:197], v[58:61]
	v_mfma_f32_16x16x32_bf16 v[54:57], v[186:189], v[194:197], v[54:57]
	v_mfma_f32_16x16x32_bf16 v[42:45], v[160:163], v[214:217], v[42:45]
	v_mfma_f32_16x16x32_bf16 v[38:41], v[186:189], v[214:217], v[38:41]
	v_mfma_f32_16x16x32_bf16 v[26:29], v[160:163], v[222:225], v[26:29]
	v_mfma_f32_16x16x32_bf16 v[22:25], v[186:189], v[222:225], v[22:25]
	v_mfma_f32_16x16x32_bf16 v[10:13], v[160:163], v[230:233], v[10:13]
	v_mfma_f32_16x16x32_bf16 v[2:5], v[186:189], v[230:233], v[2:5]
	s_setprio 0
	s_barrier
	s_branch .LBB0_488
	.p2alignl 6, 3212836864
.LBB0_488:
	s_add_i32 s22, 0, 0x10000
	v_add_u32_e32 v143, s22, v139
	s_add_i32 s23, 0, 0x14000
	ds_read_b128 v[134:137], v143
	ds_read_b128 v[144:147], v143 offset:1024
	ds_read_b128 v[148:151], v143 offset:2048
	ds_read_b128 v[152:155], v143 offset:3072
	v_add_u32_e32 v143, s23, v139
	ds_read_b128 v[156:159], v143
	ds_read_b128 v[160:163], v143 offset:1024
	ds_read_b128 v[182:185], v143 offset:2048
	ds_read_b128 v[186:189], v143 offset:3072
	ds_read_b128 v[190:193], v142
	ds_read_b128 v[194:197], v142 offset:1024
	ds_read_b128 v[198:201], v142 offset:2048
	ds_read_b128 v[214:217], v142 offset:3072
	ds_read_b128 v[218:221], v142 offset:4096
	ds_read_b128 v[222:225], v142 offset:5120
	ds_read_b128 v[226:229], v142 offset:6144
	ds_read_b128 v[230:233], v142 offset:7168
	s_add_u32 s20, s68, 0xfffc0080
	s_addc_u32 s21, s69, -1
	s_cmp_eq_u32 s97, 12
	s_cselect_b32 s77, s57, s21
	s_cselect_b32 s76, s86, s20
	s_cselect_b32 s21, s51, s96
	s_cselect_b32 s20, s87, s91
	s_add_i32 m0, s43, 0xc000
	v_lshl_add_u64 v[202:203], s[68:69], 0, v[132:133]
	global_load_lds_dwordx4 v[202:203], off
	v_lshl_add_u64 v[202:203], v[202:203], 0, s[72:73]
	s_add_i32 m0, s43, 0xe000
	s_nop 0
	global_load_lds_dwordx4 v[202:203], off
	s_waitcnt vmcnt(8)
	s_waitcnt lgkmcnt(0)
	s_barrier
	s_setprio 1
	s_waitcnt lgkmcnt(0)
	v_mfma_f32_16x16x32_bf16 v[126:129], v[134:137], v[190:193], v[126:129]
	v_mfma_f32_16x16x32_bf16 v[114:117], v[148:151], v[190:193], v[114:117]
	v_mfma_f32_16x16x32_bf16 v[110:113], v[134:137], v[198:201], v[110:113]
	v_mfma_f32_16x16x32_bf16 v[98:101], v[148:151], v[198:201], v[98:101]
	v_mfma_f32_16x16x32_bf16 v[94:97], v[134:137], v[218:221], v[94:97]
	v_mfma_f32_16x16x32_bf16 v[82:85], v[148:151], v[218:221], v[82:85]
	v_mfma_f32_16x16x32_bf16 v[78:81], v[134:137], v[226:229], v[78:81]
	v_mfma_f32_16x16x32_bf16 v[66:69], v[148:151], v[226:229], v[66:69]
	v_mfma_f32_16x16x32_bf16 v[126:129], v[144:147], v[194:197], v[126:129]
	v_mfma_f32_16x16x32_bf16 v[114:117], v[152:155], v[194:197], v[114:117]
	v_mfma_f32_16x16x32_bf16 v[110:113], v[144:147], v[214:217], v[110:113]
	v_mfma_f32_16x16x32_bf16 v[98:101], v[152:155], v[214:217], v[98:101]
	v_mfma_f32_16x16x32_bf16 v[94:97], v[144:147], v[222:225], v[94:97]
	v_mfma_f32_16x16x32_bf16 v[82:85], v[152:155], v[222:225], v[82:85]
	v_mfma_f32_16x16x32_bf16 v[78:81], v[144:147], v[230:233], v[78:81]
	v_mfma_f32_16x16x32_bf16 v[66:69], v[152:155], v[230:233], v[66:69]
	s_setprio 0
	s_setprio 1
	v_mfma_f32_16x16x32_bf16 v[122:125], v[156:159], v[190:193], v[122:125]
	v_mfma_f32_16x16x32_bf16 v[118:121], v[182:185], v[190:193], v[118:121]
	v_mfma_f32_16x16x32_bf16 v[106:109], v[156:159], v[198:201], v[106:109]
	v_mfma_f32_16x16x32_bf16 v[102:105], v[182:185], v[198:201], v[102:105]
	v_mfma_f32_16x16x32_bf16 v[90:93], v[156:159], v[218:221], v[90:93]
	v_mfma_f32_16x16x32_bf16 v[86:89], v[182:185], v[218:221], v[86:89]
	v_mfma_f32_16x16x32_bf16 v[74:77], v[156:159], v[226:229], v[74:77]
	v_mfma_f32_16x16x32_bf16 v[70:73], v[182:185], v[226:229], v[70:73]
	v_mfma_f32_16x16x32_bf16 v[122:125], v[160:163], v[194:197], v[122:125]
	v_mfma_f32_16x16x32_bf16 v[118:121], v[186:189], v[194:197], v[118:121]
	v_mfma_f32_16x16x32_bf16 v[106:109], v[160:163], v[214:217], v[106:109]
	v_mfma_f32_16x16x32_bf16 v[102:105], v[186:189], v[214:217], v[102:105]
	v_mfma_f32_16x16x32_bf16 v[90:93], v[160:163], v[222:225], v[90:93]
	v_mfma_f32_16x16x32_bf16 v[86:89], v[186:189], v[222:225], v[86:89]
	v_mfma_f32_16x16x32_bf16 v[74:77], v[160:163], v[230:233], v[74:77]
	v_mfma_f32_16x16x32_bf16 v[70:73], v[186:189], v[230:233], v[70:73]
	s_setprio 0
	s_barrier
	ds_read_b128 v[190:193], v142 offset:16384
	ds_read_b128 v[194:197], v142 offset:17408
	ds_read_b128 v[198:201], v142 offset:18432
	ds_read_b128 v[214:217], v142 offset:19456
	ds_read_b128 v[218:221], v142 offset:20480
	ds_read_b128 v[222:225], v142 offset:21504
	ds_read_b128 v[226:229], v142 offset:22528
	ds_read_b128 v[230:233], v142 offset:23552
	v_lshl_add_u64 v[202:203], s[20:21], 0, v[0:1]
	s_add_i32 s20, s22, s14
	s_mov_b32 m0, s20
	s_nop 0
	s_nop 0
	global_load_lds_dwordx4 v[202:203], off
	v_lshl_add_u64 v[234:235], v[202:203], 0, s[72:73]
	s_add_i32 m0, s20, 0x2000
	s_add_i32 s20, s23, s14
	global_load_lds_dwordx4 v[234:235], off
	v_lshl_add_u64 v[234:235], v[202:203], 0, s[28:29]
	s_mov_b32 m0, s20
	s_nop 0
	global_load_lds_dwordx4 v[234:235], off
	v_lshl_add_u64 v[234:235], v[202:203], 0, s[82:83]
	s_add_i32 m0, s20, 0x2000
	s_nop 0
	global_load_lds_dwordx4 v[234:235], off
	v_lshl_add_u64 v[234:235], s[76:77], 0, v[130:131]
	s_mov_b32 m0, s43
	v_lshl_add_u64 v[236:237], v[234:235], 0, s[72:73]
	global_load_lds_dwordx4 v[234:235], off
	s_mov_b32 m0, s46
	s_nop 0
	global_load_lds_dwordx4 v[236:237], off
	s_waitcnt vmcnt(8)
	s_waitcnt lgkmcnt(0)
	s_barrier
	s_setprio 1
	s_waitcnt lgkmcnt(0)
	v_mfma_f32_16x16x32_bf16 v[62:65], v[134:137], v[190:193], v[62:65]
	v_mfma_f32_16x16x32_bf16 v[50:53], v[148:151], v[190:193], v[50:53]
	v_mfma_f32_16x16x32_bf16 v[46:49], v[134:137], v[198:201], v[46:49]
	v_mfma_f32_16x16x32_bf16 v[34:37], v[148:151], v[198:201], v[34:37]
	v_mfma_f32_16x16x32_bf16 v[30:33], v[134:137], v[218:221], v[30:33]
	v_mfma_f32_16x16x32_bf16 v[18:21], v[148:151], v[218:221], v[18:21]
	v_mfma_f32_16x16x32_bf16 v[14:17], v[134:137], v[226:229], v[14:17]
	v_mfma_f32_16x16x32_bf16 v[6:9], v[148:151], v[226:229], v[6:9]
	v_mfma_f32_16x16x32_bf16 v[62:65], v[144:147], v[194:197], v[62:65]
	v_mfma_f32_16x16x32_bf16 v[50:53], v[152:155], v[194:197], v[50:53]
	v_mfma_f32_16x16x32_bf16 v[46:49], v[144:147], v[214:217], v[46:49]
	v_mfma_f32_16x16x32_bf16 v[34:37], v[152:155], v[214:217], v[34:37]
	v_mfma_f32_16x16x32_bf16 v[30:33], v[144:147], v[222:225], v[30:33]
	v_mfma_f32_16x16x32_bf16 v[18:21], v[152:155], v[222:225], v[18:21]
	v_mfma_f32_16x16x32_bf16 v[14:17], v[144:147], v[230:233], v[14:17]
	v_mfma_f32_16x16x32_bf16 v[6:9], v[152:155], v[230:233], v[6:9]
	s_setprio 0
	s_setprio 1
	v_mfma_f32_16x16x32_bf16 v[58:61], v[156:159], v[190:193], v[58:61]
	v_mfma_f32_16x16x32_bf16 v[54:57], v[182:185], v[190:193], v[54:57]
	v_mfma_f32_16x16x32_bf16 v[42:45], v[156:159], v[198:201], v[42:45]
	v_mfma_f32_16x16x32_bf16 v[38:41], v[182:185], v[198:201], v[38:41]
	v_mfma_f32_16x16x32_bf16 v[26:29], v[156:159], v[218:221], v[26:29]
	v_mfma_f32_16x16x32_bf16 v[22:25], v[182:185], v[218:221], v[22:25]
	v_mfma_f32_16x16x32_bf16 v[10:13], v[156:159], v[226:229], v[10:13]
	v_mfma_f32_16x16x32_bf16 v[2:5], v[182:185], v[226:229], v[2:5]
	v_mfma_f32_16x16x32_bf16 v[58:61], v[160:163], v[194:197], v[58:61]
	v_mfma_f32_16x16x32_bf16 v[54:57], v[186:189], v[194:197], v[54:57]
	v_mfma_f32_16x16x32_bf16 v[42:45], v[160:163], v[214:217], v[42:45]
	v_mfma_f32_16x16x32_bf16 v[38:41], v[186:189], v[214:217], v[38:41]
	v_mfma_f32_16x16x32_bf16 v[26:29], v[160:163], v[222:225], v[26:29]
	v_mfma_f32_16x16x32_bf16 v[22:25], v[186:189], v[222:225], v[22:25]
	v_mfma_f32_16x16x32_bf16 v[10:13], v[160:163], v[230:233], v[10:13]
	v_mfma_f32_16x16x32_bf16 v[2:5], v[186:189], v[230:233], v[2:5]
	s_setprio 0
	s_barrier
	s_add_i32 s20, 0, 0x18000
	v_add_u32_e32 v143, s20, v139
	s_add_i32 s21, 0, 0x1c000
	ds_read_b128 v[134:137], v143
	ds_read_b128 v[144:147], v143 offset:1024
	ds_read_b128 v[148:151], v143 offset:2048
	ds_read_b128 v[152:155], v143 offset:3072
	v_add_u32_e32 v143, s21, v139
	ds_read_b128 v[156:159], v143
	ds_read_b128 v[160:163], v143 offset:1024
	ds_read_b128 v[182:185], v143 offset:2048
	ds_read_b128 v[186:189], v143 offset:3072
	ds_read_b128 v[190:193], v142 offset:32768
	ds_read_b128 v[194:197], v142 offset:33792
	ds_read_b128 v[198:201], v142 offset:34816
	ds_read_b128 v[214:217], v142 offset:35840
	ds_read_b128 v[218:221], v142 offset:36864
	ds_read_b128 v[222:225], v142 offset:37888
	ds_read_b128 v[226:229], v142 offset:38912
	ds_read_b128 v[230:233], v142 offset:39936
	s_mov_b32 m0, s47
	v_lshl_add_u64 v[236:237], v[234:235], 0, s[28:29]
	global_load_lds_dwordx4 v[236:237], off
	v_lshl_add_u64 v[236:237], v[234:235], 0, s[82:83]
	s_mov_b32 m0, s78
	s_nop 0
	global_load_lds_dwordx4 v[236:237], off
	s_waitcnt vmcnt(8)
	s_waitcnt lgkmcnt(0)
	s_barrier
	s_setprio 1
	s_waitcnt lgkmcnt(0)
	v_mfma_f32_16x16x32_bf16 v[126:129], v[134:137], v[190:193], v[126:129]
	v_mfma_f32_16x16x32_bf16 v[114:117], v[148:151], v[190:193], v[114:117]
	v_mfma_f32_16x16x32_bf16 v[110:113], v[134:137], v[198:201], v[110:113]
	v_mfma_f32_16x16x32_bf16 v[98:101], v[148:151], v[198:201], v[98:101]
	v_mfma_f32_16x16x32_bf16 v[94:97], v[134:137], v[218:221], v[94:97]
	v_mfma_f32_16x16x32_bf16 v[82:85], v[148:151], v[218:221], v[82:85]
	v_mfma_f32_16x16x32_bf16 v[78:81], v[134:137], v[226:229], v[78:81]
	v_mfma_f32_16x16x32_bf16 v[66:69], v[148:151], v[226:229], v[66:69]
	v_mfma_f32_16x16x32_bf16 v[126:129], v[144:147], v[194:197], v[126:129]
	v_mfma_f32_16x16x32_bf16 v[114:117], v[152:155], v[194:197], v[114:117]
	v_mfma_f32_16x16x32_bf16 v[110:113], v[144:147], v[214:217], v[110:113]
	v_mfma_f32_16x16x32_bf16 v[98:101], v[152:155], v[214:217], v[98:101]
	v_mfma_f32_16x16x32_bf16 v[94:97], v[144:147], v[222:225], v[94:97]
	v_mfma_f32_16x16x32_bf16 v[82:85], v[152:155], v[222:225], v[82:85]
	v_mfma_f32_16x16x32_bf16 v[78:81], v[144:147], v[230:233], v[78:81]
	v_mfma_f32_16x16x32_bf16 v[66:69], v[152:155], v[230:233], v[66:69]
	s_setprio 0
	s_setprio 1
	v_mfma_f32_16x16x32_bf16 v[122:125], v[156:159], v[190:193], v[122:125]
	v_mfma_f32_16x16x32_bf16 v[118:121], v[182:185], v[190:193], v[118:121]
	v_mfma_f32_16x16x32_bf16 v[106:109], v[156:159], v[198:201], v[106:109]
	v_mfma_f32_16x16x32_bf16 v[102:105], v[182:185], v[198:201], v[102:105]
	v_mfma_f32_16x16x32_bf16 v[90:93], v[156:159], v[218:221], v[90:93]
	v_mfma_f32_16x16x32_bf16 v[86:89], v[182:185], v[218:221], v[86:89]
	v_mfma_f32_16x16x32_bf16 v[74:77], v[156:159], v[226:229], v[74:77]
	v_mfma_f32_16x16x32_bf16 v[70:73], v[182:185], v[226:229], v[70:73]
	v_mfma_f32_16x16x32_bf16 v[122:125], v[160:163], v[194:197], v[122:125]
	v_mfma_f32_16x16x32_bf16 v[118:121], v[186:189], v[194:197], v[118:121]
	v_mfma_f32_16x16x32_bf16 v[106:109], v[160:163], v[214:217], v[106:109]
	v_mfma_f32_16x16x32_bf16 v[102:105], v[186:189], v[214:217], v[102:105]
	v_mfma_f32_16x16x32_bf16 v[90:93], v[160:163], v[222:225], v[90:93]
	v_mfma_f32_16x16x32_bf16 v[86:89], v[186:189], v[222:225], v[86:89]
	v_mfma_f32_16x16x32_bf16 v[74:77], v[160:163], v[230:233], v[74:77]
	v_mfma_f32_16x16x32_bf16 v[70:73], v[186:189], v[230:233], v[70:73]
	s_setprio 0
	s_barrier
	ds_read_b128 v[190:193], v142 offset:49152
	ds_read_b128 v[194:197], v142 offset:50176
	ds_read_b128 v[198:201], v142 offset:51200
	ds_read_b128 v[214:217], v142 offset:52224
	ds_read_b128 v[218:221], v142 offset:53248
	ds_read_b128 v[222:225], v142 offset:54272
	ds_read_b128 v[226:229], v142 offset:55296
	ds_read_b128 v[230:233], v142 offset:56320
	s_add_i32 s20, s20, s14
	s_mov_b32 m0, s20
	v_lshl_add_u64 v[236:237], v[202:203], 0, s[34:35]
	global_load_lds_dwordx4 v[236:237], off
	v_lshl_add_u64 v[236:237], v[202:203], 0, s[38:39]
	s_add_i32 m0, s20, 0x2000
	s_add_i32 s20, s21, s14
	global_load_lds_dwordx4 v[236:237], off
	v_lshl_add_u64 v[236:237], v[202:203], 0, s[44:45]
	s_mov_b32 m0, s20
	v_lshl_add_u64 v[202:203], v[202:203], 0, s[10:11]
	global_load_lds_dwordx4 v[236:237], off
	s_add_i32 m0, s20, 0x2000
	s_nop 0
	global_load_lds_dwordx4 v[202:203], off
	v_lshl_add_u64 v[202:203], v[234:235], 0, s[34:35]
	s_mov_b32 m0, s79
	s_nop 0
	global_load_lds_dwordx4 v[202:203], off
	v_lshl_add_u64 v[202:203], v[234:235], 0, s[38:39]
	s_mov_b32 m0, s88
	s_nop 0
	global_load_lds_dwordx4 v[202:203], off
	s_waitcnt vmcnt(8)
	s_waitcnt lgkmcnt(0)
	s_barrier
	s_setprio 1
	s_waitcnt lgkmcnt(0)
	v_mfma_f32_16x16x32_bf16 v[62:65], v[134:137], v[190:193], v[62:65]
	v_mfma_f32_16x16x32_bf16 v[50:53], v[148:151], v[190:193], v[50:53]
	v_mfma_f32_16x16x32_bf16 v[46:49], v[134:137], v[198:201], v[46:49]
	v_mfma_f32_16x16x32_bf16 v[34:37], v[148:151], v[198:201], v[34:37]
	v_mfma_f32_16x16x32_bf16 v[30:33], v[134:137], v[218:221], v[30:33]
	v_mfma_f32_16x16x32_bf16 v[18:21], v[148:151], v[218:221], v[18:21]
	v_mfma_f32_16x16x32_bf16 v[14:17], v[134:137], v[226:229], v[14:17]
	v_mfma_f32_16x16x32_bf16 v[6:9], v[148:151], v[226:229], v[6:9]
	v_mfma_f32_16x16x32_bf16 v[62:65], v[144:147], v[194:197], v[62:65]
	v_mfma_f32_16x16x32_bf16 v[50:53], v[152:155], v[194:197], v[50:53]
	v_mfma_f32_16x16x32_bf16 v[46:49], v[144:147], v[214:217], v[46:49]
	v_mfma_f32_16x16x32_bf16 v[34:37], v[152:155], v[214:217], v[34:37]
	v_mfma_f32_16x16x32_bf16 v[30:33], v[144:147], v[222:225], v[30:33]
	v_mfma_f32_16x16x32_bf16 v[18:21], v[152:155], v[222:225], v[18:21]
	v_mfma_f32_16x16x32_bf16 v[14:17], v[144:147], v[230:233], v[14:17]
	v_mfma_f32_16x16x32_bf16 v[6:9], v[152:155], v[230:233], v[6:9]
	s_add_i32 s97, s97, 2
	s_add_u32 s68, s68, 0x100
	s_addc_u32 s69, s69, 0
	s_add_u32 s91, s91, 0x100
	s_addc_u32 s96, s96, 0
	s_setprio 0
	s_setprio 1
	v_mfma_f32_16x16x32_bf16 v[58:61], v[156:159], v[190:193], v[58:61]
	v_mfma_f32_16x16x32_bf16 v[54:57], v[182:185], v[190:193], v[54:57]
	v_mfma_f32_16x16x32_bf16 v[42:45], v[156:159], v[198:201], v[42:45]
	v_mfma_f32_16x16x32_bf16 v[38:41], v[182:185], v[198:201], v[38:41]
	v_mfma_f32_16x16x32_bf16 v[26:29], v[156:159], v[218:221], v[26:29]
	v_mfma_f32_16x16x32_bf16 v[22:25], v[182:185], v[218:221], v[22:25]
	v_mfma_f32_16x16x32_bf16 v[10:13], v[156:159], v[226:229], v[10:13]
	v_mfma_f32_16x16x32_bf16 v[2:5], v[182:185], v[226:229], v[2:5]
	v_mfma_f32_16x16x32_bf16 v[58:61], v[160:163], v[194:197], v[58:61]
	v_mfma_f32_16x16x32_bf16 v[54:57], v[186:189], v[194:197], v[54:57]
	v_mfma_f32_16x16x32_bf16 v[42:45], v[160:163], v[214:217], v[42:45]
	v_mfma_f32_16x16x32_bf16 v[38:41], v[186:189], v[214:217], v[38:41]
	v_mfma_f32_16x16x32_bf16 v[26:29], v[160:163], v[222:225], v[26:29]
	v_mfma_f32_16x16x32_bf16 v[22:25], v[186:189], v[222:225], v[22:25]
	v_mfma_f32_16x16x32_bf16 v[10:13], v[160:163], v[230:233], v[10:13]
	v_mfma_f32_16x16x32_bf16 v[2:5], v[186:189], v[230:233], v[2:5]
	s_setprio 0
	s_barrier
	s_cmp_gt_u32 s97, 13
	s_cbranch_scc0 .LBB0_488
	s_and_b64 vcc, exec, s[48:49]
	s_cbranch_vccz .LBB0_491
	s_barrier

.Lmid1_604:
	s_add_i32 s22, 0, 0x10000
	s_add_i32 s23, 0, 0x14000
	s_add_u32 s20, s6, 0xfffe0080
	s_addc_u32 s21, s7, -1
	s_cmp_eq_u32 s84, 4
	s_cselect_b32 s69, s42, s21
	s_cselect_b32 s68, s43, s20
	s_cselect_b32 s21, s46, s51
	s_cselect_b32 s20, s47, s49
	s_add_i32 m0, s89, 0xc000
	v_lshl_add_u64 v[162:163], s[6:7], 0, v[132:133]
	global_load_lds_dwordx4 v[162:163], off
	v_lshl_add_u64 v[162:163], v[162:163], 0, s[64:65]
	s_add_i32 m0, s89, 0xe000
	s_nop 0
	global_load_lds_dwordx4 v[162:163], off
	s_waitcnt vmcnt(8)
	s_waitcnt lgkmcnt(0)
	s_barrier
	s_setprio 1
	s_waitcnt lgkmcnt(0)
	v_mfma_f32_16x16x32_bf16 v[126:129], v[134:137], v[190:193], 0
	v_mfma_f32_16x16x32_bf16 v[122:125], v[146:149], v[190:193], 0
	v_mfma_f32_16x16x32_bf16 v[110:113], v[134:137], v[198:201], 0
	v_mfma_f32_16x16x32_bf16 v[106:109], v[146:149], v[198:201], 0
	v_mfma_f32_16x16x32_bf16 v[94:97], v[134:137], v[218:221], 0
	v_mfma_f32_16x16x32_bf16 v[90:93], v[146:149], v[218:221], 0
	v_mfma_f32_16x16x32_bf16 v[78:81], v[134:137], v[226:229], 0
	v_mfma_f32_16x16x32_bf16 v[74:77], v[146:149], v[226:229], 0
	v_mfma_f32_16x16x32_bf16 v[126:129], v[142:145], v[194:197], v[126:129]
	v_mfma_f32_16x16x32_bf16 v[122:125], v[150:153], v[194:197], v[122:125]
	v_mfma_f32_16x16x32_bf16 v[110:113], v[142:145], v[214:217], v[110:113]
	v_mfma_f32_16x16x32_bf16 v[106:109], v[150:153], v[214:217], v[106:109]
	v_mfma_f32_16x16x32_bf16 v[94:97], v[142:145], v[222:225], v[94:97]
	v_mfma_f32_16x16x32_bf16 v[90:93], v[150:153], v[222:225], v[90:93]
	v_mfma_f32_16x16x32_bf16 v[78:81], v[142:145], v[230:233], v[78:81]
	v_mfma_f32_16x16x32_bf16 v[74:77], v[150:153], v[230:233], v[74:77]
	s_setprio 0
	s_setprio 1
	v_mfma_f32_16x16x32_bf16 v[118:121], v[154:157], v[190:193], 0
	v_mfma_f32_16x16x32_bf16 v[114:117], v[182:185], v[190:193], 0
	v_mfma_f32_16x16x32_bf16 v[102:105], v[154:157], v[198:201], 0
	v_mfma_f32_16x16x32_bf16 v[98:101], v[182:185], v[198:201], 0
	v_mfma_f32_16x16x32_bf16 v[86:89], v[154:157], v[218:221], 0
	v_mfma_f32_16x16x32_bf16 v[82:85], v[182:185], v[218:221], 0
	v_mfma_f32_16x16x32_bf16 v[70:73], v[154:157], v[226:229], 0
	v_mfma_f32_16x16x32_bf16 v[66:69], v[182:185], v[226:229], 0
	v_mfma_f32_16x16x32_bf16 v[118:121], v[158:161], v[194:197], v[118:121]
	v_mfma_f32_16x16x32_bf16 v[114:117], v[186:189], v[194:197], v[114:117]
	v_mfma_f32_16x16x32_bf16 v[102:105], v[158:161], v[214:217], v[102:105]
	v_mfma_f32_16x16x32_bf16 v[98:101], v[186:189], v[214:217], v[98:101]
	v_mfma_f32_16x16x32_bf16 v[86:89], v[158:161], v[222:225], v[86:89]
	v_mfma_f32_16x16x32_bf16 v[82:85], v[186:189], v[222:225], v[82:85]
	v_mfma_f32_16x16x32_bf16 v[70:73], v[158:161], v[230:233], v[70:73]
	v_mfma_f32_16x16x32_bf16 v[66:69], v[186:189], v[230:233], v[66:69]
	s_setprio 0
	s_barrier
	ds_read_b128 v[190:193], v141 offset:16384
	ds_read_b128 v[194:197], v141 offset:17408
	ds_read_b128 v[198:201], v141 offset:18432
	ds_read_b128 v[214:217], v141 offset:19456
	ds_read_b128 v[218:221], v141 offset:20480
	ds_read_b128 v[222:225], v141 offset:21504
	ds_read_b128 v[226:229], v141 offset:22528
	ds_read_b128 v[230:233], v141 offset:23552
	v_lshl_add_u64 v[162:163], s[20:21], 0, v[0:1]
	s_add_i32 s20, s22, s88
	s_mov_b32 m0, s20
	s_nop 0
	s_nop 0
	global_load_lds_dwordx4 v[162:163], off
	v_lshl_add_u64 v[202:203], v[162:163], 0, s[64:65]
	s_add_i32 m0, s20, 0x2000
	s_add_i32 s20, s23, s88
	global_load_lds_dwordx4 v[202:203], off
	v_lshl_add_u64 v[202:203], v[162:163], 0, s[72:73]
	s_mov_b32 m0, s20
	s_nop 0
	global_load_lds_dwordx4 v[202:203], off
	v_lshl_add_u64 v[202:203], v[162:163], 0, s[74:75]
	s_add_i32 m0, s20, 0x2000
	s_nop 0
	global_load_lds_dwordx4 v[202:203], off
	v_lshl_add_u64 v[202:203], s[68:69], 0, v[130:131]
	s_mov_b32 m0, s89
	v_lshl_add_u64 v[234:235], v[202:203], 0, s[64:65]
	global_load_lds_dwordx4 v[202:203], off
	s_mov_b32 m0, s90
	s_nop 0
	global_load_lds_dwordx4 v[234:235], off
	s_waitcnt vmcnt(8)
	s_waitcnt lgkmcnt(0)
	s_barrier
	s_setprio 1
	s_waitcnt lgkmcnt(0)
	v_mfma_f32_16x16x32_bf16 v[62:65], v[134:137], v[190:193], 0
	v_mfma_f32_16x16x32_bf16 v[58:61], v[146:149], v[190:193], 0
	v_mfma_f32_16x16x32_bf16 v[46:49], v[134:137], v[198:201], 0
	v_mfma_f32_16x16x32_bf16 v[42:45], v[146:149], v[198:201], 0
	v_mfma_f32_16x16x32_bf16 v[30:33], v[134:137], v[218:221], 0
	v_mfma_f32_16x16x32_bf16 v[26:29], v[146:149], v[218:221], 0
	v_mfma_f32_16x16x32_bf16 v[14:17], v[134:137], v[226:229], 0
	v_mfma_f32_16x16x32_bf16 v[10:13], v[146:149], v[226:229], 0
	v_mfma_f32_16x16x32_bf16 v[62:65], v[142:145], v[194:197], v[62:65]
	v_mfma_f32_16x16x32_bf16 v[58:61], v[150:153], v[194:197], v[58:61]
	v_mfma_f32_16x16x32_bf16 v[46:49], v[142:145], v[214:217], v[46:49]
	v_mfma_f32_16x16x32_bf16 v[42:45], v[150:153], v[214:217], v[42:45]
	v_mfma_f32_16x16x32_bf16 v[30:33], v[142:145], v[222:225], v[30:33]
	v_mfma_f32_16x16x32_bf16 v[26:29], v[150:153], v[222:225], v[26:29]
	v_mfma_f32_16x16x32_bf16 v[14:17], v[142:145], v[230:233], v[14:17]
	v_mfma_f32_16x16x32_bf16 v[10:13], v[150:153], v[230:233], v[10:13]
	s_setprio 0
	s_setprio 1
	v_mfma_f32_16x16x32_bf16 v[54:57], v[154:157], v[190:193], 0
	v_mfma_f32_16x16x32_bf16 v[50:53], v[182:185], v[190:193], 0
	v_mfma_f32_16x16x32_bf16 v[38:41], v[154:157], v[198:201], 0
	v_mfma_f32_16x16x32_bf16 v[34:37], v[182:185], v[198:201], 0
	v_mfma_f32_16x16x32_bf16 v[22:25], v[154:157], v[218:221], 0
	v_mfma_f32_16x16x32_bf16 v[18:21], v[182:185], v[218:221], 0
	v_mfma_f32_16x16x32_bf16 v[6:9], v[154:157], v[226:229], 0
	v_mfma_f32_16x16x32_bf16 v[2:5], v[182:185], v[226:229], 0
	v_mfma_f32_16x16x32_bf16 v[54:57], v[158:161], v[194:197], v[54:57]
	v_mfma_f32_16x16x32_bf16 v[50:53], v[186:189], v[194:197], v[50:53]
	v_mfma_f32_16x16x32_bf16 v[38:41], v[158:161], v[214:217], v[38:41]
	v_mfma_f32_16x16x32_bf16 v[34:37], v[186:189], v[214:217], v[34:37]
	v_mfma_f32_16x16x32_bf16 v[22:25], v[158:161], v[222:225], v[22:25]
	v_mfma_f32_16x16x32_bf16 v[18:21], v[186:189], v[222:225], v[18:21]
	v_mfma_f32_16x16x32_bf16 v[6:9], v[158:161], v[230:233], v[6:9]
	v_mfma_f32_16x16x32_bf16 v[2:5], v[186:189], v[230:233], v[2:5]
	s_setprio 0
	s_barrier
	s_add_i32 s20, 0, 0x18000
	s_add_i32 s21, 0, 0x1c000
	v_add_u32_e32 v150, s20, v139
	v_add_u32_e32 v186, s21, v139
	ds_read_b128 v[134:137], v150
	ds_read_b128 v[142:145], v150 offset:1024
	ds_read_b128 v[146:149], v150 offset:2048
	ds_read_b128 v[150:153], v150 offset:3072
	ds_read_b128 v[154:157], v186
	ds_read_b128 v[158:161], v186 offset:1024
	ds_read_b128 v[182:185], v186 offset:2048
	ds_read_b128 v[186:189], v186 offset:3072
	ds_read_b128 v[190:193], v141 offset:32768
	ds_read_b128 v[194:197], v141 offset:33792
	ds_read_b128 v[198:201], v141 offset:34816
	ds_read_b128 v[214:217], v141 offset:35840
	ds_read_b128 v[218:221], v141 offset:36864
	ds_read_b128 v[222:225], v141 offset:37888
	ds_read_b128 v[226:229], v141 offset:38912
	ds_read_b128 v[230:233], v141 offset:39936
	s_mov_b32 m0, s91
	v_lshl_add_u64 v[234:235], v[202:203], 0, s[72:73]
	global_load_lds_dwordx4 v[234:235], off
	v_lshl_add_u64 v[234:235], v[202:203], 0, s[74:75]
	s_mov_b32 m0, s96
	s_nop 0
	global_load_lds_dwordx4 v[234:235], off
	s_waitcnt vmcnt(8)
	s_waitcnt lgkmcnt(0)
	s_barrier
	s_setprio 1
	s_waitcnt lgkmcnt(0)
	v_mfma_f32_16x16x32_bf16 v[126:129], v[134:137], v[190:193], v[126:129]
	v_mfma_f32_16x16x32_bf16 v[122:125], v[146:149], v[190:193], v[122:125]
	v_mfma_f32_16x16x32_bf16 v[110:113], v[134:137], v[198:201], v[110:113]
	v_mfma_f32_16x16x32_bf16 v[106:109], v[146:149], v[198:201], v[106:109]
	v_mfma_f32_16x16x32_bf16 v[94:97], v[134:137], v[218:221], v[94:97]
	v_mfma_f32_16x16x32_bf16 v[90:93], v[146:149], v[218:221], v[90:93]
	v_mfma_f32_16x16x32_bf16 v[78:81], v[134:137], v[226:229], v[78:81]
	v_mfma_f32_16x16x32_bf16 v[74:77], v[146:149], v[226:229], v[74:77]
	v_mfma_f32_16x16x32_bf16 v[126:129], v[142:145], v[194:197], v[126:129]
	v_mfma_f32_16x16x32_bf16 v[122:125], v[150:153], v[194:197], v[122:125]
	v_mfma_f32_16x16x32_bf16 v[110:113], v[142:145], v[214:217], v[110:113]
	v_mfma_f32_16x16x32_bf16 v[106:109], v[150:153], v[214:217], v[106:109]
	v_mfma_f32_16x16x32_bf16 v[94:97], v[142:145], v[222:225], v[94:97]
	v_mfma_f32_16x16x32_bf16 v[90:93], v[150:153], v[222:225], v[90:93]
	v_mfma_f32_16x16x32_bf16 v[78:81], v[142:145], v[230:233], v[78:81]
	v_mfma_f32_16x16x32_bf16 v[74:77], v[150:153], v[230:233], v[74:77]
	s_setprio 0
	s_setprio 1
	v_mfma_f32_16x16x32_bf16 v[118:121], v[154:157], v[190:193], v[118:121]
	v_mfma_f32_16x16x32_bf16 v[114:117], v[182:185], v[190:193], v[114:117]
	v_mfma_f32_16x16x32_bf16 v[102:105], v[154:157], v[198:201], v[102:105]
	v_mfma_f32_16x16x32_bf16 v[98:101], v[182:185], v[198:201], v[98:101]
	v_mfma_f32_16x16x32_bf16 v[86:89], v[154:157], v[218:221], v[86:89]
	v_mfma_f32_16x16x32_bf16 v[82:85], v[182:185], v[218:221], v[82:85]
	v_mfma_f32_16x16x32_bf16 v[70:73], v[154:157], v[226:229], v[70:73]
	v_mfma_f32_16x16x32_bf16 v[66:69], v[182:185], v[226:229], v[66:69]
	v_mfma_f32_16x16x32_bf16 v[118:121], v[158:161], v[194:197], v[118:121]
	v_mfma_f32_16x16x32_bf16 v[114:117], v[186:189], v[194:197], v[114:117]
	v_mfma_f32_16x16x32_bf16 v[102:105], v[158:161], v[214:217], v[102:105]
	v_mfma_f32_16x16x32_bf16 v[98:101], v[186:189], v[214:217], v[98:101]
	v_mfma_f32_16x16x32_bf16 v[86:89], v[158:161], v[222:225], v[86:89]
	v_mfma_f32_16x16x32_bf16 v[82:85], v[186:189], v[222:225], v[82:85]
	v_mfma_f32_16x16x32_bf16 v[70:73], v[158:161], v[230:233], v[70:73]
	v_mfma_f32_16x16x32_bf16 v[66:69], v[186:189], v[230:233], v[66:69]
	s_setprio 0
	s_barrier
	ds_read_b128 v[190:193], v141 offset:49152
	ds_read_b128 v[194:197], v141 offset:50176
	ds_read_b128 v[198:201], v141 offset:51200
	ds_read_b128 v[214:217], v141 offset:52224
	ds_read_b128 v[218:221], v141 offset:53248
	ds_read_b128 v[222:225], v141 offset:54272
	ds_read_b128 v[226:229], v141 offset:55296
	ds_read_b128 v[230:233], v141 offset:56320
	s_add_i32 s20, s20, s88
	s_mov_b32 m0, s20
	v_lshl_add_u64 v[234:235], v[162:163], 0, s[34:35]
	global_load_lds_dwordx4 v[234:235], off
	v_lshl_add_u64 v[234:235], v[162:163], 0, s[80:81]
	s_add_i32 m0, s20, 0x2000
	s_add_i32 s20, s21, s88
	global_load_lds_dwordx4 v[234:235], off
	v_lshl_add_u64 v[234:235], v[162:163], 0, s[38:39]
	s_mov_b32 m0, s20
	v_lshl_add_u64 v[162:163], v[162:163], 0, s[86:87]
	global_load_lds_dwordx4 v[234:235], off
	s_add_i32 m0, s20, 0x2000
	s_nop 0
	global_load_lds_dwordx4 v[162:163], off
	v_lshl_add_u64 v[162:163], v[202:203], 0, s[34:35]
	s_mov_b32 m0, s97
	s_nop 0
	global_load_lds_dwordx4 v[162:163], off
	v_lshl_add_u64 v[162:163], v[202:203], 0, s[80:81]
	s_mov_b32 m0, s58
	s_nop 0
	global_load_lds_dwordx4 v[162:163], off
	s_waitcnt vmcnt(8)
	s_waitcnt lgkmcnt(0)
	s_barrier
	s_setprio 1
	s_waitcnt lgkmcnt(0)
	v_mfma_f32_16x16x32_bf16 v[62:65], v[134:137], v[190:193], v[62:65]
	v_mfma_f32_16x16x32_bf16 v[58:61], v[146:149], v[190:193], v[58:61]
	v_mfma_f32_16x16x32_bf16 v[46:49], v[134:137], v[198:201], v[46:49]
	v_mfma_f32_16x16x32_bf16 v[42:45], v[146:149], v[198:201], v[42:45]
	v_mfma_f32_16x16x32_bf16 v[30:33], v[134:137], v[218:221], v[30:33]
	v_mfma_f32_16x16x32_bf16 v[26:29], v[146:149], v[218:221], v[26:29]
	v_mfma_f32_16x16x32_bf16 v[14:17], v[134:137], v[226:229], v[14:17]
	v_mfma_f32_16x16x32_bf16 v[10:13], v[146:149], v[226:229], v[10:13]
	v_mfma_f32_16x16x32_bf16 v[62:65], v[142:145], v[194:197], v[62:65]
	v_mfma_f32_16x16x32_bf16 v[58:61], v[150:153], v[194:197], v[58:61]
	v_mfma_f32_16x16x32_bf16 v[46:49], v[142:145], v[214:217], v[46:49]
	v_mfma_f32_16x16x32_bf16 v[42:45], v[150:153], v[214:217], v[42:45]
	v_mfma_f32_16x16x32_bf16 v[30:33], v[142:145], v[222:225], v[30:33]
	v_mfma_f32_16x16x32_bf16 v[26:29], v[150:153], v[222:225], v[26:29]
	v_mfma_f32_16x16x32_bf16 v[14:17], v[142:145], v[230:233], v[14:17]
	v_mfma_f32_16x16x32_bf16 v[10:13], v[150:153], v[230:233], v[10:13]
	s_add_i32 s84, s84, 2
	s_add_u32 s6, s6, 0x100
	s_addc_u32 s7, s7, 0
	s_add_u32 s49, s49, 0x100
	s_addc_u32 s51, s51, 0
	s_setprio 0
	s_setprio 1
	v_mfma_f32_16x16x32_bf16 v[54:57], v[154:157], v[190:193], v[54:57]
	v_mfma_f32_16x16x32_bf16 v[50:53], v[182:185], v[190:193], v[50:53]
	v_mfma_f32_16x16x32_bf16 v[38:41], v[154:157], v[198:201], v[38:41]
	v_mfma_f32_16x16x32_bf16 v[34:37], v[182:185], v[198:201], v[34:37]
	v_mfma_f32_16x16x32_bf16 v[22:25], v[154:157], v[218:221], v[22:25]
	v_mfma_f32_16x16x32_bf16 v[18:21], v[182:185], v[218:221], v[18:21]
	v_mfma_f32_16x16x32_bf16 v[6:9], v[154:157], v[226:229], v[6:9]
	v_mfma_f32_16x16x32_bf16 v[2:5], v[182:185], v[226:229], v[2:5]
	v_mfma_f32_16x16x32_bf16 v[54:57], v[158:161], v[194:197], v[54:57]
	v_mfma_f32_16x16x32_bf16 v[50:53], v[186:189], v[194:197], v[50:53]
	v_mfma_f32_16x16x32_bf16 v[38:41], v[158:161], v[214:217], v[38:41]
	v_mfma_f32_16x16x32_bf16 v[34:37], v[186:189], v[214:217], v[34:37]
	v_mfma_f32_16x16x32_bf16 v[22:25], v[158:161], v[222:225], v[22:25]
	v_mfma_f32_16x16x32_bf16 v[18:21], v[186:189], v[222:225], v[18:21]
	v_mfma_f32_16x16x32_bf16 v[6:9], v[158:161], v[230:233], v[6:9]
	v_mfma_f32_16x16x32_bf16 v[2:5], v[186:189], v[230:233], v[2:5]
	s_setprio 0
	s_barrier
	s_branch .LBB0_604
	.p2alignl 6, 3212836864
.LBB0_604:
	s_add_i32 s22, 0, 0x10000
	s_add_i32 s23, 0, 0x14000
	v_add_u32_e32 v150, s22, v139
	v_add_u32_e32 v162, s23, v139
	ds_read_b128 v[134:137], v150
	ds_read_b128 v[142:145], v150 offset:1024
	ds_read_b128 v[146:149], v150 offset:2048
	ds_read_b128 v[150:153], v150 offset:3072
	ds_read_b128 v[154:157], v162
	ds_read_b128 v[158:161], v162 offset:1024
	ds_read_b128 v[182:185], v162 offset:2048
	ds_read_b128 v[186:189], v162 offset:3072
	ds_read_b128 v[190:193], v141
	ds_read_b128 v[194:197], v141 offset:1024
	ds_read_b128 v[198:201], v141 offset:2048
	ds_read_b128 v[214:217], v141 offset:3072
	ds_read_b128 v[218:221], v141 offset:4096
	ds_read_b128 v[222:225], v141 offset:5120
	ds_read_b128 v[226:229], v141 offset:6144
	ds_read_b128 v[230:233], v141 offset:7168
	s_add_u32 s20, s6, 0xfffe0080
	s_addc_u32 s21, s7, -1
	s_cmp_eq_u32 s84, 4
	s_cselect_b32 s69, s42, s21
	s_cselect_b32 s68, s43, s20
	s_cselect_b32 s21, s46, s51
	s_cselect_b32 s20, s47, s49
	s_add_i32 m0, s89, 0xc000
	v_lshl_add_u64 v[162:163], s[6:7], 0, v[132:133]
	global_load_lds_dwordx4 v[162:163], off
	v_lshl_add_u64 v[162:163], v[162:163], 0, s[64:65]
	s_add_i32 m0, s89, 0xe000
	s_nop 0
	global_load_lds_dwordx4 v[162:163], off
	s_waitcnt vmcnt(8)
	s_waitcnt lgkmcnt(0)
	s_barrier
	s_setprio 1
	s_waitcnt lgkmcnt(0)
	v_mfma_f32_16x16x32_bf16 v[126:129], v[134:137], v[190:193], v[126:129]
	v_mfma_f32_16x16x32_bf16 v[122:125], v[146:149], v[190:193], v[122:125]
	v_mfma_f32_16x16x32_bf16 v[110:113], v[134:137], v[198:201], v[110:113]
	v_mfma_f32_16x16x32_bf16 v[106:109], v[146:149], v[198:201], v[106:109]
	v_mfma_f32_16x16x32_bf16 v[94:97], v[134:137], v[218:221], v[94:97]
	v_mfma_f32_16x16x32_bf16 v[90:93], v[146:149], v[218:221], v[90:93]
	v_mfma_f32_16x16x32_bf16 v[78:81], v[134:137], v[226:229], v[78:81]
	v_mfma_f32_16x16x32_bf16 v[74:77], v[146:149], v[226:229], v[74:77]
	v_mfma_f32_16x16x32_bf16 v[126:129], v[142:145], v[194:197], v[126:129]
	v_mfma_f32_16x16x32_bf16 v[122:125], v[150:153], v[194:197], v[122:125]
	v_mfma_f32_16x16x32_bf16 v[110:113], v[142:145], v[214:217], v[110:113]
	v_mfma_f32_16x16x32_bf16 v[106:109], v[150:153], v[214:217], v[106:109]
	v_mfma_f32_16x16x32_bf16 v[94:97], v[142:145], v[222:225], v[94:97]
	v_mfma_f32_16x16x32_bf16 v[90:93], v[150:153], v[222:225], v[90:93]
	v_mfma_f32_16x16x32_bf16 v[78:81], v[142:145], v[230:233], v[78:81]
	v_mfma_f32_16x16x32_bf16 v[74:77], v[150:153], v[230:233], v[74:77]
	s_setprio 0
	s_setprio 1
	v_mfma_f32_16x16x32_bf16 v[118:121], v[154:157], v[190:193], v[118:121]
	v_mfma_f32_16x16x32_bf16 v[114:117], v[182:185], v[190:193], v[114:117]
	v_mfma_f32_16x16x32_bf16 v[102:105], v[154:157], v[198:201], v[102:105]
	v_mfma_f32_16x16x32_bf16 v[98:101], v[182:185], v[198:201], v[98:101]
	v_mfma_f32_16x16x32_bf16 v[86:89], v[154:157], v[218:221], v[86:89]
	v_mfma_f32_16x16x32_bf16 v[82:85], v[182:185], v[218:221], v[82:85]
	v_mfma_f32_16x16x32_bf16 v[70:73], v[154:157], v[226:229], v[70:73]
	v_mfma_f32_16x16x32_bf16 v[66:69], v[182:185], v[226:229], v[66:69]
	v_mfma_f32_16x16x32_bf16 v[118:121], v[158:161], v[194:197], v[118:121]
	v_mfma_f32_16x16x32_bf16 v[114:117], v[186:189], v[194:197], v[114:117]
	v_mfma_f32_16x16x32_bf16 v[102:105], v[158:161], v[214:217], v[102:105]
	v_mfma_f32_16x16x32_bf16 v[98:101], v[186:189], v[214:217], v[98:101]
	v_mfma_f32_16x16x32_bf16 v[86:89], v[158:161], v[222:225], v[86:89]
	v_mfma_f32_16x16x32_bf16 v[82:85], v[186:189], v[222:225], v[82:85]
	v_mfma_f32_16x16x32_bf16 v[70:73], v[158:161], v[230:233], v[70:73]
	v_mfma_f32_16x16x32_bf16 v[66:69], v[186:189], v[230:233], v[66:69]
	s_setprio 0
	s_barrier
	ds_read_b128 v[190:193], v141 offset:16384
	ds_read_b128 v[194:197], v141 offset:17408
	ds_read_b128 v[198:201], v141 offset:18432
	ds_read_b128 v[214:217], v141 offset:19456
	ds_read_b128 v[218:221], v141 offset:20480
	ds_read_b128 v[222:225], v141 offset:21504
	ds_read_b128 v[226:229], v141 offset:22528
	ds_read_b128 v[230:233], v141 offset:23552
	v_lshl_add_u64 v[162:163], s[20:21], 0, v[0:1]
	s_add_i32 s20, s22, s88
	s_mov_b32 m0, s20
	s_nop 0
	s_nop 0
	global_load_lds_dwordx4 v[162:163], off
	v_lshl_add_u64 v[202:203], v[162:163], 0, s[64:65]
	s_add_i32 m0, s20, 0x2000
	s_add_i32 s20, s23, s88
	global_load_lds_dwordx4 v[202:203], off
	v_lshl_add_u64 v[202:203], v[162:163], 0, s[72:73]
	s_mov_b32 m0, s20
	s_nop 0
	global_load_lds_dwordx4 v[202:203], off
	v_lshl_add_u64 v[202:203], v[162:163], 0, s[74:75]
	s_add_i32 m0, s20, 0x2000
	s_nop 0
	global_load_lds_dwordx4 v[202:203], off
	v_lshl_add_u64 v[202:203], s[68:69], 0, v[130:131]
	s_mov_b32 m0, s89
	v_lshl_add_u64 v[234:235], v[202:203], 0, s[64:65]
	global_load_lds_dwordx4 v[202:203], off
	s_mov_b32 m0, s90
	s_nop 0
	global_load_lds_dwordx4 v[234:235], off
	s_waitcnt vmcnt(8)
	s_waitcnt lgkmcnt(0)
	s_barrier
	s_setprio 1
	s_waitcnt lgkmcnt(0)
	v_mfma_f32_16x16x32_bf16 v[62:65], v[134:137], v[190:193], v[62:65]
	v_mfma_f32_16x16x32_bf16 v[58:61], v[146:149], v[190:193], v[58:61]
	v_mfma_f32_16x16x32_bf16 v[46:49], v[134:137], v[198:201], v[46:49]
	v_mfma_f32_16x16x32_bf16 v[42:45], v[146:149], v[198:201], v[42:45]
	v_mfma_f32_16x16x32_bf16 v[30:33], v[134:137], v[218:221], v[30:33]
	v_mfma_f32_16x16x32_bf16 v[26:29], v[146:149], v[218:221], v[26:29]
	v_mfma_f32_16x16x32_bf16 v[14:17], v[134:137], v[226:229], v[14:17]
	v_mfma_f32_16x16x32_bf16 v[10:13], v[146:149], v[226:229], v[10:13]
	v_mfma_f32_16x16x32_bf16 v[62:65], v[142:145], v[194:197], v[62:65]
	v_mfma_f32_16x16x32_bf16 v[58:61], v[150:153], v[194:197], v[58:61]
	v_mfma_f32_16x16x32_bf16 v[46:49], v[142:145], v[214:217], v[46:49]
	v_mfma_f32_16x16x32_bf16 v[42:45], v[150:153], v[214:217], v[42:45]
	v_mfma_f32_16x16x32_bf16 v[30:33], v[142:145], v[222:225], v[30:33]
	v_mfma_f32_16x16x32_bf16 v[26:29], v[150:153], v[222:225], v[26:29]
	v_mfma_f32_16x16x32_bf16 v[14:17], v[142:145], v[230:233], v[14:17]
	v_mfma_f32_16x16x32_bf16 v[10:13], v[150:153], v[230:233], v[10:13]
	s_setprio 0
	s_setprio 1
	v_mfma_f32_16x16x32_bf16 v[54:57], v[154:157], v[190:193], v[54:57]
	v_mfma_f32_16x16x32_bf16 v[50:53], v[182:185], v[190:193], v[50:53]
	v_mfma_f32_16x16x32_bf16 v[38:41], v[154:157], v[198:201], v[38:41]
	v_mfma_f32_16x16x32_bf16 v[34:37], v[182:185], v[198:201], v[34:37]
	v_mfma_f32_16x16x32_bf16 v[22:25], v[154:157], v[218:221], v[22:25]
	v_mfma_f32_16x16x32_bf16 v[18:21], v[182:185], v[218:221], v[18:21]
	v_mfma_f32_16x16x32_bf16 v[6:9], v[154:157], v[226:229], v[6:9]
	v_mfma_f32_16x16x32_bf16 v[2:5], v[182:185], v[226:229], v[2:5]
	v_mfma_f32_16x16x32_bf16 v[54:57], v[158:161], v[194:197], v[54:57]
	v_mfma_f32_16x16x32_bf16 v[50:53], v[186:189], v[194:197], v[50:53]
	v_mfma_f32_16x16x32_bf16 v[38:41], v[158:161], v[214:217], v[38:41]
	v_mfma_f32_16x16x32_bf16 v[34:37], v[186:189], v[214:217], v[34:37]
	v_mfma_f32_16x16x32_bf16 v[22:25], v[158:161], v[222:225], v[22:25]
	v_mfma_f32_16x16x32_bf16 v[18:21], v[186:189], v[222:225], v[18:21]
	v_mfma_f32_16x16x32_bf16 v[6:9], v[158:161], v[230:233], v[6:9]
	v_mfma_f32_16x16x32_bf16 v[2:5], v[186:189], v[230:233], v[2:5]
	s_setprio 0
	s_barrier
	s_add_i32 s20, 0, 0x18000
	s_add_i32 s21, 0, 0x1c000
	v_add_u32_e32 v150, s20, v139
	v_add_u32_e32 v186, s21, v139
	ds_read_b128 v[134:137], v150
	ds_read_b128 v[142:145], v150 offset:1024
	ds_read_b128 v[146:149], v150 offset:2048
	ds_read_b128 v[150:153], v150 offset:3072
	ds_read_b128 v[154:157], v186
	ds_read_b128 v[158:161], v186 offset:1024
	ds_read_b128 v[182:185], v186 offset:2048
	ds_read_b128 v[186:189], v186 offset:3072
	ds_read_b128 v[190:193], v141 offset:32768
	ds_read_b128 v[194:197], v141 offset:33792
	ds_read_b128 v[198:201], v141 offset:34816
	ds_read_b128 v[214:217], v141 offset:35840
	ds_read_b128 v[218:221], v141 offset:36864
	ds_read_b128 v[222:225], v141 offset:37888
	ds_read_b128 v[226:229], v141 offset:38912
	ds_read_b128 v[230:233], v141 offset:39936
	s_mov_b32 m0, s91
	v_lshl_add_u64 v[234:235], v[202:203], 0, s[72:73]
	global_load_lds_dwordx4 v[234:235], off
	v_lshl_add_u64 v[234:235], v[202:203], 0, s[74:75]
	s_mov_b32 m0, s96
	s_nop 0
	global_load_lds_dwordx4 v[234:235], off
	s_waitcnt vmcnt(8)
	s_waitcnt lgkmcnt(0)
	s_barrier
	s_setprio 1
	s_waitcnt lgkmcnt(0)
	v_mfma_f32_16x16x32_bf16 v[126:129], v[134:137], v[190:193], v[126:129]
	v_mfma_f32_16x16x32_bf16 v[122:125], v[146:149], v[190:193], v[122:125]
	v_mfma_f32_16x16x32_bf16 v[110:113], v[134:137], v[198:201], v[110:113]
	v_mfma_f32_16x16x32_bf16 v[106:109], v[146:149], v[198:201], v[106:109]
	v_mfma_f32_16x16x32_bf16 v[94:97], v[134:137], v[218:221], v[94:97]
	v_mfma_f32_16x16x32_bf16 v[90:93], v[146:149], v[218:221], v[90:93]
	v_mfma_f32_16x16x32_bf16 v[78:81], v[134:137], v[226:229], v[78:81]
	v_mfma_f32_16x16x32_bf16 v[74:77], v[146:149], v[226:229], v[74:77]
	v_mfma_f32_16x16x32_bf16 v[126:129], v[142:145], v[194:197], v[126:129]
	v_mfma_f32_16x16x32_bf16 v[122:125], v[150:153], v[194:197], v[122:125]
	v_mfma_f32_16x16x32_bf16 v[110:113], v[142:145], v[214:217], v[110:113]
	v_mfma_f32_16x16x32_bf16 v[106:109], v[150:153], v[214:217], v[106:109]
	v_mfma_f32_16x16x32_bf16 v[94:97], v[142:145], v[222:225], v[94:97]
	v_mfma_f32_16x16x32_bf16 v[90:93], v[150:153], v[222:225], v[90:93]
	v_mfma_f32_16x16x32_bf16 v[78:81], v[142:145], v[230:233], v[78:81]
	v_mfma_f32_16x16x32_bf16 v[74:77], v[150:153], v[230:233], v[74:77]
	s_setprio 0
	s_setprio 1
	v_mfma_f32_16x16x32_bf16 v[118:121], v[154:157], v[190:193], v[118:121]
	v_mfma_f32_16x16x32_bf16 v[114:117], v[182:185], v[190:193], v[114:117]
	v_mfma_f32_16x16x32_bf16 v[102:105], v[154:157], v[198:201], v[102:105]
	v_mfma_f32_16x16x32_bf16 v[98:101], v[182:185], v[198:201], v[98:101]
	v_mfma_f32_16x16x32_bf16 v[86:89], v[154:157], v[218:221], v[86:89]
	v_mfma_f32_16x16x32_bf16 v[82:85], v[182:185], v[218:221], v[82:85]
	v_mfma_f32_16x16x32_bf16 v[70:73], v[154:157], v[226:229], v[70:73]
	v_mfma_f32_16x16x32_bf16 v[66:69], v[182:185], v[226:229], v[66:69]
	v_mfma_f32_16x16x32_bf16 v[118:121], v[158:161], v[194:197], v[118:121]
	v_mfma_f32_16x16x32_bf16 v[114:117], v[186:189], v[194:197], v[114:117]
	v_mfma_f32_16x16x32_bf16 v[102:105], v[158:161], v[214:217], v[102:105]
	v_mfma_f32_16x16x32_bf16 v[98:101], v[186:189], v[214:217], v[98:101]
	v_mfma_f32_16x16x32_bf16 v[86:89], v[158:161], v[222:225], v[86:89]
	v_mfma_f32_16x16x32_bf16 v[82:85], v[186:189], v[222:225], v[82:85]
	v_mfma_f32_16x16x32_bf16 v[70:73], v[158:161], v[230:233], v[70:73]
	v_mfma_f32_16x16x32_bf16 v[66:69], v[186:189], v[230:233], v[66:69]
	s_setprio 0
	s_barrier
	ds_read_b128 v[190:193], v141 offset:49152
	ds_read_b128 v[194:197], v141 offset:50176
	ds_read_b128 v[198:201], v141 offset:51200
	ds_read_b128 v[214:217], v141 offset:52224
	ds_read_b128 v[218:221], v141 offset:53248
	ds_read_b128 v[222:225], v141 offset:54272
	ds_read_b128 v[226:229], v141 offset:55296
	ds_read_b128 v[230:233], v141 offset:56320
	s_add_i32 s20, s20, s88
	s_mov_b32 m0, s20
	v_lshl_add_u64 v[234:235], v[162:163], 0, s[34:35]
	global_load_lds_dwordx4 v[234:235], off
	v_lshl_add_u64 v[234:235], v[162:163], 0, s[80:81]
	s_add_i32 m0, s20, 0x2000
	s_add_i32 s20, s21, s88
	global_load_lds_dwordx4 v[234:235], off
	v_lshl_add_u64 v[234:235], v[162:163], 0, s[38:39]
	s_mov_b32 m0, s20
	v_lshl_add_u64 v[162:163], v[162:163], 0, s[86:87]
	global_load_lds_dwordx4 v[234:235], off
	s_add_i32 m0, s20, 0x2000
	s_nop 0
	global_load_lds_dwordx4 v[162:163], off
	v_lshl_add_u64 v[162:163], v[202:203], 0, s[34:35]
	s_mov_b32 m0, s97
	s_nop 0
	global_load_lds_dwordx4 v[162:163], off
	v_lshl_add_u64 v[162:163], v[202:203], 0, s[80:81]
	s_mov_b32 m0, s58
	s_nop 0
	global_load_lds_dwordx4 v[162:163], off
	s_waitcnt vmcnt(8)
	s_waitcnt lgkmcnt(0)
	s_barrier
	s_setprio 1
	s_waitcnt lgkmcnt(0)
	v_mfma_f32_16x16x32_bf16 v[62:65], v[134:137], v[190:193], v[62:65]
	v_mfma_f32_16x16x32_bf16 v[58:61], v[146:149], v[190:193], v[58:61]
	v_mfma_f32_16x16x32_bf16 v[46:49], v[134:137], v[198:201], v[46:49]
	v_mfma_f32_16x16x32_bf16 v[42:45], v[146:149], v[198:201], v[42:45]
	v_mfma_f32_16x16x32_bf16 v[30:33], v[134:137], v[218:221], v[30:33]
	v_mfma_f32_16x16x32_bf16 v[26:29], v[146:149], v[218:221], v[26:29]
	v_mfma_f32_16x16x32_bf16 v[14:17], v[134:137], v[226:229], v[14:17]
	v_mfma_f32_16x16x32_bf16 v[10:13], v[146:149], v[226:229], v[10:13]
	v_mfma_f32_16x16x32_bf16 v[62:65], v[142:145], v[194:197], v[62:65]
	v_mfma_f32_16x16x32_bf16 v[58:61], v[150:153], v[194:197], v[58:61]
	v_mfma_f32_16x16x32_bf16 v[46:49], v[142:145], v[214:217], v[46:49]
	v_mfma_f32_16x16x32_bf16 v[42:45], v[150:153], v[214:217], v[42:45]
	v_mfma_f32_16x16x32_bf16 v[30:33], v[142:145], v[222:225], v[30:33]
	v_mfma_f32_16x16x32_bf16 v[26:29], v[150:153], v[222:225], v[26:29]
	v_mfma_f32_16x16x32_bf16 v[14:17], v[142:145], v[230:233], v[14:17]
	v_mfma_f32_16x16x32_bf16 v[10:13], v[150:153], v[230:233], v[10:13]
	s_add_i32 s84, s84, 2
	s_add_u32 s6, s6, 0x100
	s_addc_u32 s7, s7, 0
	s_add_u32 s49, s49, 0x100
	s_addc_u32 s51, s51, 0
	s_setprio 0
	s_setprio 1
	v_mfma_f32_16x16x32_bf16 v[54:57], v[154:157], v[190:193], v[54:57]
	v_mfma_f32_16x16x32_bf16 v[50:53], v[182:185], v[190:193], v[50:53]
	v_mfma_f32_16x16x32_bf16 v[38:41], v[154:157], v[198:201], v[38:41]
	v_mfma_f32_16x16x32_bf16 v[34:37], v[182:185], v[198:201], v[34:37]
	v_mfma_f32_16x16x32_bf16 v[22:25], v[154:157], v[218:221], v[22:25]
	v_mfma_f32_16x16x32_bf16 v[18:21], v[182:185], v[218:221], v[18:21]
	v_mfma_f32_16x16x32_bf16 v[6:9], v[154:157], v[226:229], v[6:9]
	v_mfma_f32_16x16x32_bf16 v[2:5], v[182:185], v[226:229], v[2:5]
	v_mfma_f32_16x16x32_bf16 v[54:57], v[158:161], v[194:197], v[54:57]
	v_mfma_f32_16x16x32_bf16 v[50:53], v[186:189], v[194:197], v[50:53]
	v_mfma_f32_16x16x32_bf16 v[38:41], v[158:161], v[214:217], v[38:41]
	v_mfma_f32_16x16x32_bf16 v[34:37], v[186:189], v[214:217], v[34:37]
	v_mfma_f32_16x16x32_bf16 v[22:25], v[158:161], v[222:225], v[22:25]
	v_mfma_f32_16x16x32_bf16 v[18:21], v[186:189], v[222:225], v[18:21]
	v_mfma_f32_16x16x32_bf16 v[6:9], v[158:161], v[230:233], v[6:9]
	v_mfma_f32_16x16x32_bf16 v[2:5], v[186:189], v[230:233], v[2:5]
	s_setprio 0
	s_barrier
	s_cmp_gt_u32 s84, 5
	s_cbranch_scc0 .LBB0_604
	s_and_b64 vcc, exec, s[52:53]
	s_cbranch_vccz .LBB0_607
	s_barrier

.Lmid1_778:
	s_add_i32 s22, 0, 0x10000
	s_add_i32 s23, 0, 0x14000
	s_add_u32 s20, s76, 0xfffc0080
	s_addc_u32 s21, s77, -1
	s_cmp_eq_u32 vcc_hi, 12
	s_cselect_b32 s79, s61, s21
	s_cselect_b32 s78, s85, s20
	s_cselect_b32 s21, s59, vcc_lo
	s_cselect_b32 s20, s86, s87
	s_add_i32 m0, s43, 0xc000
	v_lshl_add_u64 v[202:203], s[76:77], 0, v[182:183]
	global_load_lds_dwordx4 v[202:203], off
	v_lshl_add_u64 v[202:203], v[202:203], 0, s[72:73]
	s_add_i32 m0, s43, 0xe000
	s_nop 0
	global_load_lds_dwordx4 v[202:203], off
	s_waitcnt vmcnt(8)
	s_waitcnt lgkmcnt(0)
	s_barrier
	s_setprio 1
	s_waitcnt lgkmcnt(0)
	v_mfma_f32_16x16x32_bf16 v[126:129], v[130:133], v[184:187], 0
	v_mfma_f32_16x16x32_bf16 v[122:125], v[138:141], v[184:187], 0
	v_mfma_f32_16x16x32_bf16 v[110:113], v[130:133], v[198:201], 0
	v_mfma_f32_16x16x32_bf16 v[106:109], v[138:141], v[198:201], 0
	v_mfma_f32_16x16x32_bf16 v[94:97], v[130:133], v[218:221], 0
	v_mfma_f32_16x16x32_bf16 v[90:93], v[138:141], v[218:221], 0
	v_mfma_f32_16x16x32_bf16 v[78:81], v[130:133], v[226:229], 0
	v_mfma_f32_16x16x32_bf16 v[74:77], v[138:141], v[226:229], 0
	v_mfma_f32_16x16x32_bf16 v[126:129], v[134:137], v[188:191], v[126:129]
	v_mfma_f32_16x16x32_bf16 v[122:125], v[142:145], v[188:191], v[122:125]
	v_mfma_f32_16x16x32_bf16 v[110:113], v[134:137], v[214:217], v[110:113]
	v_mfma_f32_16x16x32_bf16 v[106:109], v[142:145], v[214:217], v[106:109]
	v_mfma_f32_16x16x32_bf16 v[94:97], v[134:137], v[222:225], v[94:97]
	v_mfma_f32_16x16x32_bf16 v[90:93], v[142:145], v[222:225], v[90:93]
	v_mfma_f32_16x16x32_bf16 v[78:81], v[134:137], v[230:233], v[78:81]
	v_mfma_f32_16x16x32_bf16 v[74:77], v[142:145], v[230:233], v[74:77]
	s_setprio 0
	s_setprio 1
	v_mfma_f32_16x16x32_bf16 v[118:121], v[146:149], v[184:187], 0
	v_mfma_f32_16x16x32_bf16 v[114:117], v[154:157], v[184:187], 0
	v_mfma_f32_16x16x32_bf16 v[102:105], v[146:149], v[198:201], 0
	v_mfma_f32_16x16x32_bf16 v[98:101], v[154:157], v[198:201], 0
	v_mfma_f32_16x16x32_bf16 v[86:89], v[146:149], v[218:221], 0
	v_mfma_f32_16x16x32_bf16 v[82:85], v[154:157], v[218:221], 0
	v_mfma_f32_16x16x32_bf16 v[70:73], v[146:149], v[226:229], 0
	v_mfma_f32_16x16x32_bf16 v[66:69], v[154:157], v[226:229], 0
	v_mfma_f32_16x16x32_bf16 v[118:121], v[150:153], v[188:191], v[118:121]
	v_mfma_f32_16x16x32_bf16 v[114:117], v[158:161], v[188:191], v[114:117]
	v_mfma_f32_16x16x32_bf16 v[102:105], v[150:153], v[214:217], v[102:105]
	v_mfma_f32_16x16x32_bf16 v[98:101], v[158:161], v[214:217], v[98:101]
	v_mfma_f32_16x16x32_bf16 v[86:89], v[150:153], v[222:225], v[86:89]
	v_mfma_f32_16x16x32_bf16 v[82:85], v[158:161], v[222:225], v[82:85]
	v_mfma_f32_16x16x32_bf16 v[70:73], v[150:153], v[230:233], v[70:73]
	v_mfma_f32_16x16x32_bf16 v[66:69], v[158:161], v[230:233], v[66:69]
	s_setprio 0
	s_barrier
	ds_read_b128 v[184:187], v196 offset:16384
	ds_read_b128 v[188:191], v196 offset:17408
	ds_read_b128 v[198:201], v196 offset:18432
	ds_read_b128 v[214:217], v196 offset:19456
	ds_read_b128 v[218:221], v196 offset:20480
	ds_read_b128 v[222:225], v196 offset:21504
	ds_read_b128 v[226:229], v196 offset:22528
	ds_read_b128 v[230:233], v196 offset:23552
	v_lshl_add_u64 v[202:203], s[20:21], 0, v[0:1]
	s_add_i32 s20, s22, s14
	s_mov_b32 m0, s20
	s_nop 0
	s_nop 0
	global_load_lds_dwordx4 v[202:203], off
	v_lshl_add_u64 v[234:235], v[202:203], 0, s[72:73]
	s_add_i32 m0, s20, 0x2000
	s_add_i32 s20, s23, s14
	global_load_lds_dwordx4 v[234:235], off
	v_lshl_add_u64 v[234:235], v[202:203], 0, s[28:29]
	s_mov_b32 m0, s20
	s_nop 0
	global_load_lds_dwordx4 v[234:235], off
	v_lshl_add_u64 v[234:235], v[202:203], 0, s[82:83]
	s_add_i32 m0, s20, 0x2000
	s_nop 0
	global_load_lds_dwordx4 v[234:235], off
	v_lshl_add_u64 v[234:235], s[78:79], 0, v[162:163]
	s_mov_b32 m0, s43
	v_lshl_add_u64 v[236:237], v[234:235], 0, s[72:73]
	global_load_lds_dwordx4 v[234:235], off
	s_mov_b32 m0, s46
	s_nop 0
	global_load_lds_dwordx4 v[236:237], off
	s_waitcnt vmcnt(8)
	s_waitcnt lgkmcnt(0)
	s_barrier
	s_setprio 1
	s_waitcnt lgkmcnt(0)
	v_mfma_f32_16x16x32_bf16 v[62:65], v[130:133], v[184:187], 0
	v_mfma_f32_16x16x32_bf16 v[58:61], v[138:141], v[184:187], 0
	v_mfma_f32_16x16x32_bf16 v[46:49], v[130:133], v[198:201], 0
	v_mfma_f32_16x16x32_bf16 v[42:45], v[138:141], v[198:201], 0
	v_mfma_f32_16x16x32_bf16 v[30:33], v[130:133], v[218:221], 0
	v_mfma_f32_16x16x32_bf16 v[26:29], v[138:141], v[218:221], 0
	v_mfma_f32_16x16x32_bf16 v[14:17], v[130:133], v[226:229], 0
	v_mfma_f32_16x16x32_bf16 v[10:13], v[138:141], v[226:229], 0
	v_mfma_f32_16x16x32_bf16 v[62:65], v[134:137], v[188:191], v[62:65]
	v_mfma_f32_16x16x32_bf16 v[58:61], v[142:145], v[188:191], v[58:61]
	v_mfma_f32_16x16x32_bf16 v[46:49], v[134:137], v[214:217], v[46:49]
	v_mfma_f32_16x16x32_bf16 v[42:45], v[142:145], v[214:217], v[42:45]
	v_mfma_f32_16x16x32_bf16 v[30:33], v[134:137], v[222:225], v[30:33]
	v_mfma_f32_16x16x32_bf16 v[26:29], v[142:145], v[222:225], v[26:29]
	v_mfma_f32_16x16x32_bf16 v[14:17], v[134:137], v[230:233], v[14:17]
	v_mfma_f32_16x16x32_bf16 v[10:13], v[142:145], v[230:233], v[10:13]
	s_setprio 0
	s_setprio 1
	v_mfma_f32_16x16x32_bf16 v[54:57], v[146:149], v[184:187], 0
	v_mfma_f32_16x16x32_bf16 v[50:53], v[154:157], v[184:187], 0
	v_mfma_f32_16x16x32_bf16 v[38:41], v[146:149], v[198:201], 0
	v_mfma_f32_16x16x32_bf16 v[34:37], v[154:157], v[198:201], 0
	v_mfma_f32_16x16x32_bf16 v[22:25], v[146:149], v[218:221], 0
	v_mfma_f32_16x16x32_bf16 v[18:21], v[154:157], v[218:221], 0
	v_mfma_f32_16x16x32_bf16 v[6:9], v[146:149], v[226:229], 0
	v_mfma_f32_16x16x32_bf16 v[2:5], v[154:157], v[226:229], 0
	v_mfma_f32_16x16x32_bf16 v[54:57], v[150:153], v[188:191], v[54:57]
	v_mfma_f32_16x16x32_bf16 v[50:53], v[158:161], v[188:191], v[50:53]
	v_mfma_f32_16x16x32_bf16 v[38:41], v[150:153], v[214:217], v[38:41]
	v_mfma_f32_16x16x32_bf16 v[34:37], v[158:161], v[214:217], v[34:37]
	v_mfma_f32_16x16x32_bf16 v[22:25], v[150:153], v[222:225], v[22:25]
	v_mfma_f32_16x16x32_bf16 v[18:21], v[158:161], v[222:225], v[18:21]
	v_mfma_f32_16x16x32_bf16 v[6:9], v[150:153], v[230:233], v[6:9]
	v_mfma_f32_16x16x32_bf16 v[2:5], v[158:161], v[230:233], v[2:5]
	s_setprio 0
	s_barrier
	s_add_i32 s20, 0, 0x18000
	s_add_i32 s21, 0, 0x1c000
	v_add_u32_e32 v142, s20, v193
	v_add_u32_e32 v158, s21, v193
	ds_read_b128 v[130:133], v142
	ds_read_b128 v[134:137], v142 offset:1024
	ds_read_b128 v[138:141], v142 offset:2048
	ds_read_b128 v[142:145], v142 offset:3072
	ds_read_b128 v[146:149], v158
	ds_read_b128 v[150:153], v158 offset:1024
	ds_read_b128 v[154:157], v158 offset:2048
	ds_read_b128 v[158:161], v158 offset:3072
	ds_read_b128 v[184:187], v196 offset:32768
	ds_read_b128 v[188:191], v196 offset:33792
	ds_read_b128 v[198:201], v196 offset:34816
	ds_read_b128 v[214:217], v196 offset:35840
	ds_read_b128 v[218:221], v196 offset:36864
	ds_read_b128 v[222:225], v196 offset:37888
	ds_read_b128 v[226:229], v196 offset:38912
	ds_read_b128 v[230:233], v196 offset:39936
	s_mov_b32 m0, s47
	v_lshl_add_u64 v[236:237], v[234:235], 0, s[28:29]
	global_load_lds_dwordx4 v[236:237], off
	v_lshl_add_u64 v[236:237], v[234:235], 0, s[82:83]
	s_mov_b32 m0, s88
	s_nop 0
	global_load_lds_dwordx4 v[236:237], off
	s_waitcnt vmcnt(8)
	s_waitcnt lgkmcnt(0)
	s_barrier
	s_setprio 1
	s_waitcnt lgkmcnt(0)
	v_mfma_f32_16x16x32_bf16 v[126:129], v[130:133], v[184:187], v[126:129]
	v_mfma_f32_16x16x32_bf16 v[122:125], v[138:141], v[184:187], v[122:125]
	v_mfma_f32_16x16x32_bf16 v[110:113], v[130:133], v[198:201], v[110:113]
	v_mfma_f32_16x16x32_bf16 v[106:109], v[138:141], v[198:201], v[106:109]
	v_mfma_f32_16x16x32_bf16 v[94:97], v[130:133], v[218:221], v[94:97]
	v_mfma_f32_16x16x32_bf16 v[90:93], v[138:141], v[218:221], v[90:93]
	v_mfma_f32_16x16x32_bf16 v[78:81], v[130:133], v[226:229], v[78:81]
	v_mfma_f32_16x16x32_bf16 v[74:77], v[138:141], v[226:229], v[74:77]
	v_mfma_f32_16x16x32_bf16 v[126:129], v[134:137], v[188:191], v[126:129]
	v_mfma_f32_16x16x32_bf16 v[122:125], v[142:145], v[188:191], v[122:125]
	v_mfma_f32_16x16x32_bf16 v[110:113], v[134:137], v[214:217], v[110:113]
	v_mfma_f32_16x16x32_bf16 v[106:109], v[142:145], v[214:217], v[106:109]
	v_mfma_f32_16x16x32_bf16 v[94:97], v[134:137], v[222:225], v[94:97]
	v_mfma_f32_16x16x32_bf16 v[90:93], v[142:145], v[222:225], v[90:93]
	v_mfma_f32_16x16x32_bf16 v[78:81], v[134:137], v[230:233], v[78:81]
	v_mfma_f32_16x16x32_bf16 v[74:77], v[142:145], v[230:233], v[74:77]
	s_setprio 0
	s_setprio 1
	v_mfma_f32_16x16x32_bf16 v[118:121], v[146:149], v[184:187], v[118:121]
	v_mfma_f32_16x16x32_bf16 v[114:117], v[154:157], v[184:187], v[114:117]
	v_mfma_f32_16x16x32_bf16 v[102:105], v[146:149], v[198:201], v[102:105]
	v_mfma_f32_16x16x32_bf16 v[98:101], v[154:157], v[198:201], v[98:101]
	v_mfma_f32_16x16x32_bf16 v[86:89], v[146:149], v[218:221], v[86:89]
	v_mfma_f32_16x16x32_bf16 v[82:85], v[154:157], v[218:221], v[82:85]
	v_mfma_f32_16x16x32_bf16 v[70:73], v[146:149], v[226:229], v[70:73]
	v_mfma_f32_16x16x32_bf16 v[66:69], v[154:157], v[226:229], v[66:69]
	v_mfma_f32_16x16x32_bf16 v[118:121], v[150:153], v[188:191], v[118:121]
	v_mfma_f32_16x16x32_bf16 v[114:117], v[158:161], v[188:191], v[114:117]
	v_mfma_f32_16x16x32_bf16 v[102:105], v[150:153], v[214:217], v[102:105]
	v_mfma_f32_16x16x32_bf16 v[98:101], v[158:161], v[214:217], v[98:101]
	v_mfma_f32_16x16x32_bf16 v[86:89], v[150:153], v[222:225], v[86:89]
	v_mfma_f32_16x16x32_bf16 v[82:85], v[158:161], v[222:225], v[82:85]
	v_mfma_f32_16x16x32_bf16 v[70:73], v[150:153], v[230:233], v[70:73]
	v_mfma_f32_16x16x32_bf16 v[66:69], v[158:161], v[230:233], v[66:69]
	s_setprio 0
	s_barrier
	ds_read_b128 v[184:187], v196 offset:49152
	ds_read_b128 v[188:191], v196 offset:50176
	ds_read_b128 v[198:201], v196 offset:51200
	ds_read_b128 v[214:217], v196 offset:52224
	ds_read_b128 v[218:221], v196 offset:53248
	ds_read_b128 v[222:225], v196 offset:54272
	ds_read_b128 v[226:229], v196 offset:55296
	ds_read_b128 v[230:233], v196 offset:56320
	s_add_i32 s20, s20, s14
	s_mov_b32 m0, s20
	v_lshl_add_u64 v[236:237], v[202:203], 0, s[34:35]
	global_load_lds_dwordx4 v[236:237], off
	v_lshl_add_u64 v[236:237], v[202:203], 0, s[38:39]
	s_add_i32 m0, s20, 0x2000
	s_add_i32 s20, s21, s14
	global_load_lds_dwordx4 v[236:237], off
	v_lshl_add_u64 v[236:237], v[202:203], 0, s[44:45]
	s_mov_b32 m0, s20
	v_lshl_add_u64 v[202:203], v[202:203], 0, s[10:11]
	global_load_lds_dwordx4 v[236:237], off
	s_add_i32 m0, s20, 0x2000
	s_nop 0
	global_load_lds_dwordx4 v[202:203], off
	v_lshl_add_u64 v[202:203], v[234:235], 0, s[34:35]
	s_mov_b32 m0, s89
	s_nop 0
	global_load_lds_dwordx4 v[202:203], off
	v_lshl_add_u64 v[202:203], v[234:235], 0, s[38:39]
	s_mov_b32 m0, s90
	s_nop 0
	global_load_lds_dwordx4 v[202:203], off
	s_waitcnt vmcnt(8)
	s_waitcnt lgkmcnt(0)
	s_barrier
	s_setprio 1
	s_waitcnt lgkmcnt(0)
	v_mfma_f32_16x16x32_bf16 v[62:65], v[130:133], v[184:187], v[62:65]
	v_mfma_f32_16x16x32_bf16 v[58:61], v[138:141], v[184:187], v[58:61]
	v_mfma_f32_16x16x32_bf16 v[46:49], v[130:133], v[198:201], v[46:49]
	v_mfma_f32_16x16x32_bf16 v[42:45], v[138:141], v[198:201], v[42:45]
	v_mfma_f32_16x16x32_bf16 v[30:33], v[130:133], v[218:221], v[30:33]
	v_mfma_f32_16x16x32_bf16 v[26:29], v[138:141], v[218:221], v[26:29]
	v_mfma_f32_16x16x32_bf16 v[14:17], v[130:133], v[226:229], v[14:17]
	v_mfma_f32_16x16x32_bf16 v[10:13], v[138:141], v[226:229], v[10:13]
	v_mfma_f32_16x16x32_bf16 v[62:65], v[134:137], v[188:191], v[62:65]
	v_mfma_f32_16x16x32_bf16 v[58:61], v[142:145], v[188:191], v[58:61]
	v_mfma_f32_16x16x32_bf16 v[46:49], v[134:137], v[214:217], v[46:49]
	v_mfma_f32_16x16x32_bf16 v[42:45], v[142:145], v[214:217], v[42:45]
	v_mfma_f32_16x16x32_bf16 v[30:33], v[134:137], v[222:225], v[30:33]
	v_mfma_f32_16x16x32_bf16 v[26:29], v[142:145], v[222:225], v[26:29]
	v_mfma_f32_16x16x32_bf16 v[14:17], v[134:137], v[230:233], v[14:17]
	v_mfma_f32_16x16x32_bf16 v[10:13], v[142:145], v[230:233], v[10:13]
	s_add_i32 vcc_hi, vcc_hi, 2
	s_add_u32 s76, s76, 0x100
	s_addc_u32 s77, s77, 0
	s_add_u32 s87, s87, 0x100
	s_addc_u32 vcc_lo, vcc_lo, 0
	s_setprio 0
	s_setprio 1
	v_mfma_f32_16x16x32_bf16 v[54:57], v[146:149], v[184:187], v[54:57]
	v_mfma_f32_16x16x32_bf16 v[50:53], v[154:157], v[184:187], v[50:53]
	v_mfma_f32_16x16x32_bf16 v[38:41], v[146:149], v[198:201], v[38:41]
	v_mfma_f32_16x16x32_bf16 v[34:37], v[154:157], v[198:201], v[34:37]
	v_mfma_f32_16x16x32_bf16 v[22:25], v[146:149], v[218:221], v[22:25]
	v_mfma_f32_16x16x32_bf16 v[18:21], v[154:157], v[218:221], v[18:21]
	v_mfma_f32_16x16x32_bf16 v[6:9], v[146:149], v[226:229], v[6:9]
	v_mfma_f32_16x16x32_bf16 v[2:5], v[154:157], v[226:229], v[2:5]
	v_mfma_f32_16x16x32_bf16 v[54:57], v[150:153], v[188:191], v[54:57]
	v_mfma_f32_16x16x32_bf16 v[50:53], v[158:161], v[188:191], v[50:53]
	v_mfma_f32_16x16x32_bf16 v[38:41], v[150:153], v[214:217], v[38:41]
	v_mfma_f32_16x16x32_bf16 v[34:37], v[158:161], v[214:217], v[34:37]
	v_mfma_f32_16x16x32_bf16 v[22:25], v[150:153], v[222:225], v[22:25]
	v_mfma_f32_16x16x32_bf16 v[18:21], v[158:161], v[222:225], v[18:21]
	v_mfma_f32_16x16x32_bf16 v[6:9], v[150:153], v[230:233], v[6:9]
	v_mfma_f32_16x16x32_bf16 v[2:5], v[158:161], v[230:233], v[2:5]
	s_setprio 0
	s_barrier
	s_branch .LBB0_778
	.p2alignl 6, 3212836864
.LBB0_778:
	s_add_i32 s22, 0, 0x10000
	s_add_i32 s23, 0, 0x14000
	v_add_u32_e32 v142, s22, v193
	v_add_u32_e32 v158, s23, v193
	ds_read_b128 v[130:133], v142
	ds_read_b128 v[134:137], v142 offset:1024
	ds_read_b128 v[138:141], v142 offset:2048
	ds_read_b128 v[142:145], v142 offset:3072
	ds_read_b128 v[146:149], v158
	ds_read_b128 v[150:153], v158 offset:1024
	ds_read_b128 v[154:157], v158 offset:2048
	ds_read_b128 v[158:161], v158 offset:3072
	ds_read_b128 v[184:187], v196
	ds_read_b128 v[188:191], v196 offset:1024
	ds_read_b128 v[198:201], v196 offset:2048
	ds_read_b128 v[214:217], v196 offset:3072
	ds_read_b128 v[218:221], v196 offset:4096
	ds_read_b128 v[222:225], v196 offset:5120
	ds_read_b128 v[226:229], v196 offset:6144
	ds_read_b128 v[230:233], v196 offset:7168
	s_add_u32 s20, s76, 0xfffc0080
	s_addc_u32 s21, s77, -1
	s_cmp_eq_u32 vcc_hi, 12
	s_cselect_b32 s79, s61, s21
	s_cselect_b32 s78, s85, s20
	s_cselect_b32 s21, s59, vcc_lo
	s_cselect_b32 s20, s86, s87
	s_add_i32 m0, s43, 0xc000
	v_lshl_add_u64 v[202:203], s[76:77], 0, v[182:183]
	global_load_lds_dwordx4 v[202:203], off
	v_lshl_add_u64 v[202:203], v[202:203], 0, s[72:73]
	s_add_i32 m0, s43, 0xe000
	s_nop 0
	global_load_lds_dwordx4 v[202:203], off
	s_waitcnt vmcnt(8)
	s_waitcnt lgkmcnt(0)
	s_barrier
	s_setprio 1
	s_waitcnt lgkmcnt(0)
	v_mfma_f32_16x16x32_bf16 v[126:129], v[130:133], v[184:187], v[126:129]
	v_mfma_f32_16x16x32_bf16 v[122:125], v[138:141], v[184:187], v[122:125]
	v_mfma_f32_16x16x32_bf16 v[110:113], v[130:133], v[198:201], v[110:113]
	v_mfma_f32_16x16x32_bf16 v[106:109], v[138:141], v[198:201], v[106:109]
	v_mfma_f32_16x16x32_bf16 v[94:97], v[130:133], v[218:221], v[94:97]
	v_mfma_f32_16x16x32_bf16 v[90:93], v[138:141], v[218:221], v[90:93]
	v_mfma_f32_16x16x32_bf16 v[78:81], v[130:133], v[226:229], v[78:81]
	v_mfma_f32_16x16x32_bf16 v[74:77], v[138:141], v[226:229], v[74:77]
	v_mfma_f32_16x16x32_bf16 v[126:129], v[134:137], v[188:191], v[126:129]
	v_mfma_f32_16x16x32_bf16 v[122:125], v[142:145], v[188:191], v[122:125]
	v_mfma_f32_16x16x32_bf16 v[110:113], v[134:137], v[214:217], v[110:113]
	v_mfma_f32_16x16x32_bf16 v[106:109], v[142:145], v[214:217], v[106:109]
	v_mfma_f32_16x16x32_bf16 v[94:97], v[134:137], v[222:225], v[94:97]
	v_mfma_f32_16x16x32_bf16 v[90:93], v[142:145], v[222:225], v[90:93]
	v_mfma_f32_16x16x32_bf16 v[78:81], v[134:137], v[230:233], v[78:81]
	v_mfma_f32_16x16x32_bf16 v[74:77], v[142:145], v[230:233], v[74:77]
	s_setprio 0
	s_setprio 1
	v_mfma_f32_16x16x32_bf16 v[118:121], v[146:149], v[184:187], v[118:121]
	v_mfma_f32_16x16x32_bf16 v[114:117], v[154:157], v[184:187], v[114:117]
	v_mfma_f32_16x16x32_bf16 v[102:105], v[146:149], v[198:201], v[102:105]
	v_mfma_f32_16x16x32_bf16 v[98:101], v[154:157], v[198:201], v[98:101]
	v_mfma_f32_16x16x32_bf16 v[86:89], v[146:149], v[218:221], v[86:89]
	v_mfma_f32_16x16x32_bf16 v[82:85], v[154:157], v[218:221], v[82:85]
	v_mfma_f32_16x16x32_bf16 v[70:73], v[146:149], v[226:229], v[70:73]
	v_mfma_f32_16x16x32_bf16 v[66:69], v[154:157], v[226:229], v[66:69]
	v_mfma_f32_16x16x32_bf16 v[118:121], v[150:153], v[188:191], v[118:121]
	v_mfma_f32_16x16x32_bf16 v[114:117], v[158:161], v[188:191], v[114:117]
	v_mfma_f32_16x16x32_bf16 v[102:105], v[150:153], v[214:217], v[102:105]
	v_mfma_f32_16x16x32_bf16 v[98:101], v[158:161], v[214:217], v[98:101]
	v_mfma_f32_16x16x32_bf16 v[86:89], v[150:153], v[222:225], v[86:89]
	v_mfma_f32_16x16x32_bf16 v[82:85], v[158:161], v[222:225], v[82:85]
	v_mfma_f32_16x16x32_bf16 v[70:73], v[150:153], v[230:233], v[70:73]
	v_mfma_f32_16x16x32_bf16 v[66:69], v[158:161], v[230:233], v[66:69]
	s_setprio 0
	s_barrier
	ds_read_b128 v[184:187], v196 offset:16384
	ds_read_b128 v[188:191], v196 offset:17408
	ds_read_b128 v[198:201], v196 offset:18432
	ds_read_b128 v[214:217], v196 offset:19456
	ds_read_b128 v[218:221], v196 offset:20480
	ds_read_b128 v[222:225], v196 offset:21504
	ds_read_b128 v[226:229], v196 offset:22528
	ds_read_b128 v[230:233], v196 offset:23552
	v_lshl_add_u64 v[202:203], s[20:21], 0, v[0:1]
	s_add_i32 s20, s22, s14
	s_mov_b32 m0, s20
	s_nop 0
	s_nop 0
	global_load_lds_dwordx4 v[202:203], off
	v_lshl_add_u64 v[234:235], v[202:203], 0, s[72:73]
	s_add_i32 m0, s20, 0x2000
	s_add_i32 s20, s23, s14
	global_load_lds_dwordx4 v[234:235], off
	v_lshl_add_u64 v[234:235], v[202:203], 0, s[28:29]
	s_mov_b32 m0, s20
	s_nop 0
	global_load_lds_dwordx4 v[234:235], off
	v_lshl_add_u64 v[234:235], v[202:203], 0, s[82:83]
	s_add_i32 m0, s20, 0x2000
	s_nop 0
	global_load_lds_dwordx4 v[234:235], off
	v_lshl_add_u64 v[234:235], s[78:79], 0, v[162:163]
	s_mov_b32 m0, s43
	v_lshl_add_u64 v[236:237], v[234:235], 0, s[72:73]
	global_load_lds_dwordx4 v[234:235], off
	s_mov_b32 m0, s46
	s_nop 0
	global_load_lds_dwordx4 v[236:237], off
	s_waitcnt vmcnt(8)
	s_waitcnt lgkmcnt(0)
	s_barrier
	s_setprio 1
	s_waitcnt lgkmcnt(0)
	v_mfma_f32_16x16x32_bf16 v[62:65], v[130:133], v[184:187], v[62:65]
	v_mfma_f32_16x16x32_bf16 v[58:61], v[138:141], v[184:187], v[58:61]
	v_mfma_f32_16x16x32_bf16 v[46:49], v[130:133], v[198:201], v[46:49]
	v_mfma_f32_16x16x32_bf16 v[42:45], v[138:141], v[198:201], v[42:45]
	v_mfma_f32_16x16x32_bf16 v[30:33], v[130:133], v[218:221], v[30:33]
	v_mfma_f32_16x16x32_bf16 v[26:29], v[138:141], v[218:221], v[26:29]
	v_mfma_f32_16x16x32_bf16 v[14:17], v[130:133], v[226:229], v[14:17]
	v_mfma_f32_16x16x32_bf16 v[10:13], v[138:141], v[226:229], v[10:13]
	v_mfma_f32_16x16x32_bf16 v[62:65], v[134:137], v[188:191], v[62:65]
	v_mfma_f32_16x16x32_bf16 v[58:61], v[142:145], v[188:191], v[58:61]
	v_mfma_f32_16x16x32_bf16 v[46:49], v[134:137], v[214:217], v[46:49]
	v_mfma_f32_16x16x32_bf16 v[42:45], v[142:145], v[214:217], v[42:45]
	v_mfma_f32_16x16x32_bf16 v[30:33], v[134:137], v[222:225], v[30:33]
	v_mfma_f32_16x16x32_bf16 v[26:29], v[142:145], v[222:225], v[26:29]
	v_mfma_f32_16x16x32_bf16 v[14:17], v[134:137], v[230:233], v[14:17]
	v_mfma_f32_16x16x32_bf16 v[10:13], v[142:145], v[230:233], v[10:13]
	s_setprio 0
	s_setprio 1
	v_mfma_f32_16x16x32_bf16 v[54:57], v[146:149], v[184:187], v[54:57]
	v_mfma_f32_16x16x32_bf16 v[50:53], v[154:157], v[184:187], v[50:53]
	v_mfma_f32_16x16x32_bf16 v[38:41], v[146:149], v[198:201], v[38:41]
	v_mfma_f32_16x16x32_bf16 v[34:37], v[154:157], v[198:201], v[34:37]
	v_mfma_f32_16x16x32_bf16 v[22:25], v[146:149], v[218:221], v[22:25]
	v_mfma_f32_16x16x32_bf16 v[18:21], v[154:157], v[218:221], v[18:21]
	v_mfma_f32_16x16x32_bf16 v[6:9], v[146:149], v[226:229], v[6:9]
	v_mfma_f32_16x16x32_bf16 v[2:5], v[154:157], v[226:229], v[2:5]
	v_mfma_f32_16x16x32_bf16 v[54:57], v[150:153], v[188:191], v[54:57]
	v_mfma_f32_16x16x32_bf16 v[50:53], v[158:161], v[188:191], v[50:53]
	v_mfma_f32_16x16x32_bf16 v[38:41], v[150:153], v[214:217], v[38:41]
	v_mfma_f32_16x16x32_bf16 v[34:37], v[158:161], v[214:217], v[34:37]
	v_mfma_f32_16x16x32_bf16 v[22:25], v[150:153], v[222:225], v[22:25]
	v_mfma_f32_16x16x32_bf16 v[18:21], v[158:161], v[222:225], v[18:21]
	v_mfma_f32_16x16x32_bf16 v[6:9], v[150:153], v[230:233], v[6:9]
	v_mfma_f32_16x16x32_bf16 v[2:5], v[158:161], v[230:233], v[2:5]
	s_setprio 0
	s_barrier
	s_add_i32 s20, 0, 0x18000
	s_add_i32 s21, 0, 0x1c000
	v_add_u32_e32 v142, s20, v193
	v_add_u32_e32 v158, s21, v193
	ds_read_b128 v[130:133], v142
	ds_read_b128 v[134:137], v142 offset:1024
	ds_read_b128 v[138:141], v142 offset:2048
	ds_read_b128 v[142:145], v142 offset:3072
	ds_read_b128 v[146:149], v158
	ds_read_b128 v[150:153], v158 offset:1024
	ds_read_b128 v[154:157], v158 offset:2048
	ds_read_b128 v[158:161], v158 offset:3072
	ds_read_b128 v[184:187], v196 offset:32768
	ds_read_b128 v[188:191], v196 offset:33792
	ds_read_b128 v[198:201], v196 offset:34816
	ds_read_b128 v[214:217], v196 offset:35840
	ds_read_b128 v[218:221], v196 offset:36864
	ds_read_b128 v[222:225], v196 offset:37888
	ds_read_b128 v[226:229], v196 offset:38912
	ds_read_b128 v[230:233], v196 offset:39936
	s_mov_b32 m0, s47
	v_lshl_add_u64 v[236:237], v[234:235], 0, s[28:29]
	global_load_lds_dwordx4 v[236:237], off
	v_lshl_add_u64 v[236:237], v[234:235], 0, s[82:83]
	s_mov_b32 m0, s88
	s_nop 0
	global_load_lds_dwordx4 v[236:237], off
	s_waitcnt vmcnt(8)
	s_waitcnt lgkmcnt(0)
	s_barrier
	s_setprio 1
	s_waitcnt lgkmcnt(0)
	v_mfma_f32_16x16x32_bf16 v[126:129], v[130:133], v[184:187], v[126:129]
	v_mfma_f32_16x16x32_bf16 v[122:125], v[138:141], v[184:187], v[122:125]
	v_mfma_f32_16x16x32_bf16 v[110:113], v[130:133], v[198:201], v[110:113]
	v_mfma_f32_16x16x32_bf16 v[106:109], v[138:141], v[198:201], v[106:109]
	v_mfma_f32_16x16x32_bf16 v[94:97], v[130:133], v[218:221], v[94:97]
	v_mfma_f32_16x16x32_bf16 v[90:93], v[138:141], v[218:221], v[90:93]
	v_mfma_f32_16x16x32_bf16 v[78:81], v[130:133], v[226:229], v[78:81]
	v_mfma_f32_16x16x32_bf16 v[74:77], v[138:141], v[226:229], v[74:77]
	v_mfma_f32_16x16x32_bf16 v[126:129], v[134:137], v[188:191], v[126:129]
	v_mfma_f32_16x16x32_bf16 v[122:125], v[142:145], v[188:191], v[122:125]
	v_mfma_f32_16x16x32_bf16 v[110:113], v[134:137], v[214:217], v[110:113]
	v_mfma_f32_16x16x32_bf16 v[106:109], v[142:145], v[214:217], v[106:109]
	v_mfma_f32_16x16x32_bf16 v[94:97], v[134:137], v[222:225], v[94:97]
	v_mfma_f32_16x16x32_bf16 v[90:93], v[142:145], v[222:225], v[90:93]
	v_mfma_f32_16x16x32_bf16 v[78:81], v[134:137], v[230:233], v[78:81]
	v_mfma_f32_16x16x32_bf16 v[74:77], v[142:145], v[230:233], v[74:77]
	s_setprio 0
	s_setprio 1
	v_mfma_f32_16x16x32_bf16 v[118:121], v[146:149], v[184:187], v[118:121]
	v_mfma_f32_16x16x32_bf16 v[114:117], v[154:157], v[184:187], v[114:117]
	v_mfma_f32_16x16x32_bf16 v[102:105], v[146:149], v[198:201], v[102:105]
	v_mfma_f32_16x16x32_bf16 v[98:101], v[154:157], v[198:201], v[98:101]
	v_mfma_f32_16x16x32_bf16 v[86:89], v[146:149], v[218:221], v[86:89]
	v_mfma_f32_16x16x32_bf16 v[82:85], v[154:157], v[218:221], v[82:85]
	v_mfma_f32_16x16x32_bf16 v[70:73], v[146:149], v[226:229], v[70:73]
	v_mfma_f32_16x16x32_bf16 v[66:69], v[154:157], v[226:229], v[66:69]
	v_mfma_f32_16x16x32_bf16 v[118:121], v[150:153], v[188:191], v[118:121]
	v_mfma_f32_16x16x32_bf16 v[114:117], v[158:161], v[188:191], v[114:117]
	v_mfma_f32_16x16x32_bf16 v[102:105], v[150:153], v[214:217], v[102:105]
	v_mfma_f32_16x16x32_bf16 v[98:101], v[158:161], v[214:217], v[98:101]
	v_mfma_f32_16x16x32_bf16 v[86:89], v[150:153], v[222:225], v[86:89]
	v_mfma_f32_16x16x32_bf16 v[82:85], v[158:161], v[222:225], v[82:85]
	v_mfma_f32_16x16x32_bf16 v[70:73], v[150:153], v[230:233], v[70:73]
	v_mfma_f32_16x16x32_bf16 v[66:69], v[158:161], v[230:233], v[66:69]
	s_setprio 0
	s_barrier
	ds_read_b128 v[184:187], v196 offset:49152
	ds_read_b128 v[188:191], v196 offset:50176
	ds_read_b128 v[198:201], v196 offset:51200
	ds_read_b128 v[214:217], v196 offset:52224
	ds_read_b128 v[218:221], v196 offset:53248
	ds_read_b128 v[222:225], v196 offset:54272
	ds_read_b128 v[226:229], v196 offset:55296
	ds_read_b128 v[230:233], v196 offset:56320
	s_add_i32 s20, s20, s14
	s_mov_b32 m0, s20
	v_lshl_add_u64 v[236:237], v[202:203], 0, s[34:35]
	global_load_lds_dwordx4 v[236:237], off
	v_lshl_add_u64 v[236:237], v[202:203], 0, s[38:39]
	s_add_i32 m0, s20, 0x2000
	s_add_i32 s20, s21, s14
	global_load_lds_dwordx4 v[236:237], off
	v_lshl_add_u64 v[236:237], v[202:203], 0, s[44:45]
	s_mov_b32 m0, s20
	v_lshl_add_u64 v[202:203], v[202:203], 0, s[10:11]
	global_load_lds_dwordx4 v[236:237], off
	s_add_i32 m0, s20, 0x2000
	s_nop 0
	global_load_lds_dwordx4 v[202:203], off
	v_lshl_add_u64 v[202:203], v[234:235], 0, s[34:35]
	s_mov_b32 m0, s89
	s_nop 0
	global_load_lds_dwordx4 v[202:203], off
	v_lshl_add_u64 v[202:203], v[234:235], 0, s[38:39]
	s_mov_b32 m0, s90
	s_nop 0
	global_load_lds_dwordx4 v[202:203], off
	s_waitcnt vmcnt(8)
	s_waitcnt lgkmcnt(0)
	s_barrier
	s_setprio 1
	s_waitcnt lgkmcnt(0)
	v_mfma_f32_16x16x32_bf16 v[62:65], v[130:133], v[184:187], v[62:65]
	v_mfma_f32_16x16x32_bf16 v[58:61], v[138:141], v[184:187], v[58:61]
	v_mfma_f32_16x16x32_bf16 v[46:49], v[130:133], v[198:201], v[46:49]
	v_mfma_f32_16x16x32_bf16 v[42:45], v[138:141], v[198:201], v[42:45]
	v_mfma_f32_16x16x32_bf16 v[30:33], v[130:133], v[218:221], v[30:33]
	v_mfma_f32_16x16x32_bf16 v[26:29], v[138:141], v[218:221], v[26:29]
	v_mfma_f32_16x16x32_bf16 v[14:17], v[130:133], v[226:229], v[14:17]
	v_mfma_f32_16x16x32_bf16 v[10:13], v[138:141], v[226:229], v[10:13]
	v_mfma_f32_16x16x32_bf16 v[62:65], v[134:137], v[188:191], v[62:65]
	v_mfma_f32_16x16x32_bf16 v[58:61], v[142:145], v[188:191], v[58:61]
	v_mfma_f32_16x16x32_bf16 v[46:49], v[134:137], v[214:217], v[46:49]
	v_mfma_f32_16x16x32_bf16 v[42:45], v[142:145], v[214:217], v[42:45]
	v_mfma_f32_16x16x32_bf16 v[30:33], v[134:137], v[222:225], v[30:33]
	v_mfma_f32_16x16x32_bf16 v[26:29], v[142:145], v[222:225], v[26:29]
	v_mfma_f32_16x16x32_bf16 v[14:17], v[134:137], v[230:233], v[14:17]
	v_mfma_f32_16x16x32_bf16 v[10:13], v[142:145], v[230:233], v[10:13]
	s_add_i32 vcc_hi, vcc_hi, 2
	s_add_u32 s76, s76, 0x100
	s_addc_u32 s77, s77, 0
	s_add_u32 s87, s87, 0x100
	s_addc_u32 vcc_lo, vcc_lo, 0
	s_setprio 0
	s_setprio 1
	v_mfma_f32_16x16x32_bf16 v[54:57], v[146:149], v[184:187], v[54:57]
	v_mfma_f32_16x16x32_bf16 v[50:53], v[154:157], v[184:187], v[50:53]
	v_mfma_f32_16x16x32_bf16 v[38:41], v[146:149], v[198:201], v[38:41]
	v_mfma_f32_16x16x32_bf16 v[34:37], v[154:157], v[198:201], v[34:37]
	v_mfma_f32_16x16x32_bf16 v[22:25], v[146:149], v[218:221], v[22:25]
	v_mfma_f32_16x16x32_bf16 v[18:21], v[154:157], v[218:221], v[18:21]
	v_mfma_f32_16x16x32_bf16 v[6:9], v[146:149], v[226:229], v[6:9]
	v_mfma_f32_16x16x32_bf16 v[2:5], v[154:157], v[226:229], v[2:5]
	v_mfma_f32_16x16x32_bf16 v[54:57], v[150:153], v[188:191], v[54:57]
	v_mfma_f32_16x16x32_bf16 v[50:53], v[158:161], v[188:191], v[50:53]
	v_mfma_f32_16x16x32_bf16 v[38:41], v[150:153], v[214:217], v[38:41]
	v_mfma_f32_16x16x32_bf16 v[34:37], v[158:161], v[214:217], v[34:37]
	v_mfma_f32_16x16x32_bf16 v[22:25], v[150:153], v[222:225], v[22:25]
	v_mfma_f32_16x16x32_bf16 v[18:21], v[158:161], v[222:225], v[18:21]
	v_mfma_f32_16x16x32_bf16 v[6:9], v[150:153], v[230:233], v[6:9]
	v_mfma_f32_16x16x32_bf16 v[2:5], v[158:161], v[230:233], v[2:5]
	s_setprio 0
	s_barrier
	s_cmp_gt_u32 vcc_hi, 13
	s_cbranch_scc0 .LBB0_778
	s_and_b64 vcc, exec, s[50:51]
	s_cbranch_vccz .LBB0_781
	s_barrier

.Lmid1_850:
	s_add_i32 vcc_lo, 0, 0x10000
	s_add_i32 vcc_hi, 0, 0x14000
	s_add_u32 s20, s56, 0xfffc0080
	s_addc_u32 s21, s57, -1
	s_cmp_eq_u32 s91, 12
	s_cselect_b32 s59, s76, s21
	s_cselect_b32 s58, s77, s20
	s_cselect_b32 s21, s69, s87
	s_cselect_b32 s20, s79, s86
	s_add_i32 m0, s15, 0xc000
	v_lshl_add_u64 v[142:143], s[56:57], 0, v[136:137]
	global_load_lds_dwordx4 v[142:143], off
	v_lshl_add_u64 v[142:143], v[142:143], 0, s[72:73]
	s_add_i32 m0, s15, 0xe000
	s_nop 0
	global_load_lds_dwordx4 v[142:143], off
	s_waitcnt vmcnt(8)
	s_waitcnt lgkmcnt(0)
	s_barrier
	s_setprio 1
	s_waitcnt lgkmcnt(0)
	v_mfma_f32_16x16x32_bf16 v[126:129], v[138:141], v[198:201], 0
	v_mfma_f32_16x16x32_bf16 v[122:125], v[150:153], v[198:201], 0
	v_mfma_f32_16x16x32_bf16 v[110:113], v[138:141], v[218:221], 0
	v_mfma_f32_16x16x32_bf16 v[106:109], v[150:153], v[218:221], 0
	v_mfma_f32_16x16x32_bf16 v[94:97], v[138:141], v[226:229], 0
	v_mfma_f32_16x16x32_bf16 v[90:93], v[150:153], v[226:229], 0
	v_mfma_f32_16x16x32_bf16 v[78:81], v[138:141], v[234:237], 0
	v_mfma_f32_16x16x32_bf16 v[74:77], v[150:153], v[234:237], 0
	v_mfma_f32_16x16x32_bf16 v[126:129], v[146:149], v[214:217], v[126:129]
	v_mfma_f32_16x16x32_bf16 v[122:125], v[158:161], v[214:217], v[122:125]
	v_mfma_f32_16x16x32_bf16 v[110:113], v[146:149], v[222:225], v[110:113]
	v_mfma_f32_16x16x32_bf16 v[106:109], v[158:161], v[222:225], v[106:109]
	v_mfma_f32_16x16x32_bf16 v[94:97], v[146:149], v[230:233], v[94:97]
	v_mfma_f32_16x16x32_bf16 v[90:93], v[158:161], v[230:233], v[90:93]
	v_mfma_f32_16x16x32_bf16 v[78:81], v[146:149], v[238:241], v[78:81]
	v_mfma_f32_16x16x32_bf16 v[74:77], v[158:161], v[238:241], v[74:77]
	s_setprio 0
	s_setprio 1
	v_mfma_f32_16x16x32_bf16 v[118:121], v[182:185], v[198:201], 0
	v_mfma_f32_16x16x32_bf16 v[114:117], v[190:193], v[198:201], 0
	v_mfma_f32_16x16x32_bf16 v[102:105], v[182:185], v[218:221], 0
	v_mfma_f32_16x16x32_bf16 v[98:101], v[190:193], v[218:221], 0
	v_mfma_f32_16x16x32_bf16 v[86:89], v[182:185], v[226:229], 0
	v_mfma_f32_16x16x32_bf16 v[82:85], v[190:193], v[226:229], 0
	v_mfma_f32_16x16x32_bf16 v[70:73], v[182:185], v[234:237], 0
	v_mfma_f32_16x16x32_bf16 v[66:69], v[190:193], v[234:237], 0
	v_mfma_f32_16x16x32_bf16 v[118:121], v[186:189], v[214:217], v[118:121]
	v_mfma_f32_16x16x32_bf16 v[114:117], v[194:197], v[214:217], v[114:117]
	v_mfma_f32_16x16x32_bf16 v[102:105], v[186:189], v[222:225], v[102:105]
	v_mfma_f32_16x16x32_bf16 v[98:101], v[194:197], v[222:225], v[98:101]
	v_mfma_f32_16x16x32_bf16 v[86:89], v[186:189], v[230:233], v[86:89]
	v_mfma_f32_16x16x32_bf16 v[82:85], v[194:197], v[230:233], v[82:85]
	v_mfma_f32_16x16x32_bf16 v[70:73], v[186:189], v[238:241], v[70:73]
	v_mfma_f32_16x16x32_bf16 v[66:69], v[194:197], v[238:241], v[66:69]
	s_setprio 0
	s_barrier
	ds_read_b128 v[198:201], v157 offset:16384
	ds_read_b128 v[214:217], v157 offset:17408
	ds_read_b128 v[218:221], v157 offset:18432
	ds_read_b128 v[222:225], v157 offset:19456
	ds_read_b128 v[226:229], v157 offset:20480
	ds_read_b128 v[230:233], v157 offset:21504
	ds_read_b128 v[234:237], v157 offset:22528
	ds_read_b128 v[238:241], v157 offset:23552
	v_lshl_add_u64 v[142:143], s[20:21], 0, v[130:131]
	s_add_i32 s20, vcc_lo, s14
	s_mov_b32 m0, s20
	s_nop 0
	s_nop 0
	global_load_lds_dwordx4 v[142:143], off
	v_lshl_add_u64 v[162:163], v[142:143], 0, s[72:73]
	s_add_i32 m0, s20, 0x2000
	s_add_i32 s20, vcc_hi, s14
	global_load_lds_dwordx4 v[162:163], off
	v_lshl_add_u64 v[162:163], v[142:143], 0, s[28:29]
	s_mov_b32 m0, s20
	s_nop 0
	global_load_lds_dwordx4 v[162:163], off
	v_lshl_add_u64 v[162:163], v[142:143], 0, s[82:83]
	s_add_i32 m0, s20, 0x2000
	s_nop 0
	global_load_lds_dwordx4 v[162:163], off
	v_lshl_add_u64 v[162:163], s[58:59], 0, v[132:133]
	s_mov_b32 m0, s15
	v_lshl_add_u64 v[202:203], v[162:163], 0, s[72:73]
	global_load_lds_dwordx4 v[162:163], off
	s_mov_b32 m0, s42
	s_nop 0
	global_load_lds_dwordx4 v[202:203], off
	s_waitcnt vmcnt(8)
	s_waitcnt lgkmcnt(0)
	s_barrier
	s_setprio 1
	s_waitcnt lgkmcnt(0)
	v_mfma_f32_16x16x32_bf16 v[62:65], v[138:141], v[198:201], 0
	v_mfma_f32_16x16x32_bf16 v[58:61], v[150:153], v[198:201], 0
	v_mfma_f32_16x16x32_bf16 v[46:49], v[138:141], v[218:221], 0
	v_mfma_f32_16x16x32_bf16 v[42:45], v[150:153], v[218:221], 0
	v_mfma_f32_16x16x32_bf16 v[30:33], v[138:141], v[226:229], 0
	v_mfma_f32_16x16x32_bf16 v[26:29], v[150:153], v[226:229], 0
	v_mfma_f32_16x16x32_bf16 v[14:17], v[138:141], v[234:237], 0
	v_mfma_f32_16x16x32_bf16 v[10:13], v[150:153], v[234:237], 0
	v_mfma_f32_16x16x32_bf16 v[62:65], v[146:149], v[214:217], v[62:65]
	v_mfma_f32_16x16x32_bf16 v[58:61], v[158:161], v[214:217], v[58:61]
	v_mfma_f32_16x16x32_bf16 v[46:49], v[146:149], v[222:225], v[46:49]
	v_mfma_f32_16x16x32_bf16 v[42:45], v[158:161], v[222:225], v[42:45]
	v_mfma_f32_16x16x32_bf16 v[30:33], v[146:149], v[230:233], v[30:33]
	v_mfma_f32_16x16x32_bf16 v[26:29], v[158:161], v[230:233], v[26:29]
	v_mfma_f32_16x16x32_bf16 v[14:17], v[146:149], v[238:241], v[14:17]
	v_mfma_f32_16x16x32_bf16 v[10:13], v[158:161], v[238:241], v[10:13]
	s_setprio 0
	s_setprio 1
	v_mfma_f32_16x16x32_bf16 v[54:57], v[182:185], v[198:201], 0
	v_mfma_f32_16x16x32_bf16 v[50:53], v[190:193], v[198:201], 0
	v_mfma_f32_16x16x32_bf16 v[38:41], v[182:185], v[218:221], 0
	v_mfma_f32_16x16x32_bf16 v[34:37], v[190:193], v[218:221], 0
	v_mfma_f32_16x16x32_bf16 v[22:25], v[182:185], v[226:229], 0
	v_mfma_f32_16x16x32_bf16 v[18:21], v[190:193], v[226:229], 0
	v_mfma_f32_16x16x32_bf16 v[6:9], v[182:185], v[234:237], 0
	v_mfma_f32_16x16x32_bf16 v[2:5], v[190:193], v[234:237], 0
	v_mfma_f32_16x16x32_bf16 v[54:57], v[186:189], v[214:217], v[54:57]
	v_mfma_f32_16x16x32_bf16 v[50:53], v[194:197], v[214:217], v[50:53]
	v_mfma_f32_16x16x32_bf16 v[38:41], v[186:189], v[222:225], v[38:41]
	v_mfma_f32_16x16x32_bf16 v[34:37], v[194:197], v[222:225], v[34:37]
	v_mfma_f32_16x16x32_bf16 v[22:25], v[186:189], v[230:233], v[22:25]
	v_mfma_f32_16x16x32_bf16 v[18:21], v[194:197], v[230:233], v[18:21]
	v_mfma_f32_16x16x32_bf16 v[6:9], v[186:189], v[238:241], v[6:9]
	v_mfma_f32_16x16x32_bf16 v[2:5], v[194:197], v[238:241], v[2:5]
	s_setprio 0
	s_barrier
	s_add_i32 s20, 0, 0x18000
	v_add_u32_e32 v0, s20, v145
	s_add_i32 s21, 0, 0x1c000
	ds_read_b128 v[138:141], v0
	ds_read_b128 v[146:149], v0 offset:1024
	ds_read_b128 v[150:153], v0 offset:2048
	ds_read_b128 v[158:161], v0 offset:3072
	v_add_u32_e32 v0, s21, v145
	ds_read_b128 v[182:185], v0
	ds_read_b128 v[186:189], v0 offset:1024
	ds_read_b128 v[190:193], v0 offset:2048
	ds_read_b128 v[194:197], v0 offset:3072
	ds_read_b128 v[198:201], v157 offset:32768
	ds_read_b128 v[214:217], v157 offset:33792
	ds_read_b128 v[218:221], v157 offset:34816
	ds_read_b128 v[222:225], v157 offset:35840
	ds_read_b128 v[226:229], v157 offset:36864
	ds_read_b128 v[230:233], v157 offset:37888
	ds_read_b128 v[234:237], v157 offset:38912
	ds_read_b128 v[238:241], v157 offset:39936
	s_mov_b32 m0, s43
	v_lshl_add_u64 v[202:203], v[162:163], 0, s[28:29]
	global_load_lds_dwordx4 v[202:203], off
	v_lshl_add_u64 v[202:203], v[162:163], 0, s[82:83]
	s_mov_b32 m0, s46
	s_nop 0
	global_load_lds_dwordx4 v[202:203], off
	s_waitcnt vmcnt(8)
	s_waitcnt lgkmcnt(0)
	s_barrier
	s_setprio 1
	s_waitcnt lgkmcnt(0)
	v_mfma_f32_16x16x32_bf16 v[126:129], v[138:141], v[198:201], v[126:129]
	v_mfma_f32_16x16x32_bf16 v[122:125], v[150:153], v[198:201], v[122:125]
	v_mfma_f32_16x16x32_bf16 v[110:113], v[138:141], v[218:221], v[110:113]
	v_mfma_f32_16x16x32_bf16 v[106:109], v[150:153], v[218:221], v[106:109]
	v_mfma_f32_16x16x32_bf16 v[94:97], v[138:141], v[226:229], v[94:97]
	v_mfma_f32_16x16x32_bf16 v[90:93], v[150:153], v[226:229], v[90:93]
	v_mfma_f32_16x16x32_bf16 v[78:81], v[138:141], v[234:237], v[78:81]
	v_mfma_f32_16x16x32_bf16 v[74:77], v[150:153], v[234:237], v[74:77]
	v_mfma_f32_16x16x32_bf16 v[126:129], v[146:149], v[214:217], v[126:129]
	v_mfma_f32_16x16x32_bf16 v[122:125], v[158:161], v[214:217], v[122:125]
	v_mfma_f32_16x16x32_bf16 v[110:113], v[146:149], v[222:225], v[110:113]
	v_mfma_f32_16x16x32_bf16 v[106:109], v[158:161], v[222:225], v[106:109]
	v_mfma_f32_16x16x32_bf16 v[94:97], v[146:149], v[230:233], v[94:97]
	v_mfma_f32_16x16x32_bf16 v[90:93], v[158:161], v[230:233], v[90:93]
	v_mfma_f32_16x16x32_bf16 v[78:81], v[146:149], v[238:241], v[78:81]
	v_mfma_f32_16x16x32_bf16 v[74:77], v[158:161], v[238:241], v[74:77]
	s_setprio 0
	s_setprio 1
	v_mfma_f32_16x16x32_bf16 v[118:121], v[182:185], v[198:201], v[118:121]
	v_mfma_f32_16x16x32_bf16 v[114:117], v[190:193], v[198:201], v[114:117]
	v_mfma_f32_16x16x32_bf16 v[102:105], v[182:185], v[218:221], v[102:105]
	v_mfma_f32_16x16x32_bf16 v[98:101], v[190:193], v[218:221], v[98:101]
	v_mfma_f32_16x16x32_bf16 v[86:89], v[182:185], v[226:229], v[86:89]
	v_mfma_f32_16x16x32_bf16 v[82:85], v[190:193], v[226:229], v[82:85]
	v_mfma_f32_16x16x32_bf16 v[70:73], v[182:185], v[234:237], v[70:73]
	v_mfma_f32_16x16x32_bf16 v[66:69], v[190:193], v[234:237], v[66:69]
	v_mfma_f32_16x16x32_bf16 v[118:121], v[186:189], v[214:217], v[118:121]
	v_mfma_f32_16x16x32_bf16 v[114:117], v[194:197], v[214:217], v[114:117]
	v_mfma_f32_16x16x32_bf16 v[102:105], v[186:189], v[222:225], v[102:105]
	v_mfma_f32_16x16x32_bf16 v[98:101], v[194:197], v[222:225], v[98:101]
	v_mfma_f32_16x16x32_bf16 v[86:89], v[186:189], v[230:233], v[86:89]
	v_mfma_f32_16x16x32_bf16 v[82:85], v[194:197], v[230:233], v[82:85]
	v_mfma_f32_16x16x32_bf16 v[70:73], v[186:189], v[238:241], v[70:73]
	v_mfma_f32_16x16x32_bf16 v[66:69], v[194:197], v[238:241], v[66:69]
	s_setprio 0
	s_barrier
	ds_read_b128 v[198:201], v157 offset:49152
	ds_read_b128 v[214:217], v157 offset:50176
	ds_read_b128 v[218:221], v157 offset:51200
	ds_read_b128 v[222:225], v157 offset:52224
	ds_read_b128 v[226:229], v157 offset:53248
	ds_read_b128 v[230:233], v157 offset:54272
	ds_read_b128 v[234:237], v157 offset:55296
	ds_read_b128 v[238:241], v157 offset:56320
	s_add_i32 s20, s20, s14
	s_mov_b32 m0, s20
	v_lshl_add_u64 v[202:203], v[142:143], 0, s[34:35]
	global_load_lds_dwordx4 v[202:203], off
	v_lshl_add_u64 v[202:203], v[142:143], 0, s[38:39]
	s_add_i32 m0, s20, 0x2000
	s_add_i32 s20, s21, s14
	global_load_lds_dwordx4 v[202:203], off
	v_lshl_add_u64 v[202:203], v[142:143], 0, s[44:45]
	s_mov_b32 m0, s20
	v_lshl_add_u64 v[142:143], v[142:143], 0, s[10:11]
	global_load_lds_dwordx4 v[202:203], off
	s_add_i32 m0, s20, 0x2000
	s_nop 0
	global_load_lds_dwordx4 v[142:143], off
	v_lshl_add_u64 v[142:143], v[162:163], 0, s[34:35]
	s_mov_b32 m0, s47
	s_nop 0
	global_load_lds_dwordx4 v[142:143], off
	v_lshl_add_u64 v[142:143], v[162:163], 0, s[38:39]
	s_mov_b32 m0, s96
	s_nop 0
	global_load_lds_dwordx4 v[142:143], off
	s_waitcnt vmcnt(8)
	s_waitcnt lgkmcnt(0)
	s_barrier
	s_setprio 1
	s_waitcnt lgkmcnt(0)
	v_mfma_f32_16x16x32_bf16 v[62:65], v[138:141], v[198:201], v[62:65]
	v_mfma_f32_16x16x32_bf16 v[58:61], v[150:153], v[198:201], v[58:61]
	v_mfma_f32_16x16x32_bf16 v[46:49], v[138:141], v[218:221], v[46:49]
	v_mfma_f32_16x16x32_bf16 v[42:45], v[150:153], v[218:221], v[42:45]
	v_mfma_f32_16x16x32_bf16 v[30:33], v[138:141], v[226:229], v[30:33]
	v_mfma_f32_16x16x32_bf16 v[26:29], v[150:153], v[226:229], v[26:29]
	v_mfma_f32_16x16x32_bf16 v[14:17], v[138:141], v[234:237], v[14:17]
	v_mfma_f32_16x16x32_bf16 v[10:13], v[150:153], v[234:237], v[10:13]
	v_mfma_f32_16x16x32_bf16 v[62:65], v[146:149], v[214:217], v[62:65]
	v_mfma_f32_16x16x32_bf16 v[58:61], v[158:161], v[214:217], v[58:61]
	v_mfma_f32_16x16x32_bf16 v[46:49], v[146:149], v[222:225], v[46:49]
	v_mfma_f32_16x16x32_bf16 v[42:45], v[158:161], v[222:225], v[42:45]
	v_mfma_f32_16x16x32_bf16 v[30:33], v[146:149], v[230:233], v[30:33]
	v_mfma_f32_16x16x32_bf16 v[26:29], v[158:161], v[230:233], v[26:29]
	v_mfma_f32_16x16x32_bf16 v[14:17], v[146:149], v[238:241], v[14:17]
	v_mfma_f32_16x16x32_bf16 v[10:13], v[158:161], v[238:241], v[10:13]
	s_add_i32 s91, s91, 2
	s_add_u32 s56, s56, 0x100
	s_addc_u32 s57, s57, 0
	s_add_u32 s86, s86, 0x100
	s_addc_u32 s87, s87, 0
	s_setprio 0
	s_setprio 1
	v_mfma_f32_16x16x32_bf16 v[54:57], v[182:185], v[198:201], v[54:57]
	v_mfma_f32_16x16x32_bf16 v[50:53], v[190:193], v[198:201], v[50:53]
	v_mfma_f32_16x16x32_bf16 v[38:41], v[182:185], v[218:221], v[38:41]
	v_mfma_f32_16x16x32_bf16 v[34:37], v[190:193], v[218:221], v[34:37]
	v_mfma_f32_16x16x32_bf16 v[22:25], v[182:185], v[226:229], v[22:25]
	v_mfma_f32_16x16x32_bf16 v[18:21], v[190:193], v[226:229], v[18:21]
	v_mfma_f32_16x16x32_bf16 v[6:9], v[182:185], v[234:237], v[6:9]
	v_mfma_f32_16x16x32_bf16 v[2:5], v[190:193], v[234:237], v[2:5]
	v_mfma_f32_16x16x32_bf16 v[54:57], v[186:189], v[214:217], v[54:57]
	v_mfma_f32_16x16x32_bf16 v[50:53], v[194:197], v[214:217], v[50:53]
	v_mfma_f32_16x16x32_bf16 v[38:41], v[186:189], v[222:225], v[38:41]
	v_mfma_f32_16x16x32_bf16 v[34:37], v[194:197], v[222:225], v[34:37]
	v_mfma_f32_16x16x32_bf16 v[22:25], v[186:189], v[230:233], v[22:25]
	v_mfma_f32_16x16x32_bf16 v[18:21], v[194:197], v[230:233], v[18:21]
	v_mfma_f32_16x16x32_bf16 v[6:9], v[186:189], v[238:241], v[6:9]
	v_mfma_f32_16x16x32_bf16 v[2:5], v[194:197], v[238:241], v[2:5]
	s_setprio 0
	s_barrier
	s_branch .LBB0_850
	.p2alignl 6, 3212836864
.LBB0_850:
	s_add_i32 vcc_lo, 0, 0x10000
	v_add_u32_e32 v0, vcc_lo, v145
	s_add_i32 vcc_hi, 0, 0x14000
	ds_read_b128 v[138:141], v0
	ds_read_b128 v[146:149], v0 offset:1024
	ds_read_b128 v[150:153], v0 offset:2048
	ds_read_b128 v[158:161], v0 offset:3072
	v_add_u32_e32 v0, vcc_hi, v145
	ds_read_b128 v[182:185], v0
	ds_read_b128 v[186:189], v0 offset:1024
	ds_read_b128 v[190:193], v0 offset:2048
	ds_read_b128 v[194:197], v0 offset:3072
	ds_read_b128 v[198:201], v157
	ds_read_b128 v[214:217], v157 offset:1024
	ds_read_b128 v[218:221], v157 offset:2048
	ds_read_b128 v[222:225], v157 offset:3072
	ds_read_b128 v[226:229], v157 offset:4096
	ds_read_b128 v[230:233], v157 offset:5120
	ds_read_b128 v[234:237], v157 offset:6144
	ds_read_b128 v[238:241], v157 offset:7168
	s_add_u32 s20, s56, 0xfffc0080
	s_addc_u32 s21, s57, -1
	s_cmp_eq_u32 s91, 12
	s_cselect_b32 s59, s76, s21
	s_cselect_b32 s58, s77, s20
	s_cselect_b32 s21, s69, s87
	s_cselect_b32 s20, s79, s86
	s_add_i32 m0, s15, 0xc000
	v_lshl_add_u64 v[142:143], s[56:57], 0, v[136:137]
	global_load_lds_dwordx4 v[142:143], off
	v_lshl_add_u64 v[142:143], v[142:143], 0, s[72:73]
	s_add_i32 m0, s15, 0xe000
	s_nop 0
	global_load_lds_dwordx4 v[142:143], off
	s_waitcnt vmcnt(8)
	s_waitcnt lgkmcnt(0)
	s_barrier
	s_setprio 1
	s_waitcnt lgkmcnt(0)
	v_mfma_f32_16x16x32_bf16 v[126:129], v[138:141], v[198:201], v[126:129]
	v_mfma_f32_16x16x32_bf16 v[122:125], v[150:153], v[198:201], v[122:125]
	v_mfma_f32_16x16x32_bf16 v[110:113], v[138:141], v[218:221], v[110:113]
	v_mfma_f32_16x16x32_bf16 v[106:109], v[150:153], v[218:221], v[106:109]
	v_mfma_f32_16x16x32_bf16 v[94:97], v[138:141], v[226:229], v[94:97]
	v_mfma_f32_16x16x32_bf16 v[90:93], v[150:153], v[226:229], v[90:93]
	v_mfma_f32_16x16x32_bf16 v[78:81], v[138:141], v[234:237], v[78:81]
	v_mfma_f32_16x16x32_bf16 v[74:77], v[150:153], v[234:237], v[74:77]
	v_mfma_f32_16x16x32_bf16 v[126:129], v[146:149], v[214:217], v[126:129]
	v_mfma_f32_16x16x32_bf16 v[122:125], v[158:161], v[214:217], v[122:125]
	v_mfma_f32_16x16x32_bf16 v[110:113], v[146:149], v[222:225], v[110:113]
	v_mfma_f32_16x16x32_bf16 v[106:109], v[158:161], v[222:225], v[106:109]
	v_mfma_f32_16x16x32_bf16 v[94:97], v[146:149], v[230:233], v[94:97]
	v_mfma_f32_16x16x32_bf16 v[90:93], v[158:161], v[230:233], v[90:93]
	v_mfma_f32_16x16x32_bf16 v[78:81], v[146:149], v[238:241], v[78:81]
	v_mfma_f32_16x16x32_bf16 v[74:77], v[158:161], v[238:241], v[74:77]
	s_setprio 0
	s_setprio 1
	v_mfma_f32_16x16x32_bf16 v[118:121], v[182:185], v[198:201], v[118:121]
	v_mfma_f32_16x16x32_bf16 v[114:117], v[190:193], v[198:201], v[114:117]
	v_mfma_f32_16x16x32_bf16 v[102:105], v[182:185], v[218:221], v[102:105]
	v_mfma_f32_16x16x32_bf16 v[98:101], v[190:193], v[218:221], v[98:101]
	v_mfma_f32_16x16x32_bf16 v[86:89], v[182:185], v[226:229], v[86:89]
	v_mfma_f32_16x16x32_bf16 v[82:85], v[190:193], v[226:229], v[82:85]
	v_mfma_f32_16x16x32_bf16 v[70:73], v[182:185], v[234:237], v[70:73]
	v_mfma_f32_16x16x32_bf16 v[66:69], v[190:193], v[234:237], v[66:69]
	v_mfma_f32_16x16x32_bf16 v[118:121], v[186:189], v[214:217], v[118:121]
	v_mfma_f32_16x16x32_bf16 v[114:117], v[194:197], v[214:217], v[114:117]
	v_mfma_f32_16x16x32_bf16 v[102:105], v[186:189], v[222:225], v[102:105]
	v_mfma_f32_16x16x32_bf16 v[98:101], v[194:197], v[222:225], v[98:101]
	v_mfma_f32_16x16x32_bf16 v[86:89], v[186:189], v[230:233], v[86:89]
	v_mfma_f32_16x16x32_bf16 v[82:85], v[194:197], v[230:233], v[82:85]
	v_mfma_f32_16x16x32_bf16 v[70:73], v[186:189], v[238:241], v[70:73]
	v_mfma_f32_16x16x32_bf16 v[66:69], v[194:197], v[238:241], v[66:69]
	s_setprio 0
	s_barrier
	ds_read_b128 v[198:201], v157 offset:16384
	ds_read_b128 v[214:217], v157 offset:17408
	ds_read_b128 v[218:221], v157 offset:18432
	ds_read_b128 v[222:225], v157 offset:19456
	ds_read_b128 v[226:229], v157 offset:20480
	ds_read_b128 v[230:233], v157 offset:21504
	ds_read_b128 v[234:237], v157 offset:22528
	ds_read_b128 v[238:241], v157 offset:23552
	v_lshl_add_u64 v[142:143], s[20:21], 0, v[130:131]
	s_add_i32 s20, vcc_lo, s14
	s_mov_b32 m0, s20
	s_nop 0
	s_nop 0
	global_load_lds_dwordx4 v[142:143], off
	v_lshl_add_u64 v[162:163], v[142:143], 0, s[72:73]
	s_add_i32 m0, s20, 0x2000
	s_add_i32 s20, vcc_hi, s14
	global_load_lds_dwordx4 v[162:163], off
	v_lshl_add_u64 v[162:163], v[142:143], 0, s[28:29]
	s_mov_b32 m0, s20
	s_nop 0
	global_load_lds_dwordx4 v[162:163], off
	v_lshl_add_u64 v[162:163], v[142:143], 0, s[82:83]
	s_add_i32 m0, s20, 0x2000
	s_nop 0
	global_load_lds_dwordx4 v[162:163], off
	v_lshl_add_u64 v[162:163], s[58:59], 0, v[132:133]
	s_mov_b32 m0, s15
	v_lshl_add_u64 v[202:203], v[162:163], 0, s[72:73]
	global_load_lds_dwordx4 v[162:163], off
	s_mov_b32 m0, s42
	s_nop 0
	global_load_lds_dwordx4 v[202:203], off
	s_waitcnt vmcnt(8)
	s_waitcnt lgkmcnt(0)
	s_barrier
	s_setprio 1
	s_waitcnt lgkmcnt(0)
	v_mfma_f32_16x16x32_bf16 v[62:65], v[138:141], v[198:201], v[62:65]
	v_mfma_f32_16x16x32_bf16 v[58:61], v[150:153], v[198:201], v[58:61]
	v_mfma_f32_16x16x32_bf16 v[46:49], v[138:141], v[218:221], v[46:49]
	v_mfma_f32_16x16x32_bf16 v[42:45], v[150:153], v[218:221], v[42:45]
	v_mfma_f32_16x16x32_bf16 v[30:33], v[138:141], v[226:229], v[30:33]
	v_mfma_f32_16x16x32_bf16 v[26:29], v[150:153], v[226:229], v[26:29]
	v_mfma_f32_16x16x32_bf16 v[14:17], v[138:141], v[234:237], v[14:17]
	v_mfma_f32_16x16x32_bf16 v[10:13], v[150:153], v[234:237], v[10:13]
	v_mfma_f32_16x16x32_bf16 v[62:65], v[146:149], v[214:217], v[62:65]
	v_mfma_f32_16x16x32_bf16 v[58:61], v[158:161], v[214:217], v[58:61]
	v_mfma_f32_16x16x32_bf16 v[46:49], v[146:149], v[222:225], v[46:49]
	v_mfma_f32_16x16x32_bf16 v[42:45], v[158:161], v[222:225], v[42:45]
	v_mfma_f32_16x16x32_bf16 v[30:33], v[146:149], v[230:233], v[30:33]
	v_mfma_f32_16x16x32_bf16 v[26:29], v[158:161], v[230:233], v[26:29]
	v_mfma_f32_16x16x32_bf16 v[14:17], v[146:149], v[238:241], v[14:17]
	v_mfma_f32_16x16x32_bf16 v[10:13], v[158:161], v[238:241], v[10:13]
	s_setprio 0
	s_setprio 1
	v_mfma_f32_16x16x32_bf16 v[54:57], v[182:185], v[198:201], v[54:57]
	v_mfma_f32_16x16x32_bf16 v[50:53], v[190:193], v[198:201], v[50:53]
	v_mfma_f32_16x16x32_bf16 v[38:41], v[182:185], v[218:221], v[38:41]
	v_mfma_f32_16x16x32_bf16 v[34:37], v[190:193], v[218:221], v[34:37]
	v_mfma_f32_16x16x32_bf16 v[22:25], v[182:185], v[226:229], v[22:25]
	v_mfma_f32_16x16x32_bf16 v[18:21], v[190:193], v[226:229], v[18:21]
	v_mfma_f32_16x16x32_bf16 v[6:9], v[182:185], v[234:237], v[6:9]
	v_mfma_f32_16x16x32_bf16 v[2:5], v[190:193], v[234:237], v[2:5]
	v_mfma_f32_16x16x32_bf16 v[54:57], v[186:189], v[214:217], v[54:57]
	v_mfma_f32_16x16x32_bf16 v[50:53], v[194:197], v[214:217], v[50:53]
	v_mfma_f32_16x16x32_bf16 v[38:41], v[186:189], v[222:225], v[38:41]
	v_mfma_f32_16x16x32_bf16 v[34:37], v[194:197], v[222:225], v[34:37]
	v_mfma_f32_16x16x32_bf16 v[22:25], v[186:189], v[230:233], v[22:25]
	v_mfma_f32_16x16x32_bf16 v[18:21], v[194:197], v[230:233], v[18:21]
	v_mfma_f32_16x16x32_bf16 v[6:9], v[186:189], v[238:241], v[6:9]
	v_mfma_f32_16x16x32_bf16 v[2:5], v[194:197], v[238:241], v[2:5]
	s_setprio 0
	s_barrier
	s_add_i32 s20, 0, 0x18000
	v_add_u32_e32 v0, s20, v145
	s_add_i32 s21, 0, 0x1c000
	ds_read_b128 v[138:141], v0
	ds_read_b128 v[146:149], v0 offset:1024
	ds_read_b128 v[150:153], v0 offset:2048
	ds_read_b128 v[158:161], v0 offset:3072
	v_add_u32_e32 v0, s21, v145
	ds_read_b128 v[182:185], v0
	ds_read_b128 v[186:189], v0 offset:1024
	ds_read_b128 v[190:193], v0 offset:2048
	ds_read_b128 v[194:197], v0 offset:3072
	ds_read_b128 v[198:201], v157 offset:32768
	ds_read_b128 v[214:217], v157 offset:33792
	ds_read_b128 v[218:221], v157 offset:34816
	ds_read_b128 v[222:225], v157 offset:35840
	ds_read_b128 v[226:229], v157 offset:36864
	ds_read_b128 v[230:233], v157 offset:37888
	ds_read_b128 v[234:237], v157 offset:38912
	ds_read_b128 v[238:241], v157 offset:39936
	s_mov_b32 m0, s43
	v_lshl_add_u64 v[202:203], v[162:163], 0, s[28:29]
	global_load_lds_dwordx4 v[202:203], off
	v_lshl_add_u64 v[202:203], v[162:163], 0, s[82:83]
	s_mov_b32 m0, s46
	s_nop 0
	global_load_lds_dwordx4 v[202:203], off
	s_waitcnt vmcnt(8)
	s_waitcnt lgkmcnt(0)
	s_barrier
	s_setprio 1
	s_waitcnt lgkmcnt(0)
	v_mfma_f32_16x16x32_bf16 v[126:129], v[138:141], v[198:201], v[126:129]
	v_mfma_f32_16x16x32_bf16 v[122:125], v[150:153], v[198:201], v[122:125]
	v_mfma_f32_16x16x32_bf16 v[110:113], v[138:141], v[218:221], v[110:113]
	v_mfma_f32_16x16x32_bf16 v[106:109], v[150:153], v[218:221], v[106:109]
	v_mfma_f32_16x16x32_bf16 v[94:97], v[138:141], v[226:229], v[94:97]
	v_mfma_f32_16x16x32_bf16 v[90:93], v[150:153], v[226:229], v[90:93]
	v_mfma_f32_16x16x32_bf16 v[78:81], v[138:141], v[234:237], v[78:81]
	v_mfma_f32_16x16x32_bf16 v[74:77], v[150:153], v[234:237], v[74:77]
	v_mfma_f32_16x16x32_bf16 v[126:129], v[146:149], v[214:217], v[126:129]
	v_mfma_f32_16x16x32_bf16 v[122:125], v[158:161], v[214:217], v[122:125]
	v_mfma_f32_16x16x32_bf16 v[110:113], v[146:149], v[222:225], v[110:113]
	v_mfma_f32_16x16x32_bf16 v[106:109], v[158:161], v[222:225], v[106:109]
	v_mfma_f32_16x16x32_bf16 v[94:97], v[146:149], v[230:233], v[94:97]
	v_mfma_f32_16x16x32_bf16 v[90:93], v[158:161], v[230:233], v[90:93]
	v_mfma_f32_16x16x32_bf16 v[78:81], v[146:149], v[238:241], v[78:81]
	v_mfma_f32_16x16x32_bf16 v[74:77], v[158:161], v[238:241], v[74:77]
	s_setprio 0
	s_setprio 1
	v_mfma_f32_16x16x32_bf16 v[118:121], v[182:185], v[198:201], v[118:121]
	v_mfma_f32_16x16x32_bf16 v[114:117], v[190:193], v[198:201], v[114:117]
	v_mfma_f32_16x16x32_bf16 v[102:105], v[182:185], v[218:221], v[102:105]
	v_mfma_f32_16x16x32_bf16 v[98:101], v[190:193], v[218:221], v[98:101]
	v_mfma_f32_16x16x32_bf16 v[86:89], v[182:185], v[226:229], v[86:89]
	v_mfma_f32_16x16x32_bf16 v[82:85], v[190:193], v[226:229], v[82:85]
	v_mfma_f32_16x16x32_bf16 v[70:73], v[182:185], v[234:237], v[70:73]
	v_mfma_f32_16x16x32_bf16 v[66:69], v[190:193], v[234:237], v[66:69]
	v_mfma_f32_16x16x32_bf16 v[118:121], v[186:189], v[214:217], v[118:121]
	v_mfma_f32_16x16x32_bf16 v[114:117], v[194:197], v[214:217], v[114:117]
	v_mfma_f32_16x16x32_bf16 v[102:105], v[186:189], v[222:225], v[102:105]
	v_mfma_f32_16x16x32_bf16 v[98:101], v[194:197], v[222:225], v[98:101]
	v_mfma_f32_16x16x32_bf16 v[86:89], v[186:189], v[230:233], v[86:89]
	v_mfma_f32_16x16x32_bf16 v[82:85], v[194:197], v[230:233], v[82:85]
	v_mfma_f32_16x16x32_bf16 v[70:73], v[186:189], v[238:241], v[70:73]
	v_mfma_f32_16x16x32_bf16 v[66:69], v[194:197], v[238:241], v[66:69]
	s_setprio 0
	s_barrier
	ds_read_b128 v[198:201], v157 offset:49152
	ds_read_b128 v[214:217], v157 offset:50176
	ds_read_b128 v[218:221], v157 offset:51200
	ds_read_b128 v[222:225], v157 offset:52224
	ds_read_b128 v[226:229], v157 offset:53248
	ds_read_b128 v[230:233], v157 offset:54272
	ds_read_b128 v[234:237], v157 offset:55296
	ds_read_b128 v[238:241], v157 offset:56320
	s_add_i32 s20, s20, s14
	s_mov_b32 m0, s20
	v_lshl_add_u64 v[202:203], v[142:143], 0, s[34:35]
	global_load_lds_dwordx4 v[202:203], off
	v_lshl_add_u64 v[202:203], v[142:143], 0, s[38:39]
	s_add_i32 m0, s20, 0x2000
	s_add_i32 s20, s21, s14
	global_load_lds_dwordx4 v[202:203], off
	v_lshl_add_u64 v[202:203], v[142:143], 0, s[44:45]
	s_mov_b32 m0, s20
	v_lshl_add_u64 v[142:143], v[142:143], 0, s[10:11]
	global_load_lds_dwordx4 v[202:203], off
	s_add_i32 m0, s20, 0x2000
	s_nop 0
	global_load_lds_dwordx4 v[142:143], off
	v_lshl_add_u64 v[142:143], v[162:163], 0, s[34:35]
	s_mov_b32 m0, s47
	s_nop 0
	global_load_lds_dwordx4 v[142:143], off
	v_lshl_add_u64 v[142:143], v[162:163], 0, s[38:39]
	s_mov_b32 m0, s96
	s_nop 0
	global_load_lds_dwordx4 v[142:143], off
	s_waitcnt vmcnt(8)
	s_waitcnt lgkmcnt(0)
	s_barrier
	s_setprio 1
	s_waitcnt lgkmcnt(0)
	v_mfma_f32_16x16x32_bf16 v[62:65], v[138:141], v[198:201], v[62:65]
	v_mfma_f32_16x16x32_bf16 v[58:61], v[150:153], v[198:201], v[58:61]
	v_mfma_f32_16x16x32_bf16 v[46:49], v[138:141], v[218:221], v[46:49]
	v_mfma_f32_16x16x32_bf16 v[42:45], v[150:153], v[218:221], v[42:45]
	v_mfma_f32_16x16x32_bf16 v[30:33], v[138:141], v[226:229], v[30:33]
	v_mfma_f32_16x16x32_bf16 v[26:29], v[150:153], v[226:229], v[26:29]
	v_mfma_f32_16x16x32_bf16 v[14:17], v[138:141], v[234:237], v[14:17]
	v_mfma_f32_16x16x32_bf16 v[10:13], v[150:153], v[234:237], v[10:13]
	v_mfma_f32_16x16x32_bf16 v[62:65], v[146:149], v[214:217], v[62:65]
	v_mfma_f32_16x16x32_bf16 v[58:61], v[158:161], v[214:217], v[58:61]
	v_mfma_f32_16x16x32_bf16 v[46:49], v[146:149], v[222:225], v[46:49]
	v_mfma_f32_16x16x32_bf16 v[42:45], v[158:161], v[222:225], v[42:45]
	v_mfma_f32_16x16x32_bf16 v[30:33], v[146:149], v[230:233], v[30:33]
	v_mfma_f32_16x16x32_bf16 v[26:29], v[158:161], v[230:233], v[26:29]
	v_mfma_f32_16x16x32_bf16 v[14:17], v[146:149], v[238:241], v[14:17]
	v_mfma_f32_16x16x32_bf16 v[10:13], v[158:161], v[238:241], v[10:13]
	s_add_i32 s91, s91, 2
	s_add_u32 s56, s56, 0x100
	s_addc_u32 s57, s57, 0
	s_add_u32 s86, s86, 0x100
	s_addc_u32 s87, s87, 0
	s_setprio 0
	s_setprio 1
	v_mfma_f32_16x16x32_bf16 v[54:57], v[182:185], v[198:201], v[54:57]
	v_mfma_f32_16x16x32_bf16 v[50:53], v[190:193], v[198:201], v[50:53]
	v_mfma_f32_16x16x32_bf16 v[38:41], v[182:185], v[218:221], v[38:41]
	v_mfma_f32_16x16x32_bf16 v[34:37], v[190:193], v[218:221], v[34:37]
	v_mfma_f32_16x16x32_bf16 v[22:25], v[182:185], v[226:229], v[22:25]
	v_mfma_f32_16x16x32_bf16 v[18:21], v[190:193], v[226:229], v[18:21]
	v_mfma_f32_16x16x32_bf16 v[6:9], v[182:185], v[234:237], v[6:9]
	v_mfma_f32_16x16x32_bf16 v[2:5], v[190:193], v[234:237], v[2:5]
	v_mfma_f32_16x16x32_bf16 v[54:57], v[186:189], v[214:217], v[54:57]
	v_mfma_f32_16x16x32_bf16 v[50:53], v[194:197], v[214:217], v[50:53]
	v_mfma_f32_16x16x32_bf16 v[38:41], v[186:189], v[222:225], v[38:41]
	v_mfma_f32_16x16x32_bf16 v[34:37], v[194:197], v[222:225], v[34:37]
	v_mfma_f32_16x16x32_bf16 v[22:25], v[186:189], v[230:233], v[22:25]
	v_mfma_f32_16x16x32_bf16 v[18:21], v[194:197], v[230:233], v[18:21]
	v_mfma_f32_16x16x32_bf16 v[6:9], v[186:189], v[238:241], v[6:9]
	v_mfma_f32_16x16x32_bf16 v[2:5], v[194:197], v[238:241], v[2:5]
	s_setprio 0
	s_barrier
	s_cmp_gt_u32 s91, 13
	s_cbranch_scc0 .LBB0_850
	s_and_b64 vcc, exec, s[62:63]
	s_cbranch_vccz .LBB0_853
	s_barrier
